# v22 + contiguous ds_read groups in 16-read load segments, redundant post-barrier lgkmcnt waits dropped, tile-header early fragment reads, merged scan waits; bit-identical
# speedup vs baseline: 1.0034x; 1.0034x over previous
; #define PG8_STAGE(bufoff, gbase, voff) do { _Pragma("unroll") for (int _i = 0; _i < 2; ++_i) \
;         __builtin_amdgcn_global_load_lds((const unsigned*)((const char*)(gbase) + (voff)[_i]), (PG8_LAS unsigned*)(lds + (bufoff) + ldsw + _i * 8192), 16, 0, 0); } while (0)
; #define PG8_LDA(dst, b, h) do { _Pragma("unroll") for (int m = 0; m < 4; ++m) _Pragma("unroll") for (int k = 0; k < 2; ++k) dst[m][k] = *(const PG8_LAS bf16x8*)(lds + PG8_SA(b, h) + aoff + m * 2048 + k * 1024); } while (0)
; template <class Epi, class Sched, bool ALIGN_EPI = false, bool SP2 = false>
; __device__ __forceinline__ void gemm_phase(PG8_LAS unsigned char* lds, const Gemm g, const Sched& S, const Epi& E) {
;     ...
;         const bool has_next = S.next(ui + 1, nxt);
;         const char* nA = has_next ? (const char*)g.A + (size_t)nxt.pm * tstepA : cA; const char* nB = has_next ? (const char*)g.Bt + (size_t)nxt.pn * tstep : cB;
;         for (int t = 0; t < nt; t += 2) {
;             const bool last = (t == nt - 2);
;             const char* a1 = cA + (size_t)(t + 1) * kstepA;
;             const char* a2 = last ? nA : cA + (size_t)(t + 2) * kstepA; const char* b2 = last ? nB : cB + (size_t)(t + 2) * kstep;
;             const char* a3 = a2 + kstepA; const char* b3 = b2 + kstep;
;             if (last && has_next) S.a_ready(nxt);
;             if constexpr (SP2) {
;             PG8_LDB(B0, 0, 0); PG8_LDB(B1, 0, 1); PG8_SCHED; PG8_LDA(At, 0, 0); PG8_STAGE(PG8_SA(1, 1), a1 + hstepA, voffA);
;             PG8_WAIT_V(8); PG8_WAIT_L(0); PG8_BAR; PG8_MMA(0, 0, At, B0); PG8_MMA(0, 1, At, B1); PG8_BAR; PG8_SCHED;
;             PG8_LDA(At, 0, 1); PG8_STAGE(PG8_SB(0, 0), b2, voffB); PG8_STAGE(PG8_SB(0, 1), b2 + hstep, voffB); PG8_STAGE(PG8_SA(0, 0), a2, voffA);
;             PG8_WAIT_V(8); PG8_WAIT_L(0); PG8_BAR; PG8_MMA(1, 0, At, B0); PG8_MMA(1, 1, At, B1); PG8_BAR; PG8_SCHED;
;             PG8_LDB(B0, 1, 0); PG8_LDB(B1, 1, 1); PG8_SCHED; PG8_LDA(At, 1, 0); PG8_STAGE(PG8_SA(0, 1), a2 + hstepA, voffA);
;             PG8_WAIT_V(8); PG8_WAIT_L(0); PG8_BAR; PG8_MMA(0, 0, At, B0); PG8_MMA(0, 1, At, B1); PG8_BAR; PG8_SCHED;
;             PG8_LDA(At, 1, 1); PG8_STAGE(PG8_SB(1, 0), b3, voffB); PG8_STAGE(PG8_SB(1, 1), b3 + hstep, voffB); PG8_STAGE(PG8_SA(1, 0), a3, voffA);
;             PG8_WAIT_V(8); PG8_WAIT_L(0); PG8_BAR; PG8_MMA(1, 0, At, B0); PG8_MMA(1, 1, At, B1); PG8_BAR; PG8_SCHED;
.LBB0_195:
	s_ashr_i32 s27, s26, 31
	s_lshl_b64 s[38:39], s[26:27], 19
	s_add_u32 s38, s20, s38
	s_addc_u32 s39, s21, s39
	s_and_b64 s[40:41], s[36:37], exec
	s_cselect_b32 s27, s39, s45
	s_cselect_b32 s54, s38, s44
	s_ashr_i32 s25, s24, 31
	s_lshl_b64 s[40:41], s[24:25], 19
	s_add_u32 s40, s2, s40
	s_addc_u32 s41, s3, s41
	s_and_b64 s[46:47], s[36:37], exec
	s_cselect_b32 s25, s41, s43
	s_cselect_b32 s55, s40, s42
	s_add_u32 s56, s42, 0x100
	s_addc_u32 s57, s43, 0
	s_add_u32 s42, s44, 0x40080
	s_addc_u32 s43, s45, 0
	s_mov_b32 s58, -2
	s_add_u32 s44, s42, 0xfffc0080
	s_addc_u32 s45, s43, -1
	s_add_i32 s59, 0, 0x10000
	s_cmp_eq_u32 s58, 12
	s_cselect_b32 s47, s27, s45
	s_cselect_b32 s46, s54, s44
	s_cselect_b32 s45, s25, s57
	s_cselect_b32 s44, s55, s56
	s_add_i32 s62, 0, 0x14000
	s_add_i32 m0, s7, 0xc000
	v_lshl_add_u64 v[166:167], s[42:43], 0, v[136:137]
	global_load_lds_dwordx4 v[166:167], off
	v_lshl_add_u64 v[166:167], s[42:43], 0, v[134:135]
	s_add_i32 m0, s7, 0xe000
	s_nop 0
	global_load_lds_dwordx4 v[166:167], off
	s_waitcnt vmcnt(8)
	s_waitcnt lgkmcnt(0)
	s_barrier
	s_setprio 1
	v_mfma_f32_16x16x32_bf16 v[124:127], v[138:141], v[192:195], 0
	v_mfma_f32_16x16x32_bf16 v[120:123], v[150:153], v[192:195], 0
	v_mfma_f32_16x16x32_bf16 v[116:119], v[138:141], v[200:203], 0
	v_mfma_f32_16x16x32_bf16 v[108:111], v[150:153], v[200:203], 0
	v_mfma_f32_16x16x32_bf16 v[100:103], v[138:141], v[208:211], 0
	v_mfma_f32_16x16x32_bf16 v[92:95], v[150:153], v[208:211], 0
	v_mfma_f32_16x16x32_bf16 v[84:87], v[138:141], v[216:219], 0
	v_mfma_f32_16x16x32_bf16 v[76:79], v[150:153], v[216:219], 0
	v_mfma_f32_16x16x32_bf16 v[124:127], v[146:149], v[196:199], v[124:127]
	v_mfma_f32_16x16x32_bf16 v[120:123], v[154:157], v[196:199], v[120:123]
	v_mfma_f32_16x16x32_bf16 v[116:119], v[146:149], v[204:207], v[116:119]
	v_mfma_f32_16x16x32_bf16 v[108:111], v[154:157], v[204:207], v[108:111]
	v_mfma_f32_16x16x32_bf16 v[100:103], v[146:149], v[212:215], v[100:103]
	v_mfma_f32_16x16x32_bf16 v[92:95], v[154:157], v[212:215], v[92:95]
	v_mfma_f32_16x16x32_bf16 v[84:87], v[146:149], v[220:223], v[84:87]
	v_mfma_f32_16x16x32_bf16 v[76:79], v[154:157], v[220:223], v[76:79]
	s_setprio 0
	s_setprio 1
	v_mfma_f32_16x16x32_bf16 v[112:115], v[158:161], v[192:195], 0
	v_mfma_f32_16x16x32_bf16 v[104:107], v[170:173], v[192:195], 0
	v_mfma_f32_16x16x32_bf16 v[96:99], v[158:161], v[200:203], 0
	v_mfma_f32_16x16x32_bf16 v[88:91], v[170:173], v[200:203], 0
	v_mfma_f32_16x16x32_bf16 v[80:83], v[158:161], v[208:211], 0
	v_mfma_f32_16x16x32_bf16 v[72:75], v[170:173], v[208:211], 0
	v_mfma_f32_16x16x32_bf16 v[68:71], v[158:161], v[216:219], 0
	v_mfma_f32_16x16x32_bf16 v[64:67], v[170:173], v[216:219], 0
	v_mfma_f32_16x16x32_bf16 v[112:115], v[162:165], v[196:199], v[112:115]
	v_mfma_f32_16x16x32_bf16 v[104:107], v[188:191], v[196:199], v[104:107]
	v_mfma_f32_16x16x32_bf16 v[96:99], v[162:165], v[204:207], v[96:99]
	v_mfma_f32_16x16x32_bf16 v[88:91], v[188:191], v[204:207], v[88:91]
	v_mfma_f32_16x16x32_bf16 v[80:83], v[162:165], v[212:215], v[80:83]
	s_add_i32 s59, s59, s6
	v_mfma_f32_16x16x32_bf16 v[72:75], v[188:191], v[212:215], v[72:75]
	v_lshl_add_u64 v[166:167], s[44:45], 0, v[168:169]
	v_mfma_f32_16x16x32_bf16 v[68:71], v[162:165], v[220:223], v[68:71]
	s_mov_b32 m0, s59
	v_mfma_f32_16x16x32_bf16 v[64:67], v[188:191], v[220:223], v[64:67]
	s_setprio 0
	s_barrier
	ds_read_b128 v[192:195], v145 offset:16384
	ds_read_b128 v[196:199], v145 offset:17408
	ds_read_b128 v[200:203], v145 offset:18432
	ds_read_b128 v[204:207], v145 offset:19456
	ds_read_b128 v[208:211], v145 offset:20480
	ds_read_b128 v[212:215], v145 offset:21504
	ds_read_b128 v[216:219], v145 offset:22528
	ds_read_b128 v[220:223], v145 offset:23552
	global_load_lds_dwordx4 v[166:167], off
	s_add_i32 m0, s59, 0x2000
	s_add_u32 s60, s44, 0x40000
	v_lshl_add_u64 v[178:179], s[44:45], 0, v[128:129]
	s_addc_u32 s61, s45, 0
	s_add_i32 s59, s62, s6
	global_load_lds_dwordx4 v[178:179], off
	v_lshl_add_u64 v[224:225], s[60:61], 0, v[168:169]
	s_mov_b32 m0, s59
	v_lshl_add_u64 v[234:235], s[46:47], 0, v[130:131]
	global_load_lds_dwordx4 v[224:225], off
	v_lshl_add_u64 v[224:225], s[60:61], 0, v[128:129]
	s_add_i32 m0, s59, 0x2000
	s_nop 0
	global_load_lds_dwordx4 v[224:225], off
	v_lshl_add_u64 v[224:225], s[46:47], 0, v[132:133]
	s_mov_b32 m0, s7
	s_nop 0
	global_load_lds_dwordx4 v[224:225], off
	s_mov_b32 m0, s34
	s_nop 0
	global_load_lds_dwordx4 v[234:235], off
	s_waitcnt vmcnt(8)
	s_waitcnt lgkmcnt(0)
	s_barrier
; #define PG8_STAGE(bufoff, gbase, voff) do { _Pragma("unroll") for (int _i = 0; _i < 2; ++_i) \
;         __builtin_amdgcn_global_load_lds((const unsigned*)((const char*)(gbase) + (voff)[_i]), (PG8_LAS unsigned*)(lds + (bufoff) + ldsw + _i * 8192), 16, 0, 0); } while (0)
; #define PG8_LDA(dst, b, h) do { _Pragma("unroll") for (int m = 0; m < 4; ++m) _Pragma("unroll") for (int k = 0; k < 2; ++k) dst[m][k] = *(const PG8_LAS bf16x8*)(lds + PG8_SA(b, h) + aoff + m * 2048 + k * 1024); } while (0)
; #define PG8_LDB(dst, b, h) do { _Pragma("unroll") for (int n = 0; n < 2; ++n) _Pragma("unroll") for (int k = 0; k < 2; ++k) dst[n][k] = *(const PG8_LAS bf16x8*)(lds + PG8_SB(b, h) + boff + n * 2048 + k * 1024); } while (0)
; #define PG8_MMA(ai, bj, At, Bt) do { __builtin_amdgcn_s_setprio(1); _Pragma("unroll") for (int m = 0; m < 4; ++m) _Pragma("unroll") for (int n = 0; n < 2; ++n) _Pragma("unroll") for (int k = 0; k < 2; ++k) \
;         acc[ai][bj][m][n] = __builtin_amdgcn_mfma_f32_16x16x32_bf16(Bt[n][k], At[m][k], acc[ai][bj][m][n], 0, 0, 0); __builtin_amdgcn_s_setprio(0); } while (0)
; #define PG8_WAIT_V(n) asm volatile("s_waitcnt vmcnt(" #n ")" ::: "memory")
; template <class Epi, class Sched, bool ALIGN_EPI = false, bool SP2 = false>
; __device__ __forceinline__ void gemm_phase(PG8_LAS unsigned char* lds, const Gemm g, const Sched& S, const Epi& E) {
;     ...
;             PG8_LDB(B0, 0, 0); PG8_LDB(B1, 0, 1); PG8_SCHED; PG8_LDA(At, 0, 0); PG8_STAGE(PG8_SA(1, 1), a1 + hstepA, voffA);
;             PG8_WAIT_V(8); PG8_WAIT_L(0); PG8_BAR; PG8_MMA(0, 0, At, B0); PG8_MMA(0, 1, At, B1); PG8_BAR; PG8_SCHED;
;             PG8_LDA(At, 0, 1); PG8_STAGE(PG8_SB(0, 0), b2, voffB); PG8_STAGE(PG8_SB(0, 1), b2 + hstep, voffB); PG8_STAGE(PG8_SA(0, 0), a2, voffA);
;             PG8_WAIT_V(8); PG8_WAIT_L(0); PG8_BAR; PG8_MMA(1, 0, At, B0); PG8_MMA(1, 1, At, B1); PG8_BAR; PG8_SCHED;
;             PG8_LDB(B0, 1, 0); PG8_LDB(B1, 1, 1); PG8_SCHED; PG8_LDA(At, 1, 0); PG8_STAGE(PG8_SA(0, 1), a2 + hstepA, voffA);
;             PG8_WAIT_V(8); PG8_WAIT_L(0); PG8_BAR; PG8_MMA(0, 0, At, B0); PG8_MMA(0, 1, At, B1); PG8_BAR; PG8_SCHED;
;             PG8_LDA(At, 1, 1); PG8_STAGE(PG8_SB(1, 0), b3, voffB); PG8_STAGE(PG8_SB(1, 1), b3 + hstep, voffB); PG8_STAGE(PG8_SA(1, 0), a3, voffA);
;             PG8_WAIT_V(8); PG8_WAIT_L(0); PG8_BAR; PG8_MMA(1, 0, At, B0); PG8_MMA(1, 1, At, B1); PG8_BAR; PG8_SCHED;
	s_setprio 1
	v_mfma_f32_16x16x32_bf16 v[60:63], v[138:141], v[192:195], 0
	v_mfma_f32_16x16x32_bf16 v[56:59], v[150:153], v[192:195], 0
	v_mfma_f32_16x16x32_bf16 v[52:55], v[138:141], v[200:203], 0
	v_mfma_f32_16x16x32_bf16 v[44:47], v[150:153], v[200:203], 0
	v_mfma_f32_16x16x32_bf16 v[36:39], v[138:141], v[208:211], 0
	v_mfma_f32_16x16x32_bf16 v[28:31], v[150:153], v[208:211], 0
	v_mfma_f32_16x16x32_bf16 v[20:23], v[138:141], v[216:219], 0
	v_mfma_f32_16x16x32_bf16 v[12:15], v[150:153], v[216:219], 0
	v_mfma_f32_16x16x32_bf16 v[60:63], v[146:149], v[196:199], v[60:63]
	v_mfma_f32_16x16x32_bf16 v[56:59], v[154:157], v[196:199], v[56:59]
	v_mfma_f32_16x16x32_bf16 v[52:55], v[146:149], v[204:207], v[52:55]
	v_mfma_f32_16x16x32_bf16 v[44:47], v[154:157], v[204:207], v[44:47]
	v_mfma_f32_16x16x32_bf16 v[36:39], v[146:149], v[212:215], v[36:39]
	v_mfma_f32_16x16x32_bf16 v[28:31], v[154:157], v[212:215], v[28:31]
	v_mfma_f32_16x16x32_bf16 v[20:23], v[146:149], v[220:223], v[20:23]
	v_mfma_f32_16x16x32_bf16 v[12:15], v[154:157], v[220:223], v[12:15]
	s_setprio 0
	s_setprio 1
	v_mfma_f32_16x16x32_bf16 v[48:51], v[158:161], v[192:195], 0
	v_mfma_f32_16x16x32_bf16 v[40:43], v[170:173], v[192:195], 0
	v_mfma_f32_16x16x32_bf16 v[32:35], v[158:161], v[200:203], 0
	v_mfma_f32_16x16x32_bf16 v[24:27], v[170:173], v[200:203], 0
	v_mfma_f32_16x16x32_bf16 v[16:19], v[158:161], v[208:211], 0
	v_mfma_f32_16x16x32_bf16 v[8:11], v[170:173], v[208:211], 0
	v_mfma_f32_16x16x32_bf16 v[4:7], v[158:161], v[216:219], 0
	v_mfma_f32_16x16x32_bf16 v[0:3], v[170:173], v[216:219], 0
	v_mfma_f32_16x16x32_bf16 v[48:51], v[162:165], v[196:199], v[48:51]
	v_mfma_f32_16x16x32_bf16 v[40:43], v[188:191], v[196:199], v[40:43]
	v_mfma_f32_16x16x32_bf16 v[32:35], v[162:165], v[204:207], v[32:35]
	v_mfma_f32_16x16x32_bf16 v[24:27], v[188:191], v[204:207], v[24:27]
	s_add_i32 s59, 0, 0x18000
	v_mfma_f32_16x16x32_bf16 v[16:19], v[162:165], v[212:215], v[16:19]
	s_add_i32 s60, 0, 0x1c000
	v_mfma_f32_16x16x32_bf16 v[8:11], v[188:191], v[212:215], v[8:11]
	v_add_u32_e32 v240, s59, v143
	v_mfma_f32_16x16x32_bf16 v[4:7], v[162:165], v[220:223], v[4:7]
	v_add_u32_e32 v241, s60, v143
	v_mfma_f32_16x16x32_bf16 v[0:3], v[188:191], v[220:223], v[0:3]
	s_setprio 0
	s_barrier
	ds_read_b128 v[138:141], v240
	ds_read_b128 v[146:149], v240 offset:1024
	ds_read_b128 v[150:153], v240 offset:2048
	ds_read_b128 v[154:157], v240 offset:3072
	ds_read_b128 v[158:161], v241
	ds_read_b128 v[162:165], v241 offset:1024
	ds_read_b128 v[170:173], v241 offset:2048
	ds_read_b128 v[188:191], v241 offset:3072
	ds_read_b128 v[192:195], v145 offset:32768
	ds_read_b128 v[196:199], v145 offset:33792
	ds_read_b128 v[200:203], v145 offset:34816
	ds_read_b128 v[204:207], v145 offset:35840
	ds_read_b128 v[208:211], v145 offset:36864
	ds_read_b128 v[212:215], v145 offset:37888
	ds_read_b128 v[216:219], v145 offset:38912
	ds_read_b128 v[220:223], v145 offset:39936
	s_add_u32 s46, s46, 0x40000
	s_addc_u32 s47, s47, 0
	s_mov_b32 m0, s35
	v_lshl_add_u64 v[236:237], s[46:47], 0, v[132:133]
	global_load_lds_dwordx4 v[236:237], off
	v_lshl_add_u64 v[236:237], s[46:47], 0, v[130:131]
	s_mov_b32 m0, s48
	s_nop 0
	global_load_lds_dwordx4 v[236:237], off
	s_waitcnt vmcnt(8)
	s_waitcnt lgkmcnt(0)
	s_barrier
	s_setprio 1
	v_mfma_f32_16x16x32_bf16 v[124:127], v[138:141], v[192:195], v[124:127]
	v_mfma_f32_16x16x32_bf16 v[120:123], v[150:153], v[192:195], v[120:123]
	v_mfma_f32_16x16x32_bf16 v[116:119], v[138:141], v[200:203], v[116:119]
	v_mfma_f32_16x16x32_bf16 v[108:111], v[150:153], v[200:203], v[108:111]
	v_mfma_f32_16x16x32_bf16 v[100:103], v[138:141], v[208:211], v[100:103]
	v_mfma_f32_16x16x32_bf16 v[92:95], v[150:153], v[208:211], v[92:95]
	v_mfma_f32_16x16x32_bf16 v[84:87], v[138:141], v[216:219], v[84:87]
	v_mfma_f32_16x16x32_bf16 v[76:79], v[150:153], v[216:219], v[76:79]
	v_mfma_f32_16x16x32_bf16 v[124:127], v[146:149], v[196:199], v[124:127]
	v_mfma_f32_16x16x32_bf16 v[120:123], v[154:157], v[196:199], v[120:123]
	v_mfma_f32_16x16x32_bf16 v[116:119], v[146:149], v[204:207], v[116:119]
	v_mfma_f32_16x16x32_bf16 v[108:111], v[154:157], v[204:207], v[108:111]
	v_mfma_f32_16x16x32_bf16 v[100:103], v[146:149], v[212:215], v[100:103]
	v_mfma_f32_16x16x32_bf16 v[92:95], v[154:157], v[212:215], v[92:95]
	v_mfma_f32_16x16x32_bf16 v[84:87], v[146:149], v[220:223], v[84:87]
	v_mfma_f32_16x16x32_bf16 v[76:79], v[154:157], v[220:223], v[76:79]
	s_setprio 0
	s_setprio 1
	v_mfma_f32_16x16x32_bf16 v[112:115], v[158:161], v[192:195], v[112:115]
	v_mfma_f32_16x16x32_bf16 v[104:107], v[170:173], v[192:195], v[104:107]
	v_mfma_f32_16x16x32_bf16 v[96:99], v[158:161], v[200:203], v[96:99]
	v_mfma_f32_16x16x32_bf16 v[88:91], v[170:173], v[200:203], v[88:91]
	v_mfma_f32_16x16x32_bf16 v[80:83], v[158:161], v[208:211], v[80:83]
	v_mfma_f32_16x16x32_bf16 v[72:75], v[170:173], v[208:211], v[72:75]
	v_mfma_f32_16x16x32_bf16 v[68:71], v[158:161], v[216:219], v[68:71]
	v_mfma_f32_16x16x32_bf16 v[64:67], v[170:173], v[216:219], v[64:67]
	v_mfma_f32_16x16x32_bf16 v[112:115], v[162:165], v[196:199], v[112:115]
	v_mfma_f32_16x16x32_bf16 v[104:107], v[188:191], v[196:199], v[104:107]
	v_mfma_f32_16x16x32_bf16 v[96:99], v[162:165], v[204:207], v[96:99]
	v_mfma_f32_16x16x32_bf16 v[88:91], v[188:191], v[204:207], v[88:91]
	v_mfma_f32_16x16x32_bf16 v[80:83], v[162:165], v[212:215], v[80:83]
	s_add_i32 s46, s59, s6
	v_mfma_f32_16x16x32_bf16 v[72:75], v[188:191], v[212:215], v[72:75]
	v_lshl_add_u64 v[166:167], v[166:167], 0, s[30:31]
	v_mfma_f32_16x16x32_bf16 v[68:71], v[162:165], v[220:223], v[68:71]
	s_mov_b32 m0, s46
	v_mfma_f32_16x16x32_bf16 v[64:67], v[188:191], v[220:223], v[64:67]
	s_setprio 0
	s_barrier
; #define PG8_STAGE(bufoff, gbase, voff) do { _Pragma("unroll") for (int _i = 0; _i < 2; ++_i) \
;         __builtin_amdgcn_global_load_lds((const unsigned*)((const char*)(gbase) + (voff)[_i]), (PG8_LAS unsigned*)(lds + (bufoff) + ldsw + _i * 8192), 16, 0, 0); } while (0)
; #define PG8_LDA(dst, b, h) do { _Pragma("unroll") for (int m = 0; m < 4; ++m) _Pragma("unroll") for (int k = 0; k < 2; ++k) dst[m][k] = *(const PG8_LAS bf16x8*)(lds + PG8_SA(b, h) + aoff + m * 2048 + k * 1024); } while (0)
; #define PG8_LDB(dst, b, h) do { _Pragma("unroll") for (int n = 0; n < 2; ++n) _Pragma("unroll") for (int k = 0; k < 2; ++k) dst[n][k] = *(const PG8_LAS bf16x8*)(lds + PG8_SB(b, h) + boff + n * 2048 + k * 1024); } while (0)
; #define PG8_MMA(ai, bj, At, Bt) do { __builtin_amdgcn_s_setprio(1); _Pragma("unroll") for (int m = 0; m < 4; ++m) _Pragma("unroll") for (int n = 0; n < 2; ++n) _Pragma("unroll") for (int k = 0; k < 2; ++k) \
;         acc[ai][bj][m][n] = __builtin_amdgcn_mfma_f32_16x16x32_bf16(Bt[n][k], At[m][k], acc[ai][bj][m][n], 0, 0, 0); __builtin_amdgcn_s_setprio(0); } while (0)
; #define PG8_WAIT_V(n) asm volatile("s_waitcnt vmcnt(" #n ")" ::: "memory")
; template <class Epi, class Sched, bool ALIGN_EPI = false, bool SP2 = false>
; __device__ __forceinline__ void gemm_phase(PG8_LAS unsigned char* lds, const Gemm g, const Sched& S, const Epi& E) {
;     ...
;             PG8_LDB(B0, 0, 0); PG8_LDB(B1, 0, 1); PG8_SCHED; PG8_LDA(At, 0, 0); PG8_STAGE(PG8_SA(1, 1), a1 + hstepA, voffA);
;             PG8_WAIT_V(8); PG8_WAIT_L(0); PG8_BAR; PG8_MMA(0, 0, At, B0); PG8_MMA(0, 1, At, B1); PG8_BAR; PG8_SCHED;
;             PG8_LDA(At, 0, 1); PG8_STAGE(PG8_SB(0, 0), b2, voffB); PG8_STAGE(PG8_SB(0, 1), b2 + hstep, voffB); PG8_STAGE(PG8_SA(0, 0), a2, voffA);
;             PG8_WAIT_V(8); PG8_WAIT_L(0); PG8_BAR; PG8_MMA(1, 0, At, B0); PG8_MMA(1, 1, At, B1); PG8_BAR; PG8_SCHED;
;             PG8_LDB(B0, 1, 0); PG8_LDB(B1, 1, 1); PG8_SCHED; PG8_LDA(At, 1, 0); PG8_STAGE(PG8_SA(0, 1), a2 + hstepA, voffA);
;             PG8_WAIT_V(8); PG8_WAIT_L(0); PG8_BAR; PG8_MMA(0, 0, At, B0); PG8_MMA(0, 1, At, B1); PG8_BAR; PG8_SCHED;
;             PG8_LDA(At, 1, 1); PG8_STAGE(PG8_SB(1, 0), b3, voffB); PG8_STAGE(PG8_SB(1, 1), b3 + hstep, voffB); PG8_STAGE(PG8_SA(1, 0), a3, voffA);
;             PG8_WAIT_V(8); PG8_WAIT_L(0); PG8_BAR; PG8_MMA(1, 0, At, B0); PG8_MMA(1, 1, At, B1); PG8_BAR; PG8_SCHED;
	ds_read_b128 v[192:195], v145 offset:49152
	ds_read_b128 v[196:199], v145 offset:50176
	ds_read_b128 v[200:203], v145 offset:51200
	ds_read_b128 v[204:207], v145 offset:52224
	ds_read_b128 v[208:211], v145 offset:53248
	ds_read_b128 v[212:215], v145 offset:54272
	ds_read_b128 v[216:219], v145 offset:55296
	ds_read_b128 v[220:223], v145 offset:56320
	global_load_lds_dwordx4 v[166:167], off
	s_add_i32 m0, s46, 0x2000
	s_add_u32 s44, s44, 0x40080
	v_lshl_add_u64 v[166:167], v[178:179], 0, s[30:31]
	s_addc_u32 s45, s45, 0
	s_add_i32 s46, s60, s6
	global_load_lds_dwordx4 v[166:167], off
	v_lshl_add_u64 v[166:167], s[44:45], 0, v[168:169]
	s_mov_b32 m0, s46
	s_nop 0
	global_load_lds_dwordx4 v[166:167], off
	v_lshl_add_u64 v[166:167], s[44:45], 0, v[128:129]
	s_add_i32 m0, s46, 0x2000
	s_nop 0
	global_load_lds_dwordx4 v[166:167], off
	v_lshl_add_u64 v[166:167], v[224:225], 0, s[30:31]
	s_mov_b32 m0, s49
	s_nop 0
	global_load_lds_dwordx4 v[166:167], off
	v_lshl_add_u64 v[166:167], v[234:235], 0, s[30:31]
	s_mov_b32 m0, s50
	s_nop 0
	global_load_lds_dwordx4 v[166:167], off
	s_waitcnt vmcnt(8)
	s_waitcnt lgkmcnt(0)
	s_barrier
	s_setprio 1
	v_mfma_f32_16x16x32_bf16 v[60:63], v[138:141], v[192:195], v[60:63]
	v_mfma_f32_16x16x32_bf16 v[56:59], v[150:153], v[192:195], v[56:59]
	v_mfma_f32_16x16x32_bf16 v[52:55], v[138:141], v[200:203], v[52:55]
	v_mfma_f32_16x16x32_bf16 v[44:47], v[150:153], v[200:203], v[44:47]
	v_mfma_f32_16x16x32_bf16 v[36:39], v[138:141], v[208:211], v[36:39]
	v_mfma_f32_16x16x32_bf16 v[28:31], v[150:153], v[208:211], v[28:31]
	v_mfma_f32_16x16x32_bf16 v[20:23], v[138:141], v[216:219], v[20:23]
	v_mfma_f32_16x16x32_bf16 v[12:15], v[150:153], v[216:219], v[12:15]
	v_mfma_f32_16x16x32_bf16 v[60:63], v[146:149], v[196:199], v[60:63]
	v_mfma_f32_16x16x32_bf16 v[56:59], v[154:157], v[196:199], v[56:59]
	v_mfma_f32_16x16x32_bf16 v[52:55], v[146:149], v[204:207], v[52:55]
	v_mfma_f32_16x16x32_bf16 v[44:47], v[154:157], v[204:207], v[44:47]
	v_mfma_f32_16x16x32_bf16 v[36:39], v[146:149], v[212:215], v[36:39]
	v_mfma_f32_16x16x32_bf16 v[28:31], v[154:157], v[212:215], v[28:31]
	v_mfma_f32_16x16x32_bf16 v[20:23], v[146:149], v[220:223], v[20:23]
	v_mfma_f32_16x16x32_bf16 v[12:15], v[154:157], v[220:223], v[12:15]
	s_add_i32 s58, s58, 2
	s_setprio 0
	s_setprio 1
	v_mfma_f32_16x16x32_bf16 v[48:51], v[158:161], v[192:195], v[48:51]
	s_add_u32 s56, s56, 0x100
	v_mfma_f32_16x16x32_bf16 v[40:43], v[170:173], v[192:195], v[40:43]
	s_addc_u32 s57, s57, 0
	v_mfma_f32_16x16x32_bf16 v[32:35], v[158:161], v[200:203], v[32:35]
	s_add_u32 s42, s42, 0x100
	v_mfma_f32_16x16x32_bf16 v[24:27], v[170:173], v[200:203], v[24:27]
	s_addc_u32 s43, s43, 0
	v_mfma_f32_16x16x32_bf16 v[16:19], v[158:161], v[208:211], v[16:19]
	s_add_u32 s44, s42, 0xfffc0080
	v_mfma_f32_16x16x32_bf16 v[8:11], v[170:173], v[208:211], v[8:11]
	s_addc_u32 s45, s43, -1
	v_mfma_f32_16x16x32_bf16 v[4:7], v[158:161], v[216:219], v[4:7]
	s_add_i32 s59, 0, 0x10000
	v_mfma_f32_16x16x32_bf16 v[0:3], v[170:173], v[216:219], v[0:3]
	s_cmp_eq_u32 s58, 12
	v_mfma_f32_16x16x32_bf16 v[48:51], v[162:165], v[196:199], v[48:51]
	s_cselect_b32 s47, s27, s45
	v_mfma_f32_16x16x32_bf16 v[40:43], v[188:191], v[196:199], v[40:43]
	s_cselect_b32 s46, s54, s44
	v_mfma_f32_16x16x32_bf16 v[32:35], v[162:165], v[204:207], v[32:35]
	s_cselect_b32 s45, s25, s57
	v_mfma_f32_16x16x32_bf16 v[24:27], v[188:191], v[204:207], v[24:27]
	s_cselect_b32 s44, s55, s56
	v_mfma_f32_16x16x32_bf16 v[16:19], v[162:165], v[212:215], v[16:19]
	s_add_i32 s62, 0, 0x14000
	v_mfma_f32_16x16x32_bf16 v[8:11], v[188:191], v[212:215], v[8:11]
	v_add_u32_e32 v242, s59, v143
	v_mfma_f32_16x16x32_bf16 v[4:7], v[162:165], v[220:223], v[4:7]
	v_add_u32_e32 v166, s62, v143
	v_mfma_f32_16x16x32_bf16 v[0:3], v[188:191], v[220:223], v[0:3]
	s_setprio 0
	s_barrier
.LBB0_196:
	ds_read_b128 v[138:141], v242
	ds_read_b128 v[146:149], v242 offset:1024
	ds_read_b128 v[150:153], v242 offset:2048
	ds_read_b128 v[154:157], v242 offset:3072
	ds_read_b128 v[158:161], v166
	ds_read_b128 v[162:165], v166 offset:1024
	ds_read_b128 v[170:173], v166 offset:2048
	ds_read_b128 v[188:191], v166 offset:3072
	ds_read_b128 v[192:195], v145
	ds_read_b128 v[196:199], v145 offset:1024
	ds_read_b128 v[200:203], v145 offset:2048
	ds_read_b128 v[204:207], v145 offset:3072
	ds_read_b128 v[208:211], v145 offset:4096
	ds_read_b128 v[212:215], v145 offset:5120
	ds_read_b128 v[216:219], v145 offset:6144
	ds_read_b128 v[220:223], v145 offset:7168
	s_add_i32 m0, s7, 0xc000
	v_lshl_add_u64 v[166:167], s[42:43], 0, v[136:137]
	global_load_lds_dwordx4 v[166:167], off
	v_lshl_add_u64 v[166:167], s[42:43], 0, v[134:135]
	s_add_i32 m0, s7, 0xe000
	s_nop 0
	global_load_lds_dwordx4 v[166:167], off
	s_waitcnt vmcnt(8)
	s_waitcnt lgkmcnt(0)
	s_barrier
; #define PG8_STAGE(bufoff, gbase, voff) do { _Pragma("unroll") for (int _i = 0; _i < 2; ++_i) \
;         __builtin_amdgcn_global_load_lds((const unsigned*)((const char*)(gbase) + (voff)[_i]), (PG8_LAS unsigned*)(lds + (bufoff) + ldsw + _i * 8192), 16, 0, 0); } while (0)
; #define PG8_LDA(dst, b, h) do { _Pragma("unroll") for (int m = 0; m < 4; ++m) _Pragma("unroll") for (int k = 0; k < 2; ++k) dst[m][k] = *(const PG8_LAS bf16x8*)(lds + PG8_SA(b, h) + aoff + m * 2048 + k * 1024); } while (0)
; #define PG8_LDB(dst, b, h) do { _Pragma("unroll") for (int n = 0; n < 2; ++n) _Pragma("unroll") for (int k = 0; k < 2; ++k) dst[n][k] = *(const PG8_LAS bf16x8*)(lds + PG8_SB(b, h) + boff + n * 2048 + k * 1024); } while (0)
; #define PG8_MMA(ai, bj, At, Bt) do { __builtin_amdgcn_s_setprio(1); _Pragma("unroll") for (int m = 0; m < 4; ++m) _Pragma("unroll") for (int n = 0; n < 2; ++n) _Pragma("unroll") for (int k = 0; k < 2; ++k) \
;         acc[ai][bj][m][n] = __builtin_amdgcn_mfma_f32_16x16x32_bf16(Bt[n][k], At[m][k], acc[ai][bj][m][n], 0, 0, 0); __builtin_amdgcn_s_setprio(0); } while (0)
; #define PG8_WAIT_V(n) asm volatile("s_waitcnt vmcnt(" #n ")" ::: "memory")
; template <class Epi, class Sched, bool ALIGN_EPI = false, bool SP2 = false>
; __device__ __forceinline__ void gemm_phase(PG8_LAS unsigned char* lds, const Gemm g, const Sched& S, const Epi& E) {
;     ...
;             PG8_LDB(B0, 0, 0); PG8_LDB(B1, 0, 1); PG8_SCHED; PG8_LDA(At, 0, 0); PG8_STAGE(PG8_SA(1, 1), a1 + hstepA, voffA);
;             PG8_WAIT_V(8); PG8_WAIT_L(0); PG8_BAR; PG8_MMA(0, 0, At, B0); PG8_MMA(0, 1, At, B1); PG8_BAR; PG8_SCHED;
;             PG8_LDA(At, 0, 1); PG8_STAGE(PG8_SB(0, 0), b2, voffB); PG8_STAGE(PG8_SB(0, 1), b2 + hstep, voffB); PG8_STAGE(PG8_SA(0, 0), a2, voffA);
;             PG8_WAIT_V(8); PG8_WAIT_L(0); PG8_BAR; PG8_MMA(1, 0, At, B0); PG8_MMA(1, 1, At, B1); PG8_BAR; PG8_SCHED;
;             PG8_LDB(B0, 1, 0); PG8_LDB(B1, 1, 1); PG8_SCHED; PG8_LDA(At, 1, 0); PG8_STAGE(PG8_SA(0, 1), a2 + hstepA, voffA);
;             PG8_WAIT_V(8); PG8_WAIT_L(0); PG8_BAR; PG8_MMA(0, 0, At, B0); PG8_MMA(0, 1, At, B1); PG8_BAR; PG8_SCHED;
;             PG8_LDA(At, 1, 1); PG8_STAGE(PG8_SB(1, 0), b3, voffB); PG8_STAGE(PG8_SB(1, 1), b3 + hstep, voffB); PG8_STAGE(PG8_SA(1, 0), a3, voffA);
;             PG8_WAIT_V(8); PG8_WAIT_L(0); PG8_BAR; PG8_MMA(1, 0, At, B0); PG8_MMA(1, 1, At, B1); PG8_BAR; PG8_SCHED;
	s_setprio 1
	v_mfma_f32_16x16x32_bf16 v[124:127], v[138:141], v[192:195], v[124:127]
	v_mfma_f32_16x16x32_bf16 v[120:123], v[150:153], v[192:195], v[120:123]
	v_mfma_f32_16x16x32_bf16 v[116:119], v[138:141], v[200:203], v[116:119]
	v_mfma_f32_16x16x32_bf16 v[108:111], v[150:153], v[200:203], v[108:111]
	v_mfma_f32_16x16x32_bf16 v[100:103], v[138:141], v[208:211], v[100:103]
	v_mfma_f32_16x16x32_bf16 v[92:95], v[150:153], v[208:211], v[92:95]
	v_mfma_f32_16x16x32_bf16 v[84:87], v[138:141], v[216:219], v[84:87]
	v_mfma_f32_16x16x32_bf16 v[76:79], v[150:153], v[216:219], v[76:79]
	v_mfma_f32_16x16x32_bf16 v[124:127], v[146:149], v[196:199], v[124:127]
	v_mfma_f32_16x16x32_bf16 v[120:123], v[154:157], v[196:199], v[120:123]
	v_mfma_f32_16x16x32_bf16 v[116:119], v[146:149], v[204:207], v[116:119]
	v_mfma_f32_16x16x32_bf16 v[108:111], v[154:157], v[204:207], v[108:111]
	v_mfma_f32_16x16x32_bf16 v[100:103], v[146:149], v[212:215], v[100:103]
	v_mfma_f32_16x16x32_bf16 v[92:95], v[154:157], v[212:215], v[92:95]
	v_mfma_f32_16x16x32_bf16 v[84:87], v[146:149], v[220:223], v[84:87]
	v_mfma_f32_16x16x32_bf16 v[76:79], v[154:157], v[220:223], v[76:79]
	s_setprio 0
	s_setprio 1
	v_mfma_f32_16x16x32_bf16 v[112:115], v[158:161], v[192:195], v[112:115]
	v_mfma_f32_16x16x32_bf16 v[104:107], v[170:173], v[192:195], v[104:107]
	v_mfma_f32_16x16x32_bf16 v[96:99], v[158:161], v[200:203], v[96:99]
	v_mfma_f32_16x16x32_bf16 v[88:91], v[170:173], v[200:203], v[88:91]
	v_mfma_f32_16x16x32_bf16 v[80:83], v[158:161], v[208:211], v[80:83]
	v_mfma_f32_16x16x32_bf16 v[72:75], v[170:173], v[208:211], v[72:75]
	v_mfma_f32_16x16x32_bf16 v[68:71], v[158:161], v[216:219], v[68:71]
	v_mfma_f32_16x16x32_bf16 v[64:67], v[170:173], v[216:219], v[64:67]
	v_mfma_f32_16x16x32_bf16 v[112:115], v[162:165], v[196:199], v[112:115]
	v_mfma_f32_16x16x32_bf16 v[104:107], v[188:191], v[196:199], v[104:107]
	v_mfma_f32_16x16x32_bf16 v[96:99], v[162:165], v[204:207], v[96:99]
	v_mfma_f32_16x16x32_bf16 v[88:91], v[188:191], v[204:207], v[88:91]
	v_mfma_f32_16x16x32_bf16 v[80:83], v[162:165], v[212:215], v[80:83]
	s_add_i32 s59, s59, s6
	v_mfma_f32_16x16x32_bf16 v[72:75], v[188:191], v[212:215], v[72:75]
	v_lshl_add_u64 v[166:167], s[44:45], 0, v[168:169]
	v_mfma_f32_16x16x32_bf16 v[68:71], v[162:165], v[220:223], v[68:71]
	s_mov_b32 m0, s59
	v_mfma_f32_16x16x32_bf16 v[64:67], v[188:191], v[220:223], v[64:67]
	s_setprio 0
	s_barrier
	ds_read_b128 v[192:195], v145 offset:16384
	ds_read_b128 v[196:199], v145 offset:17408
	ds_read_b128 v[200:203], v145 offset:18432
	ds_read_b128 v[204:207], v145 offset:19456
	ds_read_b128 v[208:211], v145 offset:20480
	ds_read_b128 v[212:215], v145 offset:21504
	ds_read_b128 v[216:219], v145 offset:22528
	ds_read_b128 v[220:223], v145 offset:23552
	global_load_lds_dwordx4 v[166:167], off
	s_add_i32 m0, s59, 0x2000
	s_add_u32 s60, s44, 0x40000
	v_lshl_add_u64 v[178:179], s[44:45], 0, v[128:129]
	s_addc_u32 s61, s45, 0
	s_add_i32 s59, s62, s6
	global_load_lds_dwordx4 v[178:179], off
	v_lshl_add_u64 v[224:225], s[60:61], 0, v[168:169]
	s_mov_b32 m0, s59
	v_lshl_add_u64 v[234:235], s[46:47], 0, v[130:131]
	global_load_lds_dwordx4 v[224:225], off
	v_lshl_add_u64 v[224:225], s[60:61], 0, v[128:129]
	s_add_i32 m0, s59, 0x2000
	s_nop 0
	global_load_lds_dwordx4 v[224:225], off
	v_lshl_add_u64 v[224:225], s[46:47], 0, v[132:133]
	s_mov_b32 m0, s7
	s_nop 0
	global_load_lds_dwordx4 v[224:225], off
	s_mov_b32 m0, s34
	s_nop 0
	global_load_lds_dwordx4 v[234:235], off
	s_waitcnt vmcnt(8)
	s_waitcnt lgkmcnt(0)
	s_barrier
	s_setprio 1
	v_mfma_f32_16x16x32_bf16 v[60:63], v[138:141], v[192:195], v[60:63]
	v_mfma_f32_16x16x32_bf16 v[56:59], v[150:153], v[192:195], v[56:59]
	v_mfma_f32_16x16x32_bf16 v[52:55], v[138:141], v[200:203], v[52:55]
	v_mfma_f32_16x16x32_bf16 v[44:47], v[150:153], v[200:203], v[44:47]
	v_mfma_f32_16x16x32_bf16 v[36:39], v[138:141], v[208:211], v[36:39]
	v_mfma_f32_16x16x32_bf16 v[28:31], v[150:153], v[208:211], v[28:31]
	v_mfma_f32_16x16x32_bf16 v[20:23], v[138:141], v[216:219], v[20:23]
	v_mfma_f32_16x16x32_bf16 v[12:15], v[150:153], v[216:219], v[12:15]
	v_mfma_f32_16x16x32_bf16 v[60:63], v[146:149], v[196:199], v[60:63]
	v_mfma_f32_16x16x32_bf16 v[56:59], v[154:157], v[196:199], v[56:59]
	v_mfma_f32_16x16x32_bf16 v[52:55], v[146:149], v[204:207], v[52:55]
	v_mfma_f32_16x16x32_bf16 v[44:47], v[154:157], v[204:207], v[44:47]
	v_mfma_f32_16x16x32_bf16 v[36:39], v[146:149], v[212:215], v[36:39]
	v_mfma_f32_16x16x32_bf16 v[28:31], v[154:157], v[212:215], v[28:31]
	v_mfma_f32_16x16x32_bf16 v[20:23], v[146:149], v[220:223], v[20:23]
	v_mfma_f32_16x16x32_bf16 v[12:15], v[154:157], v[220:223], v[12:15]
	s_setprio 0
	s_setprio 1
	v_mfma_f32_16x16x32_bf16 v[48:51], v[158:161], v[192:195], v[48:51]
	v_mfma_f32_16x16x32_bf16 v[40:43], v[170:173], v[192:195], v[40:43]
	v_mfma_f32_16x16x32_bf16 v[32:35], v[158:161], v[200:203], v[32:35]
	v_mfma_f32_16x16x32_bf16 v[24:27], v[170:173], v[200:203], v[24:27]
	v_mfma_f32_16x16x32_bf16 v[16:19], v[158:161], v[208:211], v[16:19]
	v_mfma_f32_16x16x32_bf16 v[8:11], v[170:173], v[208:211], v[8:11]
	v_mfma_f32_16x16x32_bf16 v[4:7], v[158:161], v[216:219], v[4:7]
	v_mfma_f32_16x16x32_bf16 v[0:3], v[170:173], v[216:219], v[0:3]
	v_mfma_f32_16x16x32_bf16 v[48:51], v[162:165], v[196:199], v[48:51]
	v_mfma_f32_16x16x32_bf16 v[40:43], v[188:191], v[196:199], v[40:43]
	v_mfma_f32_16x16x32_bf16 v[32:35], v[162:165], v[204:207], v[32:35]
	v_mfma_f32_16x16x32_bf16 v[24:27], v[188:191], v[204:207], v[24:27]
	s_add_i32 s59, 0, 0x18000
	v_mfma_f32_16x16x32_bf16 v[16:19], v[162:165], v[212:215], v[16:19]
	s_add_i32 s60, 0, 0x1c000
	v_mfma_f32_16x16x32_bf16 v[8:11], v[188:191], v[212:215], v[8:11]
	v_add_u32_e32 v240, s59, v143
	v_mfma_f32_16x16x32_bf16 v[4:7], v[162:165], v[220:223], v[4:7]
	v_add_u32_e32 v241, s60, v143
	v_mfma_f32_16x16x32_bf16 v[0:3], v[188:191], v[220:223], v[0:3]
	s_setprio 0
	s_barrier
; #define PG8_STAGE(bufoff, gbase, voff) do { _Pragma("unroll") for (int _i = 0; _i < 2; ++_i) \
;         __builtin_amdgcn_global_load_lds((const unsigned*)((const char*)(gbase) + (voff)[_i]), (PG8_LAS unsigned*)(lds + (bufoff) + ldsw + _i * 8192), 16, 0, 0); } while (0)
; #define PG8_LDA(dst, b, h) do { _Pragma("unroll") for (int m = 0; m < 4; ++m) _Pragma("unroll") for (int k = 0; k < 2; ++k) dst[m][k] = *(const PG8_LAS bf16x8*)(lds + PG8_SA(b, h) + aoff + m * 2048 + k * 1024); } while (0)
; #define PG8_LDB(dst, b, h) do { _Pragma("unroll") for (int n = 0; n < 2; ++n) _Pragma("unroll") for (int k = 0; k < 2; ++k) dst[n][k] = *(const PG8_LAS bf16x8*)(lds + PG8_SB(b, h) + boff + n * 2048 + k * 1024); } while (0)
; #define PG8_MMA(ai, bj, At, Bt) do { __builtin_amdgcn_s_setprio(1); _Pragma("unroll") for (int m = 0; m < 4; ++m) _Pragma("unroll") for (int n = 0; n < 2; ++n) _Pragma("unroll") for (int k = 0; k < 2; ++k) \
;         acc[ai][bj][m][n] = __builtin_amdgcn_mfma_f32_16x16x32_bf16(Bt[n][k], At[m][k], acc[ai][bj][m][n], 0, 0, 0); __builtin_amdgcn_s_setprio(0); } while (0)
; #define PG8_WAIT_V(n) asm volatile("s_waitcnt vmcnt(" #n ")" ::: "memory")
; template <class Epi, class Sched, bool ALIGN_EPI = false, bool SP2 = false>
; __device__ __forceinline__ void gemm_phase(PG8_LAS unsigned char* lds, const Gemm g, const Sched& S, const Epi& E) {
;     ...
;             PG8_LDB(B0, 0, 0); PG8_LDB(B1, 0, 1); PG8_SCHED; PG8_LDA(At, 0, 0); PG8_STAGE(PG8_SA(1, 1), a1 + hstepA, voffA);
;             PG8_WAIT_V(8); PG8_WAIT_L(0); PG8_BAR; PG8_MMA(0, 0, At, B0); PG8_MMA(0, 1, At, B1); PG8_BAR; PG8_SCHED;
;             PG8_LDA(At, 0, 1); PG8_STAGE(PG8_SB(0, 0), b2, voffB); PG8_STAGE(PG8_SB(0, 1), b2 + hstep, voffB); PG8_STAGE(PG8_SA(0, 0), a2, voffA);
;             PG8_WAIT_V(8); PG8_WAIT_L(0); PG8_BAR; PG8_MMA(1, 0, At, B0); PG8_MMA(1, 1, At, B1); PG8_BAR; PG8_SCHED;
;             PG8_LDB(B0, 1, 0); PG8_LDB(B1, 1, 1); PG8_SCHED; PG8_LDA(At, 1, 0); PG8_STAGE(PG8_SA(0, 1), a2 + hstepA, voffA);
;             PG8_WAIT_V(8); PG8_WAIT_L(0); PG8_BAR; PG8_MMA(0, 0, At, B0); PG8_MMA(0, 1, At, B1); PG8_BAR; PG8_SCHED;
;             PG8_LDA(At, 1, 1); PG8_STAGE(PG8_SB(1, 0), b3, voffB); PG8_STAGE(PG8_SB(1, 1), b3 + hstep, voffB); PG8_STAGE(PG8_SA(1, 0), a3, voffA);
;             PG8_WAIT_V(8); PG8_WAIT_L(0); PG8_BAR; PG8_MMA(1, 0, At, B0); PG8_MMA(1, 1, At, B1); PG8_BAR; PG8_SCHED;
	ds_read_b128 v[138:141], v240
	ds_read_b128 v[146:149], v240 offset:1024
	ds_read_b128 v[150:153], v240 offset:2048
	ds_read_b128 v[154:157], v240 offset:3072
	ds_read_b128 v[158:161], v241
	ds_read_b128 v[162:165], v241 offset:1024
	ds_read_b128 v[170:173], v241 offset:2048
	ds_read_b128 v[188:191], v241 offset:3072
	ds_read_b128 v[192:195], v145 offset:32768
	ds_read_b128 v[196:199], v145 offset:33792
	ds_read_b128 v[200:203], v145 offset:34816
	ds_read_b128 v[204:207], v145 offset:35840
	ds_read_b128 v[208:211], v145 offset:36864
	ds_read_b128 v[212:215], v145 offset:37888
	ds_read_b128 v[216:219], v145 offset:38912
	ds_read_b128 v[220:223], v145 offset:39936
	s_add_u32 s46, s46, 0x40000
	s_addc_u32 s47, s47, 0
	s_mov_b32 m0, s35
	v_lshl_add_u64 v[236:237], s[46:47], 0, v[132:133]
	global_load_lds_dwordx4 v[236:237], off
	v_lshl_add_u64 v[236:237], s[46:47], 0, v[130:131]
	s_mov_b32 m0, s48
	s_nop 0
	global_load_lds_dwordx4 v[236:237], off
	s_waitcnt vmcnt(8)
	s_waitcnt lgkmcnt(0)
	s_barrier
	s_setprio 1
	v_mfma_f32_16x16x32_bf16 v[124:127], v[138:141], v[192:195], v[124:127]
	v_mfma_f32_16x16x32_bf16 v[120:123], v[150:153], v[192:195], v[120:123]
	v_mfma_f32_16x16x32_bf16 v[116:119], v[138:141], v[200:203], v[116:119]
	v_mfma_f32_16x16x32_bf16 v[108:111], v[150:153], v[200:203], v[108:111]
	v_mfma_f32_16x16x32_bf16 v[100:103], v[138:141], v[208:211], v[100:103]
	v_mfma_f32_16x16x32_bf16 v[92:95], v[150:153], v[208:211], v[92:95]
	v_mfma_f32_16x16x32_bf16 v[84:87], v[138:141], v[216:219], v[84:87]
	v_mfma_f32_16x16x32_bf16 v[76:79], v[150:153], v[216:219], v[76:79]
	v_mfma_f32_16x16x32_bf16 v[124:127], v[146:149], v[196:199], v[124:127]
	v_mfma_f32_16x16x32_bf16 v[120:123], v[154:157], v[196:199], v[120:123]
	v_mfma_f32_16x16x32_bf16 v[116:119], v[146:149], v[204:207], v[116:119]
	v_mfma_f32_16x16x32_bf16 v[108:111], v[154:157], v[204:207], v[108:111]
	v_mfma_f32_16x16x32_bf16 v[100:103], v[146:149], v[212:215], v[100:103]
	v_mfma_f32_16x16x32_bf16 v[92:95], v[154:157], v[212:215], v[92:95]
	v_mfma_f32_16x16x32_bf16 v[84:87], v[146:149], v[220:223], v[84:87]
	v_mfma_f32_16x16x32_bf16 v[76:79], v[154:157], v[220:223], v[76:79]
	s_setprio 0
	s_setprio 1
	v_mfma_f32_16x16x32_bf16 v[112:115], v[158:161], v[192:195], v[112:115]
	v_mfma_f32_16x16x32_bf16 v[104:107], v[170:173], v[192:195], v[104:107]
	v_mfma_f32_16x16x32_bf16 v[96:99], v[158:161], v[200:203], v[96:99]
	v_mfma_f32_16x16x32_bf16 v[88:91], v[170:173], v[200:203], v[88:91]
	v_mfma_f32_16x16x32_bf16 v[80:83], v[158:161], v[208:211], v[80:83]
	v_mfma_f32_16x16x32_bf16 v[72:75], v[170:173], v[208:211], v[72:75]
	v_mfma_f32_16x16x32_bf16 v[68:71], v[158:161], v[216:219], v[68:71]
	v_mfma_f32_16x16x32_bf16 v[64:67], v[170:173], v[216:219], v[64:67]
	v_mfma_f32_16x16x32_bf16 v[112:115], v[162:165], v[196:199], v[112:115]
	v_mfma_f32_16x16x32_bf16 v[104:107], v[188:191], v[196:199], v[104:107]
	v_mfma_f32_16x16x32_bf16 v[96:99], v[162:165], v[204:207], v[96:99]
	v_mfma_f32_16x16x32_bf16 v[88:91], v[188:191], v[204:207], v[88:91]
	v_mfma_f32_16x16x32_bf16 v[80:83], v[162:165], v[212:215], v[80:83]
	s_add_i32 s46, s59, s6
	v_mfma_f32_16x16x32_bf16 v[72:75], v[188:191], v[212:215], v[72:75]
	v_lshl_add_u64 v[166:167], v[166:167], 0, s[30:31]
	v_mfma_f32_16x16x32_bf16 v[68:71], v[162:165], v[220:223], v[68:71]
	s_mov_b32 m0, s46
	v_mfma_f32_16x16x32_bf16 v[64:67], v[188:191], v[220:223], v[64:67]
	s_setprio 0
	s_barrier
; template <class Epi, class Sched, bool ALIGN_EPI = false, bool SP2 = false>
; __device__ __forceinline__ void gemm_phase(PG8_LAS unsigned char* lds, const Gemm g, const Sched& S, const Epi& E) {
;     ...
;             PG8_LDB(B0, 0, 0); PG8_LDB(B1, 0, 1); PG8_SCHED; PG8_LDA(At, 0, 0); PG8_STAGE(PG8_SA(1, 1), a1 + hstepA, voffA);
;             PG8_WAIT_V(8); PG8_WAIT_L(0); PG8_BAR; PG8_MMA(0, 0, At, B0); PG8_MMA(0, 1, At, B1); PG8_BAR; PG8_SCHED;
;             PG8_LDA(At, 0, 1); PG8_STAGE(PG8_SB(0, 0), b2, voffB); PG8_STAGE(PG8_SB(0, 1), b2 + hstep, voffB); PG8_STAGE(PG8_SA(0, 0), a2, voffA);
;             PG8_WAIT_V(8); PG8_WAIT_L(0); PG8_BAR; PG8_MMA(1, 0, At, B0); PG8_MMA(1, 1, At, B1); PG8_BAR; PG8_SCHED;
;             PG8_LDB(B0, 1, 0); PG8_LDB(B1, 1, 1); PG8_SCHED; PG8_LDA(At, 1, 0); PG8_STAGE(PG8_SA(0, 1), a2 + hstepA, voffA);
;             PG8_WAIT_V(8); PG8_WAIT_L(0); PG8_BAR; PG8_MMA(0, 0, At, B0); PG8_MMA(0, 1, At, B1); PG8_BAR; PG8_SCHED;
;             PG8_LDA(At, 1, 1); PG8_STAGE(PG8_SB(1, 0), b3, voffB); PG8_STAGE(PG8_SB(1, 1), b3 + hstep, voffB); PG8_STAGE(PG8_SA(1, 0), a3, voffA);
;             PG8_WAIT_V(8); PG8_WAIT_L(0); PG8_BAR; PG8_MMA(1, 0, At, B0); PG8_MMA(1, 1, At, B1); PG8_BAR; PG8_SCHED;
;             } else {
;             PG8_LDB(B0, 0, 0); PG8_SCHED; PG8_LDA(At, 0, 0); PG8_STAGE(PG8_SA(1, 1), a1 + hstepA, voffA);
;             PG8_WAIT_L(8); PG8_BAR; PG8_WAIT_L(0); PG8_MMA(0, 0, At, B0); PG8_BAR; PG8_SCHED;
;             PG8_LDB(B1, 0, 1); PG8_STAGE(PG8_SB(0, 0), b2, voffB);
;             PG8_BAR; PG8_WAIT_L(0); PG8_MMA(0, 1, At, B1); PG8_BAR;
;             PG8_LDA(At, 0, 1); PG8_STAGE(PG8_SA(0, 0), a2, voffA);
;             PG8_BAR; PG8_WAIT_L(0); PG8_MMA(1, 0, At, B0); PG8_BAR; PG8_SCHED;
;             PG8_STAGE(PG8_SB(0, 1), b2 + hstep, voffB);
;             PG8_WAIT_V(6); PG8_BAR; PG8_MMA(1, 1, At, B1); PG8_BAR;
;             PG8_LDB(B0, 1, 0); PG8_SCHED; PG8_LDA(At, 1, 0); PG8_STAGE(PG8_SA(0, 1), a2 + hstepA, voffA);
;             PG8_WAIT_L(8); PG8_BAR; PG8_WAIT_L(0); PG8_MMA(0, 0, At, B0); PG8_BAR; PG8_SCHED;
;             PG8_LDB(B1, 1, 1); PG8_STAGE(PG8_SB(1, 0), b3, voffB);
;             PG8_BAR; PG8_WAIT_L(0); PG8_MMA(0, 1, At, B1); PG8_BAR;
;             PG8_LDA(At, 1, 1); PG8_STAGE(PG8_SA(1, 0), a3, voffA);
;             PG8_BAR; PG8_WAIT_L(0); PG8_MMA(1, 0, At, B0); PG8_BAR; PG8_SCHED;
	ds_read_b128 v[192:195], v145 offset:49152
	ds_read_b128 v[196:199], v145 offset:50176
	ds_read_b128 v[200:203], v145 offset:51200
	ds_read_b128 v[204:207], v145 offset:52224
	ds_read_b128 v[208:211], v145 offset:53248
	ds_read_b128 v[212:215], v145 offset:54272
	ds_read_b128 v[216:219], v145 offset:55296
	ds_read_b128 v[220:223], v145 offset:56320
	global_load_lds_dwordx4 v[166:167], off
	s_add_i32 m0, s46, 0x2000
	s_add_u32 s44, s44, 0x40080
	v_lshl_add_u64 v[166:167], v[178:179], 0, s[30:31]
	s_addc_u32 s45, s45, 0
	s_add_i32 s46, s60, s6
	global_load_lds_dwordx4 v[166:167], off
	v_lshl_add_u64 v[166:167], s[44:45], 0, v[168:169]
	s_mov_b32 m0, s46
	s_nop 0
	global_load_lds_dwordx4 v[166:167], off
	v_lshl_add_u64 v[166:167], s[44:45], 0, v[128:129]
	s_add_i32 m0, s46, 0x2000
	s_nop 0
	global_load_lds_dwordx4 v[166:167], off
	v_lshl_add_u64 v[166:167], v[224:225], 0, s[30:31]
	s_mov_b32 m0, s49
	s_nop 0
	global_load_lds_dwordx4 v[166:167], off
	v_lshl_add_u64 v[166:167], v[234:235], 0, s[30:31]
	s_mov_b32 m0, s50
	s_nop 0
	global_load_lds_dwordx4 v[166:167], off
	s_waitcnt vmcnt(8)
	s_waitcnt lgkmcnt(0)
	s_barrier
	s_setprio 1
	v_mfma_f32_16x16x32_bf16 v[60:63], v[138:141], v[192:195], v[60:63]
	v_mfma_f32_16x16x32_bf16 v[56:59], v[150:153], v[192:195], v[56:59]
	v_mfma_f32_16x16x32_bf16 v[52:55], v[138:141], v[200:203], v[52:55]
	v_mfma_f32_16x16x32_bf16 v[44:47], v[150:153], v[200:203], v[44:47]
	v_mfma_f32_16x16x32_bf16 v[36:39], v[138:141], v[208:211], v[36:39]
	v_mfma_f32_16x16x32_bf16 v[28:31], v[150:153], v[208:211], v[28:31]
	v_mfma_f32_16x16x32_bf16 v[20:23], v[138:141], v[216:219], v[20:23]
	v_mfma_f32_16x16x32_bf16 v[12:15], v[150:153], v[216:219], v[12:15]
	v_mfma_f32_16x16x32_bf16 v[60:63], v[146:149], v[196:199], v[60:63]
	v_mfma_f32_16x16x32_bf16 v[56:59], v[154:157], v[196:199], v[56:59]
	v_mfma_f32_16x16x32_bf16 v[52:55], v[146:149], v[204:207], v[52:55]
	v_mfma_f32_16x16x32_bf16 v[44:47], v[154:157], v[204:207], v[44:47]
	v_mfma_f32_16x16x32_bf16 v[36:39], v[146:149], v[212:215], v[36:39]
	v_mfma_f32_16x16x32_bf16 v[28:31], v[154:157], v[212:215], v[28:31]
	v_mfma_f32_16x16x32_bf16 v[20:23], v[146:149], v[220:223], v[20:23]
	s_add_i32 s58, s58, 2
	v_mfma_f32_16x16x32_bf16 v[12:15], v[154:157], v[220:223], v[12:15]
	s_add_u32 s56, s56, 0x100
	s_setprio 0
	s_setprio 1
	v_mfma_f32_16x16x32_bf16 v[48:51], v[158:161], v[192:195], v[48:51]
	s_addc_u32 s57, s57, 0
	v_mfma_f32_16x16x32_bf16 v[40:43], v[170:173], v[192:195], v[40:43]
	s_add_u32 s42, s42, 0x100
	v_mfma_f32_16x16x32_bf16 v[32:35], v[158:161], v[200:203], v[32:35]
	s_addc_u32 s43, s43, 0
	v_mfma_f32_16x16x32_bf16 v[24:27], v[170:173], v[200:203], v[24:27]
	s_add_u32 s44, s42, 0xfffc0080
	v_mfma_f32_16x16x32_bf16 v[16:19], v[158:161], v[208:211], v[16:19]
	s_addc_u32 s45, s43, -1
	v_mfma_f32_16x16x32_bf16 v[8:11], v[170:173], v[208:211], v[8:11]
	s_add_i32 s59, 0, 0x10000
	v_mfma_f32_16x16x32_bf16 v[4:7], v[158:161], v[216:219], v[4:7]
	s_cmp_eq_u32 s58, 12
	v_mfma_f32_16x16x32_bf16 v[0:3], v[170:173], v[216:219], v[0:3]
	s_cselect_b32 s47, s27, s45
	v_mfma_f32_16x16x32_bf16 v[48:51], v[162:165], v[196:199], v[48:51]
	s_cselect_b32 s46, s54, s44
	v_mfma_f32_16x16x32_bf16 v[40:43], v[188:191], v[196:199], v[40:43]
	s_cselect_b32 s45, s25, s57
	v_mfma_f32_16x16x32_bf16 v[32:35], v[162:165], v[204:207], v[32:35]
	s_cselect_b32 s44, s55, s56
	v_mfma_f32_16x16x32_bf16 v[24:27], v[188:191], v[204:207], v[24:27]
	s_add_i32 s62, 0, 0x14000
	v_mfma_f32_16x16x32_bf16 v[16:19], v[162:165], v[212:215], v[16:19]
	v_add_u32_e32 v242, s59, v143
	v_mfma_f32_16x16x32_bf16 v[8:11], v[188:191], v[212:215], v[8:11]
	v_add_u32_e32 v166, s62, v143
	v_mfma_f32_16x16x32_bf16 v[4:7], v[162:165], v[220:223], v[4:7]
	s_cmp_gt_u32 s58, 13
	v_mfma_f32_16x16x32_bf16 v[0:3], v[188:191], v[220:223], v[0:3]
	s_setprio 0
	s_barrier
	s_cbranch_scc0 .LBB0_196
	s_and_b64 vcc, exec, s[4:5]
	s_cbranch_vccz .LBB0_199
	s_barrier

; #define PG8_STAGE(bufoff, gbase, voff) do { _Pragma("unroll") for (int _i = 0; _i < 2; ++_i) \
;         __builtin_amdgcn_global_load_lds((const unsigned*)((const char*)(gbase) + (voff)[_i]), (PG8_LAS unsigned*)(lds + (bufoff) + ldsw + _i * 8192), 16, 0, 0); } while (0)
; #define PG8_LDA(dst, b, h) do { _Pragma("unroll") for (int m = 0; m < 4; ++m) _Pragma("unroll") for (int k = 0; k < 2; ++k) dst[m][k] = *(const PG8_LAS bf16x8*)(lds + PG8_SA(b, h) + aoff + m * 2048 + k * 1024); } while (0)
; template <class Epi, class Sched, bool ALIGN_EPI = false, bool SP2 = false>
; __device__ __forceinline__ void gemm_phase(PG8_LAS unsigned char* lds, const Gemm g, const Sched& S, const Epi& E) {
;     ...
;         const bool has_next = S.next(ui + 1, nxt);
;         const char* nA = has_next ? (const char*)g.A + (size_t)nxt.pm * tstepA : cA; const char* nB = has_next ? (const char*)g.Bt + (size_t)nxt.pn * tstep : cB;
;         for (int t = 0; t < nt; t += 2) {
;             const bool last = (t == nt - 2);
;             const char* a1 = cA + (size_t)(t + 1) * kstepA;
;             const char* a2 = last ? nA : cA + (size_t)(t + 2) * kstepA; const char* b2 = last ? nB : cB + (size_t)(t + 2) * kstep;
;             const char* a3 = a2 + kstepA; const char* b3 = b2 + kstep;
;             if (last && has_next) S.a_ready(nxt);
;             if constexpr (SP2) {
;             PG8_LDB(B0, 0, 0); PG8_LDB(B1, 0, 1); PG8_SCHED; PG8_LDA(At, 0, 0); PG8_STAGE(PG8_SA(1, 1), a1 + hstepA, voffA);
;             PG8_WAIT_V(8); PG8_WAIT_L(0); PG8_BAR; PG8_MMA(0, 0, At, B0); PG8_MMA(0, 1, At, B1); PG8_BAR; PG8_SCHED;
;             PG8_LDA(At, 0, 1); PG8_STAGE(PG8_SB(0, 0), b2, voffB); PG8_STAGE(PG8_SB(0, 1), b2 + hstep, voffB); PG8_STAGE(PG8_SA(0, 0), a2, voffA);
;             PG8_WAIT_V(8); PG8_WAIT_L(0); PG8_BAR; PG8_MMA(1, 0, At, B0); PG8_MMA(1, 1, At, B1); PG8_BAR; PG8_SCHED;
;             PG8_LDB(B0, 1, 0); PG8_LDB(B1, 1, 1); PG8_SCHED; PG8_LDA(At, 1, 0); PG8_STAGE(PG8_SA(0, 1), a2 + hstepA, voffA);
;             PG8_WAIT_V(8); PG8_WAIT_L(0); PG8_BAR; PG8_MMA(0, 0, At, B0); PG8_MMA(0, 1, At, B1); PG8_BAR; PG8_SCHED;
;             PG8_LDA(At, 1, 1); PG8_STAGE(PG8_SB(1, 0), b3, voffB); PG8_STAGE(PG8_SB(1, 1), b3 + hstep, voffB); PG8_STAGE(PG8_SA(1, 0), a3, voffA);
;             PG8_WAIT_V(8); PG8_WAIT_L(0); PG8_BAR; PG8_MMA(1, 0, At, B0); PG8_MMA(1, 1, At, B1); PG8_BAR; PG8_SCHED;
.LBB0_433:
	s_ashr_i32 s41, s40, 31
	s_lshl_b64 s[42:43], s[40:41], 19
	s_add_u32 s42, s20, s42
	s_addc_u32 s43, s21, s43
	s_and_b64 s[44:45], s[36:37], exec
	s_cselect_b32 s41, s43, s39
	s_cselect_b32 s54, s42, s38
	s_ashr_i32 s27, s26, 31
	s_lshl_b64 s[44:45], s[26:27], 19
	s_add_u32 s44, s3, s44
	s_addc_u32 s45, s6, s45
	s_and_b64 s[46:47], s[36:37], exec
	s_cselect_b32 s27, s45, s5
	s_cselect_b32 s55, s44, s4
	s_add_u32 s56, s4, 0x100
	s_addc_u32 s57, s5, 0
	s_add_u32 s4, s38, 0x40080
	s_addc_u32 s5, s39, 0
	s_mov_b32 s58, -2
	s_add_u32 s38, s4, 0xfffc0080
	s_addc_u32 s39, s5, -1
	s_add_i32 s59, 0, 0x10000
	s_cmp_eq_u32 s58, 12
	s_cselect_b32 s47, s41, s39
	s_cselect_b32 s46, s54, s38
	s_cselect_b32 s39, s27, s57
	s_cselect_b32 s38, s55, s56
	s_add_i32 s62, 0, 0x14000
	s_add_i32 m0, s2, 0xc000
	v_lshl_add_u64 v[166:167], s[4:5], 0, v[136:137]
	global_load_lds_dwordx4 v[166:167], off
	v_lshl_add_u64 v[166:167], s[4:5], 0, v[134:135]
	s_add_i32 m0, s2, 0xe000
	s_nop 0
	global_load_lds_dwordx4 v[166:167], off
	s_waitcnt vmcnt(8)
	s_waitcnt lgkmcnt(0)
	s_barrier
	s_setprio 1
	v_mfma_f32_16x16x32_bf16 v[124:127], v[138:141], v[196:199], 0
	v_mfma_f32_16x16x32_bf16 v[120:123], v[150:153], v[196:199], 0
	v_mfma_f32_16x16x32_bf16 v[108:111], v[138:141], v[204:207], 0
	v_mfma_f32_16x16x32_bf16 v[104:107], v[150:153], v[204:207], 0
	v_mfma_f32_16x16x32_bf16 v[92:95], v[138:141], v[212:215], 0
	v_mfma_f32_16x16x32_bf16 v[88:91], v[150:153], v[212:215], 0
	v_mfma_f32_16x16x32_bf16 v[76:79], v[138:141], v[220:223], 0
	v_mfma_f32_16x16x32_bf16 v[72:75], v[150:153], v[220:223], 0
	v_mfma_f32_16x16x32_bf16 v[124:127], v[146:149], v[200:203], v[124:127]
	v_mfma_f32_16x16x32_bf16 v[120:123], v[154:157], v[200:203], v[120:123]
	v_mfma_f32_16x16x32_bf16 v[108:111], v[146:149], v[208:211], v[108:111]
	v_mfma_f32_16x16x32_bf16 v[104:107], v[154:157], v[208:211], v[104:107]
	v_mfma_f32_16x16x32_bf16 v[92:95], v[146:149], v[216:219], v[92:95]
	v_mfma_f32_16x16x32_bf16 v[88:91], v[154:157], v[216:219], v[88:91]
	v_mfma_f32_16x16x32_bf16 v[76:79], v[146:149], v[234:237], v[76:79]
	v_mfma_f32_16x16x32_bf16 v[72:75], v[154:157], v[234:237], v[72:75]
	s_setprio 0
	s_setprio 1
	v_mfma_f32_16x16x32_bf16 v[116:119], v[158:161], v[196:199], 0
	v_mfma_f32_16x16x32_bf16 v[112:115], v[188:191], v[196:199], 0
	v_mfma_f32_16x16x32_bf16 v[100:103], v[158:161], v[204:207], 0
	v_mfma_f32_16x16x32_bf16 v[96:99], v[188:191], v[204:207], 0
	v_mfma_f32_16x16x32_bf16 v[84:87], v[158:161], v[212:215], 0
	v_mfma_f32_16x16x32_bf16 v[80:83], v[188:191], v[212:215], 0
	v_mfma_f32_16x16x32_bf16 v[68:71], v[158:161], v[220:223], 0
	v_mfma_f32_16x16x32_bf16 v[64:67], v[188:191], v[220:223], 0
	v_mfma_f32_16x16x32_bf16 v[116:119], v[162:165], v[200:203], v[116:119]
	v_mfma_f32_16x16x32_bf16 v[112:115], v[192:195], v[200:203], v[112:115]
	v_mfma_f32_16x16x32_bf16 v[100:103], v[162:165], v[208:211], v[100:103]
	v_mfma_f32_16x16x32_bf16 v[96:99], v[192:195], v[208:211], v[96:99]
	v_mfma_f32_16x16x32_bf16 v[84:87], v[162:165], v[216:219], v[84:87]
	s_add_i32 s59, s59, s7
	v_mfma_f32_16x16x32_bf16 v[80:83], v[192:195], v[216:219], v[80:83]
	v_lshl_add_u64 v[166:167], s[38:39], 0, v[168:169]
	v_mfma_f32_16x16x32_bf16 v[68:71], v[162:165], v[234:237], v[68:71]
	s_mov_b32 m0, s59
	v_mfma_f32_16x16x32_bf16 v[64:67], v[192:195], v[234:237], v[64:67]
	s_setprio 0
	s_barrier
	ds_read_b128 v[196:199], v145 offset:16384
	ds_read_b128 v[200:203], v145 offset:17408
	ds_read_b128 v[204:207], v145 offset:18432
	ds_read_b128 v[208:211], v145 offset:19456
	ds_read_b128 v[212:215], v145 offset:20480
	ds_read_b128 v[216:219], v145 offset:21504
	ds_read_b128 v[220:223], v145 offset:22528
	ds_read_b128 v[234:237], v145 offset:23552
	global_load_lds_dwordx4 v[166:167], off
	s_add_i32 m0, s59, 0x2000
	s_add_u32 s60, s38, 0x40000
	v_lshl_add_u64 v[170:171], s[38:39], 0, v[128:129]
	s_addc_u32 s61, s39, 0
	s_add_i32 s59, s62, s7
	global_load_lds_dwordx4 v[170:171], off
	v_lshl_add_u64 v[172:173], s[60:61], 0, v[168:169]
	s_mov_b32 m0, s59
	v_lshl_add_u64 v[224:225], s[46:47], 0, v[130:131]
	global_load_lds_dwordx4 v[172:173], off
	v_lshl_add_u64 v[172:173], s[60:61], 0, v[128:129]
	s_add_i32 m0, s59, 0x2000
	s_nop 0
	global_load_lds_dwordx4 v[172:173], off
	v_lshl_add_u64 v[172:173], s[46:47], 0, v[132:133]
	s_mov_b32 m0, s2
	s_nop 0
	global_load_lds_dwordx4 v[172:173], off
	s_mov_b32 m0, s34
	s_nop 0
	global_load_lds_dwordx4 v[224:225], off
	s_waitcnt vmcnt(8)
	s_waitcnt lgkmcnt(0)
	s_barrier
	s_setprio 1
	v_mfma_f32_16x16x32_bf16 v[60:63], v[138:141], v[196:199], 0
	v_mfma_f32_16x16x32_bf16 v[56:59], v[150:153], v[196:199], 0
	v_mfma_f32_16x16x32_bf16 v[44:47], v[138:141], v[204:207], 0
	v_mfma_f32_16x16x32_bf16 v[40:43], v[150:153], v[204:207], 0
	v_mfma_f32_16x16x32_bf16 v[28:31], v[138:141], v[212:215], 0
	v_mfma_f32_16x16x32_bf16 v[24:27], v[150:153], v[212:215], 0
	v_mfma_f32_16x16x32_bf16 v[12:15], v[138:141], v[220:223], 0
	v_mfma_f32_16x16x32_bf16 v[8:11], v[150:153], v[220:223], 0
	v_mfma_f32_16x16x32_bf16 v[60:63], v[146:149], v[200:203], v[60:63]
	v_mfma_f32_16x16x32_bf16 v[56:59], v[154:157], v[200:203], v[56:59]
	v_mfma_f32_16x16x32_bf16 v[44:47], v[146:149], v[208:211], v[44:47]
	v_mfma_f32_16x16x32_bf16 v[40:43], v[154:157], v[208:211], v[40:43]
	v_mfma_f32_16x16x32_bf16 v[28:31], v[146:149], v[216:219], v[28:31]
	v_mfma_f32_16x16x32_bf16 v[24:27], v[154:157], v[216:219], v[24:27]
	v_mfma_f32_16x16x32_bf16 v[12:15], v[146:149], v[234:237], v[12:15]
	v_mfma_f32_16x16x32_bf16 v[8:11], v[154:157], v[234:237], v[8:11]
	s_setprio 0
	s_setprio 1
	v_mfma_f32_16x16x32_bf16 v[52:55], v[158:161], v[196:199], 0
	v_mfma_f32_16x16x32_bf16 v[48:51], v[188:191], v[196:199], 0
	v_mfma_f32_16x16x32_bf16 v[36:39], v[158:161], v[204:207], 0
	v_mfma_f32_16x16x32_bf16 v[32:35], v[188:191], v[204:207], 0
	v_mfma_f32_16x16x32_bf16 v[20:23], v[158:161], v[212:215], 0
	v_mfma_f32_16x16x32_bf16 v[16:19], v[188:191], v[212:215], 0
	v_mfma_f32_16x16x32_bf16 v[4:7], v[158:161], v[220:223], 0
	v_mfma_f32_16x16x32_bf16 v[0:3], v[188:191], v[220:223], 0
	v_mfma_f32_16x16x32_bf16 v[52:55], v[162:165], v[200:203], v[52:55]
	v_mfma_f32_16x16x32_bf16 v[48:51], v[192:195], v[200:203], v[48:51]
	v_mfma_f32_16x16x32_bf16 v[36:39], v[162:165], v[208:211], v[36:39]
	v_mfma_f32_16x16x32_bf16 v[32:35], v[192:195], v[208:211], v[32:35]
	s_add_i32 s59, 0, 0x18000
	v_mfma_f32_16x16x32_bf16 v[20:23], v[162:165], v[216:219], v[20:23]
	s_add_i32 s60, 0, 0x1c000
	v_mfma_f32_16x16x32_bf16 v[16:19], v[192:195], v[216:219], v[16:19]
	v_add_u32_e32 v240, s59, v143
	v_mfma_f32_16x16x32_bf16 v[4:7], v[162:165], v[234:237], v[4:7]
	v_add_u32_e32 v178, s60, v143
	v_mfma_f32_16x16x32_bf16 v[0:3], v[192:195], v[234:237], v[0:3]
	s_setprio 0
	s_barrier
; #define PG8_STAGE(bufoff, gbase, voff) do { _Pragma("unroll") for (int _i = 0; _i < 2; ++_i) \
;         __builtin_amdgcn_global_load_lds((const unsigned*)((const char*)(gbase) + (voff)[_i]), (PG8_LAS unsigned*)(lds + (bufoff) + ldsw + _i * 8192), 16, 0, 0); } while (0)
; #define PG8_LDA(dst, b, h) do { _Pragma("unroll") for (int m = 0; m < 4; ++m) _Pragma("unroll") for (int k = 0; k < 2; ++k) dst[m][k] = *(const PG8_LAS bf16x8*)(lds + PG8_SA(b, h) + aoff + m * 2048 + k * 1024); } while (0)
; #define PG8_LDB(dst, b, h) do { _Pragma("unroll") for (int n = 0; n < 2; ++n) _Pragma("unroll") for (int k = 0; k < 2; ++k) dst[n][k] = *(const PG8_LAS bf16x8*)(lds + PG8_SB(b, h) + boff + n * 2048 + k * 1024); } while (0)
; #define PG8_MMA(ai, bj, At, Bt) do { __builtin_amdgcn_s_setprio(1); _Pragma("unroll") for (int m = 0; m < 4; ++m) _Pragma("unroll") for (int n = 0; n < 2; ++n) _Pragma("unroll") for (int k = 0; k < 2; ++k) \
;         acc[ai][bj][m][n] = __builtin_amdgcn_mfma_f32_16x16x32_bf16(Bt[n][k], At[m][k], acc[ai][bj][m][n], 0, 0, 0); __builtin_amdgcn_s_setprio(0); } while (0)
; #define PG8_WAIT_V(n) asm volatile("s_waitcnt vmcnt(" #n ")" ::: "memory")
; template <class Epi, class Sched, bool ALIGN_EPI = false, bool SP2 = false>
; __device__ __forceinline__ void gemm_phase(PG8_LAS unsigned char* lds, const Gemm g, const Sched& S, const Epi& E) {
;     ...
;             PG8_LDB(B0, 0, 0); PG8_LDB(B1, 0, 1); PG8_SCHED; PG8_LDA(At, 0, 0); PG8_STAGE(PG8_SA(1, 1), a1 + hstepA, voffA);
;             PG8_WAIT_V(8); PG8_WAIT_L(0); PG8_BAR; PG8_MMA(0, 0, At, B0); PG8_MMA(0, 1, At, B1); PG8_BAR; PG8_SCHED;
;             PG8_LDA(At, 0, 1); PG8_STAGE(PG8_SB(0, 0), b2, voffB); PG8_STAGE(PG8_SB(0, 1), b2 + hstep, voffB); PG8_STAGE(PG8_SA(0, 0), a2, voffA);
;             PG8_WAIT_V(8); PG8_WAIT_L(0); PG8_BAR; PG8_MMA(1, 0, At, B0); PG8_MMA(1, 1, At, B1); PG8_BAR; PG8_SCHED;
;             PG8_LDB(B0, 1, 0); PG8_LDB(B1, 1, 1); PG8_SCHED; PG8_LDA(At, 1, 0); PG8_STAGE(PG8_SA(0, 1), a2 + hstepA, voffA);
;             PG8_WAIT_V(8); PG8_WAIT_L(0); PG8_BAR; PG8_MMA(0, 0, At, B0); PG8_MMA(0, 1, At, B1); PG8_BAR; PG8_SCHED;
;             PG8_LDA(At, 1, 1); PG8_STAGE(PG8_SB(1, 0), b3, voffB); PG8_STAGE(PG8_SB(1, 1), b3 + hstep, voffB); PG8_STAGE(PG8_SA(1, 0), a3, voffA);
;             PG8_WAIT_V(8); PG8_WAIT_L(0); PG8_BAR; PG8_MMA(1, 0, At, B0); PG8_MMA(1, 1, At, B1); PG8_BAR; PG8_SCHED;
	ds_read_b128 v[138:141], v240
	ds_read_b128 v[146:149], v240 offset:1024
	ds_read_b128 v[150:153], v240 offset:2048
	ds_read_b128 v[154:157], v240 offset:3072
	ds_read_b128 v[158:161], v178
	ds_read_b128 v[162:165], v178 offset:1024
	ds_read_b128 v[188:191], v178 offset:2048
	ds_read_b128 v[192:195], v178 offset:3072
	ds_read_b128 v[196:199], v145 offset:32768
	ds_read_b128 v[200:203], v145 offset:33792
	ds_read_b128 v[204:207], v145 offset:34816
	ds_read_b128 v[208:211], v145 offset:35840
	ds_read_b128 v[212:215], v145 offset:36864
	ds_read_b128 v[216:219], v145 offset:37888
	ds_read_b128 v[220:223], v145 offset:38912
	ds_read_b128 v[234:237], v145 offset:39936
	s_add_u32 s46, s46, 0x40000
	s_addc_u32 s47, s47, 0
	s_mov_b32 m0, s35
	v_lshl_add_u64 v[238:239], s[46:47], 0, v[132:133]
	global_load_lds_dwordx4 v[238:239], off
	v_lshl_add_u64 v[238:239], s[46:47], 0, v[130:131]
	s_mov_b32 m0, s48
	s_nop 0
	global_load_lds_dwordx4 v[238:239], off
	s_waitcnt vmcnt(8)
	s_waitcnt lgkmcnt(0)
	s_barrier
	s_setprio 1
	v_mfma_f32_16x16x32_bf16 v[124:127], v[138:141], v[196:199], v[124:127]
	v_mfma_f32_16x16x32_bf16 v[120:123], v[150:153], v[196:199], v[120:123]
	v_mfma_f32_16x16x32_bf16 v[108:111], v[138:141], v[204:207], v[108:111]
	v_mfma_f32_16x16x32_bf16 v[104:107], v[150:153], v[204:207], v[104:107]
	v_mfma_f32_16x16x32_bf16 v[92:95], v[138:141], v[212:215], v[92:95]
	v_mfma_f32_16x16x32_bf16 v[88:91], v[150:153], v[212:215], v[88:91]
	v_mfma_f32_16x16x32_bf16 v[76:79], v[138:141], v[220:223], v[76:79]
	v_mfma_f32_16x16x32_bf16 v[72:75], v[150:153], v[220:223], v[72:75]
	v_mfma_f32_16x16x32_bf16 v[124:127], v[146:149], v[200:203], v[124:127]
	v_mfma_f32_16x16x32_bf16 v[120:123], v[154:157], v[200:203], v[120:123]
	v_mfma_f32_16x16x32_bf16 v[108:111], v[146:149], v[208:211], v[108:111]
	v_mfma_f32_16x16x32_bf16 v[104:107], v[154:157], v[208:211], v[104:107]
	v_mfma_f32_16x16x32_bf16 v[92:95], v[146:149], v[216:219], v[92:95]
	v_mfma_f32_16x16x32_bf16 v[88:91], v[154:157], v[216:219], v[88:91]
	v_mfma_f32_16x16x32_bf16 v[76:79], v[146:149], v[234:237], v[76:79]
	v_mfma_f32_16x16x32_bf16 v[72:75], v[154:157], v[234:237], v[72:75]
	s_setprio 0
	s_setprio 1
	v_mfma_f32_16x16x32_bf16 v[116:119], v[158:161], v[196:199], v[116:119]
	v_mfma_f32_16x16x32_bf16 v[112:115], v[188:191], v[196:199], v[112:115]
	v_mfma_f32_16x16x32_bf16 v[100:103], v[158:161], v[204:207], v[100:103]
	v_mfma_f32_16x16x32_bf16 v[96:99], v[188:191], v[204:207], v[96:99]
	v_mfma_f32_16x16x32_bf16 v[84:87], v[158:161], v[212:215], v[84:87]
	v_mfma_f32_16x16x32_bf16 v[80:83], v[188:191], v[212:215], v[80:83]
	v_mfma_f32_16x16x32_bf16 v[68:71], v[158:161], v[220:223], v[68:71]
	v_mfma_f32_16x16x32_bf16 v[64:67], v[188:191], v[220:223], v[64:67]
	v_mfma_f32_16x16x32_bf16 v[116:119], v[162:165], v[200:203], v[116:119]
	v_mfma_f32_16x16x32_bf16 v[112:115], v[192:195], v[200:203], v[112:115]
	v_mfma_f32_16x16x32_bf16 v[100:103], v[162:165], v[208:211], v[100:103]
	v_mfma_f32_16x16x32_bf16 v[96:99], v[192:195], v[208:211], v[96:99]
	v_mfma_f32_16x16x32_bf16 v[84:87], v[162:165], v[216:219], v[84:87]
	s_add_i32 s46, s59, s7
	v_mfma_f32_16x16x32_bf16 v[80:83], v[192:195], v[216:219], v[80:83]
	v_lshl_add_u64 v[166:167], v[166:167], 0, s[30:31]
	v_mfma_f32_16x16x32_bf16 v[68:71], v[162:165], v[234:237], v[68:71]
	s_mov_b32 m0, s46
	v_mfma_f32_16x16x32_bf16 v[64:67], v[192:195], v[234:237], v[64:67]
	s_setprio 0
	s_barrier
	ds_read_b128 v[196:199], v145 offset:49152
	ds_read_b128 v[200:203], v145 offset:50176
	ds_read_b128 v[204:207], v145 offset:51200
	ds_read_b128 v[208:211], v145 offset:52224
	ds_read_b128 v[212:215], v145 offset:53248
	ds_read_b128 v[216:219], v145 offset:54272
	ds_read_b128 v[220:223], v145 offset:55296
	ds_read_b128 v[234:237], v145 offset:56320
	global_load_lds_dwordx4 v[166:167], off
	s_add_i32 m0, s46, 0x2000
	s_add_u32 s38, s38, 0x40080
	v_lshl_add_u64 v[166:167], v[170:171], 0, s[30:31]
	s_addc_u32 s39, s39, 0
	s_add_i32 s46, s60, s7
	global_load_lds_dwordx4 v[166:167], off
	v_lshl_add_u64 v[166:167], s[38:39], 0, v[168:169]
	s_mov_b32 m0, s46
	s_nop 0
	global_load_lds_dwordx4 v[166:167], off
	v_lshl_add_u64 v[166:167], s[38:39], 0, v[128:129]
	s_add_i32 m0, s46, 0x2000
	s_nop 0
	global_load_lds_dwordx4 v[166:167], off
	v_lshl_add_u64 v[166:167], v[172:173], 0, s[30:31]
	s_mov_b32 m0, s49
	s_nop 0
	global_load_lds_dwordx4 v[166:167], off
	v_lshl_add_u64 v[166:167], v[224:225], 0, s[30:31]
	s_mov_b32 m0, s50
	s_nop 0
	global_load_lds_dwordx4 v[166:167], off
	s_waitcnt vmcnt(8)
	s_waitcnt lgkmcnt(0)
	s_barrier
; #define PG8_STAGE(bufoff, gbase, voff) do { _Pragma("unroll") for (int _i = 0; _i < 2; ++_i) \
;         __builtin_amdgcn_global_load_lds((const unsigned*)((const char*)(gbase) + (voff)[_i]), (PG8_LAS unsigned*)(lds + (bufoff) + ldsw + _i * 8192), 16, 0, 0); } while (0)
; #define PG8_LDA(dst, b, h) do { _Pragma("unroll") for (int m = 0; m < 4; ++m) _Pragma("unroll") for (int k = 0; k < 2; ++k) dst[m][k] = *(const PG8_LAS bf16x8*)(lds + PG8_SA(b, h) + aoff + m * 2048 + k * 1024); } while (0)
; #define PG8_LDB(dst, b, h) do { _Pragma("unroll") for (int n = 0; n < 2; ++n) _Pragma("unroll") for (int k = 0; k < 2; ++k) dst[n][k] = *(const PG8_LAS bf16x8*)(lds + PG8_SB(b, h) + boff + n * 2048 + k * 1024); } while (0)
; #define PG8_MMA(ai, bj, At, Bt) do { __builtin_amdgcn_s_setprio(1); _Pragma("unroll") for (int m = 0; m < 4; ++m) _Pragma("unroll") for (int n = 0; n < 2; ++n) _Pragma("unroll") for (int k = 0; k < 2; ++k) \
;         acc[ai][bj][m][n] = __builtin_amdgcn_mfma_f32_16x16x32_bf16(Bt[n][k], At[m][k], acc[ai][bj][m][n], 0, 0, 0); __builtin_amdgcn_s_setprio(0); } while (0)
; #define PG8_WAIT_V(n) asm volatile("s_waitcnt vmcnt(" #n ")" ::: "memory")
; template <class Epi, class Sched, bool ALIGN_EPI = false, bool SP2 = false>
; __device__ __forceinline__ void gemm_phase(PG8_LAS unsigned char* lds, const Gemm g, const Sched& S, const Epi& E) {
;     ...
;             PG8_LDB(B0, 0, 0); PG8_LDB(B1, 0, 1); PG8_SCHED; PG8_LDA(At, 0, 0); PG8_STAGE(PG8_SA(1, 1), a1 + hstepA, voffA);
;             PG8_WAIT_V(8); PG8_WAIT_L(0); PG8_BAR; PG8_MMA(0, 0, At, B0); PG8_MMA(0, 1, At, B1); PG8_BAR; PG8_SCHED;
;             PG8_LDA(At, 0, 1); PG8_STAGE(PG8_SB(0, 0), b2, voffB); PG8_STAGE(PG8_SB(0, 1), b2 + hstep, voffB); PG8_STAGE(PG8_SA(0, 0), a2, voffA);
;             PG8_WAIT_V(8); PG8_WAIT_L(0); PG8_BAR; PG8_MMA(1, 0, At, B0); PG8_MMA(1, 1, At, B1); PG8_BAR; PG8_SCHED;
;             PG8_LDB(B0, 1, 0); PG8_LDB(B1, 1, 1); PG8_SCHED; PG8_LDA(At, 1, 0); PG8_STAGE(PG8_SA(0, 1), a2 + hstepA, voffA);
;             PG8_WAIT_V(8); PG8_WAIT_L(0); PG8_BAR; PG8_MMA(0, 0, At, B0); PG8_MMA(0, 1, At, B1); PG8_BAR; PG8_SCHED;
;             PG8_LDA(At, 1, 1); PG8_STAGE(PG8_SB(1, 0), b3, voffB); PG8_STAGE(PG8_SB(1, 1), b3 + hstep, voffB); PG8_STAGE(PG8_SA(1, 0), a3, voffA);
;             PG8_WAIT_V(8); PG8_WAIT_L(0); PG8_BAR; PG8_MMA(1, 0, At, B0); PG8_MMA(1, 1, At, B1); PG8_BAR; PG8_SCHED;
	s_setprio 1
	v_mfma_f32_16x16x32_bf16 v[60:63], v[138:141], v[196:199], v[60:63]
	v_mfma_f32_16x16x32_bf16 v[56:59], v[150:153], v[196:199], v[56:59]
	v_mfma_f32_16x16x32_bf16 v[44:47], v[138:141], v[204:207], v[44:47]
	v_mfma_f32_16x16x32_bf16 v[40:43], v[150:153], v[204:207], v[40:43]
	v_mfma_f32_16x16x32_bf16 v[28:31], v[138:141], v[212:215], v[28:31]
	v_mfma_f32_16x16x32_bf16 v[24:27], v[150:153], v[212:215], v[24:27]
	v_mfma_f32_16x16x32_bf16 v[12:15], v[138:141], v[220:223], v[12:15]
	v_mfma_f32_16x16x32_bf16 v[8:11], v[150:153], v[220:223], v[8:11]
	v_mfma_f32_16x16x32_bf16 v[60:63], v[146:149], v[200:203], v[60:63]
	v_mfma_f32_16x16x32_bf16 v[56:59], v[154:157], v[200:203], v[56:59]
	v_mfma_f32_16x16x32_bf16 v[44:47], v[146:149], v[208:211], v[44:47]
	v_mfma_f32_16x16x32_bf16 v[40:43], v[154:157], v[208:211], v[40:43]
	v_mfma_f32_16x16x32_bf16 v[28:31], v[146:149], v[216:219], v[28:31]
	v_mfma_f32_16x16x32_bf16 v[24:27], v[154:157], v[216:219], v[24:27]
	v_mfma_f32_16x16x32_bf16 v[12:15], v[146:149], v[234:237], v[12:15]
	v_mfma_f32_16x16x32_bf16 v[8:11], v[154:157], v[234:237], v[8:11]
	s_add_i32 s58, s58, 2
	s_setprio 0
	s_setprio 1
	v_mfma_f32_16x16x32_bf16 v[52:55], v[158:161], v[196:199], v[52:55]
	s_add_u32 s56, s56, 0x100
	v_mfma_f32_16x16x32_bf16 v[48:51], v[188:191], v[196:199], v[48:51]
	s_addc_u32 s57, s57, 0
	v_mfma_f32_16x16x32_bf16 v[36:39], v[158:161], v[204:207], v[36:39]
	s_add_u32 s4, s4, 0x100
	v_mfma_f32_16x16x32_bf16 v[32:35], v[188:191], v[204:207], v[32:35]
	s_addc_u32 s5, s5, 0
	v_mfma_f32_16x16x32_bf16 v[20:23], v[158:161], v[212:215], v[20:23]
	s_add_u32 s38, s4, 0xfffc0080
	v_mfma_f32_16x16x32_bf16 v[16:19], v[188:191], v[212:215], v[16:19]
	s_addc_u32 s39, s5, -1
	v_mfma_f32_16x16x32_bf16 v[4:7], v[158:161], v[220:223], v[4:7]
	s_add_i32 s59, 0, 0x10000
	v_mfma_f32_16x16x32_bf16 v[0:3], v[188:191], v[220:223], v[0:3]
	s_cmp_eq_u32 s58, 12
	v_mfma_f32_16x16x32_bf16 v[52:55], v[162:165], v[200:203], v[52:55]
	s_cselect_b32 s47, s41, s39
	v_mfma_f32_16x16x32_bf16 v[48:51], v[192:195], v[200:203], v[48:51]
	s_cselect_b32 s46, s54, s38
	v_mfma_f32_16x16x32_bf16 v[36:39], v[162:165], v[208:211], v[36:39]
	s_cselect_b32 s39, s27, s57
	v_mfma_f32_16x16x32_bf16 v[32:35], v[192:195], v[208:211], v[32:35]
	s_cselect_b32 s38, s55, s56
	v_mfma_f32_16x16x32_bf16 v[20:23], v[162:165], v[216:219], v[20:23]
	s_add_i32 s62, 0, 0x14000
	v_mfma_f32_16x16x32_bf16 v[16:19], v[192:195], v[216:219], v[16:19]
	v_add_u32_e32 v241, s59, v143
	v_mfma_f32_16x16x32_bf16 v[4:7], v[162:165], v[234:237], v[4:7]
	v_add_u32_e32 v166, s62, v143
	v_mfma_f32_16x16x32_bf16 v[0:3], v[192:195], v[234:237], v[0:3]
	s_setprio 0
	s_barrier
.LBB0_434:
	ds_read_b128 v[138:141], v241
	ds_read_b128 v[146:149], v241 offset:1024
	ds_read_b128 v[150:153], v241 offset:2048
	ds_read_b128 v[154:157], v241 offset:3072
	ds_read_b128 v[158:161], v166
	ds_read_b128 v[162:165], v166 offset:1024
	ds_read_b128 v[188:191], v166 offset:2048
	ds_read_b128 v[192:195], v166 offset:3072
	ds_read_b128 v[196:199], v145
	ds_read_b128 v[200:203], v145 offset:1024
	ds_read_b128 v[204:207], v145 offset:2048
	ds_read_b128 v[208:211], v145 offset:3072
	ds_read_b128 v[212:215], v145 offset:4096
	ds_read_b128 v[216:219], v145 offset:5120
	ds_read_b128 v[220:223], v145 offset:6144
	ds_read_b128 v[234:237], v145 offset:7168
	s_add_i32 m0, s2, 0xc000
	v_lshl_add_u64 v[166:167], s[4:5], 0, v[136:137]
	global_load_lds_dwordx4 v[166:167], off
	v_lshl_add_u64 v[166:167], s[4:5], 0, v[134:135]
	s_add_i32 m0, s2, 0xe000
	s_nop 0
	global_load_lds_dwordx4 v[166:167], off
	s_waitcnt vmcnt(8)
	s_waitcnt lgkmcnt(0)
	s_barrier
	s_setprio 1
	v_mfma_f32_16x16x32_bf16 v[124:127], v[138:141], v[196:199], v[124:127]
	v_mfma_f32_16x16x32_bf16 v[120:123], v[150:153], v[196:199], v[120:123]
	v_mfma_f32_16x16x32_bf16 v[108:111], v[138:141], v[204:207], v[108:111]
	v_mfma_f32_16x16x32_bf16 v[104:107], v[150:153], v[204:207], v[104:107]
	v_mfma_f32_16x16x32_bf16 v[92:95], v[138:141], v[212:215], v[92:95]
	v_mfma_f32_16x16x32_bf16 v[88:91], v[150:153], v[212:215], v[88:91]
	v_mfma_f32_16x16x32_bf16 v[76:79], v[138:141], v[220:223], v[76:79]
	v_mfma_f32_16x16x32_bf16 v[72:75], v[150:153], v[220:223], v[72:75]
	v_mfma_f32_16x16x32_bf16 v[124:127], v[146:149], v[200:203], v[124:127]
	v_mfma_f32_16x16x32_bf16 v[120:123], v[154:157], v[200:203], v[120:123]
	v_mfma_f32_16x16x32_bf16 v[108:111], v[146:149], v[208:211], v[108:111]
	v_mfma_f32_16x16x32_bf16 v[104:107], v[154:157], v[208:211], v[104:107]
	v_mfma_f32_16x16x32_bf16 v[92:95], v[146:149], v[216:219], v[92:95]
	v_mfma_f32_16x16x32_bf16 v[88:91], v[154:157], v[216:219], v[88:91]
	v_mfma_f32_16x16x32_bf16 v[76:79], v[146:149], v[234:237], v[76:79]
	v_mfma_f32_16x16x32_bf16 v[72:75], v[154:157], v[234:237], v[72:75]
	s_setprio 0
	s_setprio 1
	v_mfma_f32_16x16x32_bf16 v[116:119], v[158:161], v[196:199], v[116:119]
	v_mfma_f32_16x16x32_bf16 v[112:115], v[188:191], v[196:199], v[112:115]
	v_mfma_f32_16x16x32_bf16 v[100:103], v[158:161], v[204:207], v[100:103]
	v_mfma_f32_16x16x32_bf16 v[96:99], v[188:191], v[204:207], v[96:99]
	v_mfma_f32_16x16x32_bf16 v[84:87], v[158:161], v[212:215], v[84:87]
	v_mfma_f32_16x16x32_bf16 v[80:83], v[188:191], v[212:215], v[80:83]
	v_mfma_f32_16x16x32_bf16 v[68:71], v[158:161], v[220:223], v[68:71]
	v_mfma_f32_16x16x32_bf16 v[64:67], v[188:191], v[220:223], v[64:67]
	v_mfma_f32_16x16x32_bf16 v[116:119], v[162:165], v[200:203], v[116:119]
	v_mfma_f32_16x16x32_bf16 v[112:115], v[192:195], v[200:203], v[112:115]
	v_mfma_f32_16x16x32_bf16 v[100:103], v[162:165], v[208:211], v[100:103]
	v_mfma_f32_16x16x32_bf16 v[96:99], v[192:195], v[208:211], v[96:99]
	v_mfma_f32_16x16x32_bf16 v[84:87], v[162:165], v[216:219], v[84:87]
	s_add_i32 s59, s59, s7
	v_mfma_f32_16x16x32_bf16 v[80:83], v[192:195], v[216:219], v[80:83]
	v_lshl_add_u64 v[166:167], s[38:39], 0, v[168:169]
	v_mfma_f32_16x16x32_bf16 v[68:71], v[162:165], v[234:237], v[68:71]
	s_mov_b32 m0, s59
	v_mfma_f32_16x16x32_bf16 v[64:67], v[192:195], v[234:237], v[64:67]
	s_setprio 0
	s_barrier
; #define PG8_STAGE(bufoff, gbase, voff) do { _Pragma("unroll") for (int _i = 0; _i < 2; ++_i) \
;         __builtin_amdgcn_global_load_lds((const unsigned*)((const char*)(gbase) + (voff)[_i]), (PG8_LAS unsigned*)(lds + (bufoff) + ldsw + _i * 8192), 16, 0, 0); } while (0)
; #define PG8_LDA(dst, b, h) do { _Pragma("unroll") for (int m = 0; m < 4; ++m) _Pragma("unroll") for (int k = 0; k < 2; ++k) dst[m][k] = *(const PG8_LAS bf16x8*)(lds + PG8_SA(b, h) + aoff + m * 2048 + k * 1024); } while (0)
; #define PG8_LDB(dst, b, h) do { _Pragma("unroll") for (int n = 0; n < 2; ++n) _Pragma("unroll") for (int k = 0; k < 2; ++k) dst[n][k] = *(const PG8_LAS bf16x8*)(lds + PG8_SB(b, h) + boff + n * 2048 + k * 1024); } while (0)
; #define PG8_MMA(ai, bj, At, Bt) do { __builtin_amdgcn_s_setprio(1); _Pragma("unroll") for (int m = 0; m < 4; ++m) _Pragma("unroll") for (int n = 0; n < 2; ++n) _Pragma("unroll") for (int k = 0; k < 2; ++k) \
;         acc[ai][bj][m][n] = __builtin_amdgcn_mfma_f32_16x16x32_bf16(Bt[n][k], At[m][k], acc[ai][bj][m][n], 0, 0, 0); __builtin_amdgcn_s_setprio(0); } while (0)
; #define PG8_WAIT_V(n) asm volatile("s_waitcnt vmcnt(" #n ")" ::: "memory")
; template <class Epi, class Sched, bool ALIGN_EPI = false, bool SP2 = false>
; __device__ __forceinline__ void gemm_phase(PG8_LAS unsigned char* lds, const Gemm g, const Sched& S, const Epi& E) {
;     ...
;             PG8_LDB(B0, 0, 0); PG8_LDB(B1, 0, 1); PG8_SCHED; PG8_LDA(At, 0, 0); PG8_STAGE(PG8_SA(1, 1), a1 + hstepA, voffA);
;             PG8_WAIT_V(8); PG8_WAIT_L(0); PG8_BAR; PG8_MMA(0, 0, At, B0); PG8_MMA(0, 1, At, B1); PG8_BAR; PG8_SCHED;
;             PG8_LDA(At, 0, 1); PG8_STAGE(PG8_SB(0, 0), b2, voffB); PG8_STAGE(PG8_SB(0, 1), b2 + hstep, voffB); PG8_STAGE(PG8_SA(0, 0), a2, voffA);
;             PG8_WAIT_V(8); PG8_WAIT_L(0); PG8_BAR; PG8_MMA(1, 0, At, B0); PG8_MMA(1, 1, At, B1); PG8_BAR; PG8_SCHED;
;             PG8_LDB(B0, 1, 0); PG8_LDB(B1, 1, 1); PG8_SCHED; PG8_LDA(At, 1, 0); PG8_STAGE(PG8_SA(0, 1), a2 + hstepA, voffA);
;             PG8_WAIT_V(8); PG8_WAIT_L(0); PG8_BAR; PG8_MMA(0, 0, At, B0); PG8_MMA(0, 1, At, B1); PG8_BAR; PG8_SCHED;
;             PG8_LDA(At, 1, 1); PG8_STAGE(PG8_SB(1, 0), b3, voffB); PG8_STAGE(PG8_SB(1, 1), b3 + hstep, voffB); PG8_STAGE(PG8_SA(1, 0), a3, voffA);
;             PG8_WAIT_V(8); PG8_WAIT_L(0); PG8_BAR; PG8_MMA(1, 0, At, B0); PG8_MMA(1, 1, At, B1); PG8_BAR; PG8_SCHED;
	ds_read_b128 v[196:199], v145 offset:16384
	ds_read_b128 v[200:203], v145 offset:17408
	ds_read_b128 v[204:207], v145 offset:18432
	ds_read_b128 v[208:211], v145 offset:19456
	ds_read_b128 v[212:215], v145 offset:20480
	ds_read_b128 v[216:219], v145 offset:21504
	ds_read_b128 v[220:223], v145 offset:22528
	ds_read_b128 v[234:237], v145 offset:23552
	global_load_lds_dwordx4 v[166:167], off
	s_add_i32 m0, s59, 0x2000
	s_add_u32 s60, s38, 0x40000
	v_lshl_add_u64 v[170:171], s[38:39], 0, v[128:129]
	s_addc_u32 s61, s39, 0
	s_add_i32 s59, s62, s7
	global_load_lds_dwordx4 v[170:171], off
	v_lshl_add_u64 v[172:173], s[60:61], 0, v[168:169]
	s_mov_b32 m0, s59
	v_lshl_add_u64 v[224:225], s[46:47], 0, v[130:131]
	global_load_lds_dwordx4 v[172:173], off
	v_lshl_add_u64 v[172:173], s[60:61], 0, v[128:129]
	s_add_i32 m0, s59, 0x2000
	s_nop 0
	global_load_lds_dwordx4 v[172:173], off
	v_lshl_add_u64 v[172:173], s[46:47], 0, v[132:133]
	s_mov_b32 m0, s2
	s_nop 0
	global_load_lds_dwordx4 v[172:173], off
	s_mov_b32 m0, s34
	s_nop 0
	global_load_lds_dwordx4 v[224:225], off
	s_waitcnt vmcnt(8)
	s_waitcnt lgkmcnt(0)
	s_barrier
	s_setprio 1
	v_mfma_f32_16x16x32_bf16 v[60:63], v[138:141], v[196:199], v[60:63]
	v_mfma_f32_16x16x32_bf16 v[56:59], v[150:153], v[196:199], v[56:59]
	v_mfma_f32_16x16x32_bf16 v[44:47], v[138:141], v[204:207], v[44:47]
	v_mfma_f32_16x16x32_bf16 v[40:43], v[150:153], v[204:207], v[40:43]
	v_mfma_f32_16x16x32_bf16 v[28:31], v[138:141], v[212:215], v[28:31]
	v_mfma_f32_16x16x32_bf16 v[24:27], v[150:153], v[212:215], v[24:27]
	v_mfma_f32_16x16x32_bf16 v[12:15], v[138:141], v[220:223], v[12:15]
	v_mfma_f32_16x16x32_bf16 v[8:11], v[150:153], v[220:223], v[8:11]
	v_mfma_f32_16x16x32_bf16 v[60:63], v[146:149], v[200:203], v[60:63]
	v_mfma_f32_16x16x32_bf16 v[56:59], v[154:157], v[200:203], v[56:59]
	v_mfma_f32_16x16x32_bf16 v[44:47], v[146:149], v[208:211], v[44:47]
	v_mfma_f32_16x16x32_bf16 v[40:43], v[154:157], v[208:211], v[40:43]
	v_mfma_f32_16x16x32_bf16 v[28:31], v[146:149], v[216:219], v[28:31]
	v_mfma_f32_16x16x32_bf16 v[24:27], v[154:157], v[216:219], v[24:27]
	v_mfma_f32_16x16x32_bf16 v[12:15], v[146:149], v[234:237], v[12:15]
	v_mfma_f32_16x16x32_bf16 v[8:11], v[154:157], v[234:237], v[8:11]
	s_setprio 0
	s_setprio 1
	v_mfma_f32_16x16x32_bf16 v[52:55], v[158:161], v[196:199], v[52:55]
	v_mfma_f32_16x16x32_bf16 v[48:51], v[188:191], v[196:199], v[48:51]
	v_mfma_f32_16x16x32_bf16 v[36:39], v[158:161], v[204:207], v[36:39]
	v_mfma_f32_16x16x32_bf16 v[32:35], v[188:191], v[204:207], v[32:35]
	v_mfma_f32_16x16x32_bf16 v[20:23], v[158:161], v[212:215], v[20:23]
	v_mfma_f32_16x16x32_bf16 v[16:19], v[188:191], v[212:215], v[16:19]
	v_mfma_f32_16x16x32_bf16 v[4:7], v[158:161], v[220:223], v[4:7]
	v_mfma_f32_16x16x32_bf16 v[0:3], v[188:191], v[220:223], v[0:3]
	v_mfma_f32_16x16x32_bf16 v[52:55], v[162:165], v[200:203], v[52:55]
	v_mfma_f32_16x16x32_bf16 v[48:51], v[192:195], v[200:203], v[48:51]
	v_mfma_f32_16x16x32_bf16 v[36:39], v[162:165], v[208:211], v[36:39]
	v_mfma_f32_16x16x32_bf16 v[32:35], v[192:195], v[208:211], v[32:35]
	s_add_i32 s59, 0, 0x18000
	v_mfma_f32_16x16x32_bf16 v[20:23], v[162:165], v[216:219], v[20:23]
	s_add_i32 s60, 0, 0x1c000
	v_mfma_f32_16x16x32_bf16 v[16:19], v[192:195], v[216:219], v[16:19]
	v_add_u32_e32 v240, s59, v143
	v_mfma_f32_16x16x32_bf16 v[4:7], v[162:165], v[234:237], v[4:7]
	v_add_u32_e32 v178, s60, v143
	v_mfma_f32_16x16x32_bf16 v[0:3], v[192:195], v[234:237], v[0:3]
	s_setprio 0
	s_barrier
	ds_read_b128 v[138:141], v240
	ds_read_b128 v[146:149], v240 offset:1024
	ds_read_b128 v[150:153], v240 offset:2048
	ds_read_b128 v[154:157], v240 offset:3072
	ds_read_b128 v[158:161], v178
	ds_read_b128 v[162:165], v178 offset:1024
	ds_read_b128 v[188:191], v178 offset:2048
	ds_read_b128 v[192:195], v178 offset:3072
	ds_read_b128 v[196:199], v145 offset:32768
	ds_read_b128 v[200:203], v145 offset:33792
	ds_read_b128 v[204:207], v145 offset:34816
	ds_read_b128 v[208:211], v145 offset:35840
	ds_read_b128 v[212:215], v145 offset:36864
	ds_read_b128 v[216:219], v145 offset:37888
	ds_read_b128 v[220:223], v145 offset:38912
	ds_read_b128 v[234:237], v145 offset:39936
	s_add_u32 s46, s46, 0x40000
	s_addc_u32 s47, s47, 0
	s_mov_b32 m0, s35
	v_lshl_add_u64 v[238:239], s[46:47], 0, v[132:133]
	global_load_lds_dwordx4 v[238:239], off
	v_lshl_add_u64 v[238:239], s[46:47], 0, v[130:131]
	s_mov_b32 m0, s48
	s_nop 0
	global_load_lds_dwordx4 v[238:239], off
	s_waitcnt vmcnt(8)
	s_waitcnt lgkmcnt(0)
	s_barrier
; template <class Epi, class Sched, bool ALIGN_EPI = false, bool SP2 = false>
; __device__ __forceinline__ void gemm_phase(PG8_LAS unsigned char* lds, const Gemm g, const Sched& S, const Epi& E) {
;     ...
;             PG8_LDB(B0, 0, 0); PG8_LDB(B1, 0, 1); PG8_SCHED; PG8_LDA(At, 0, 0); PG8_STAGE(PG8_SA(1, 1), a1 + hstepA, voffA);
;             PG8_WAIT_V(8); PG8_WAIT_L(0); PG8_BAR; PG8_MMA(0, 0, At, B0); PG8_MMA(0, 1, At, B1); PG8_BAR; PG8_SCHED;
;             PG8_LDA(At, 0, 1); PG8_STAGE(PG8_SB(0, 0), b2, voffB); PG8_STAGE(PG8_SB(0, 1), b2 + hstep, voffB); PG8_STAGE(PG8_SA(0, 0), a2, voffA);
;             PG8_WAIT_V(8); PG8_WAIT_L(0); PG8_BAR; PG8_MMA(1, 0, At, B0); PG8_MMA(1, 1, At, B1); PG8_BAR; PG8_SCHED;
;             PG8_LDB(B0, 1, 0); PG8_LDB(B1, 1, 1); PG8_SCHED; PG8_LDA(At, 1, 0); PG8_STAGE(PG8_SA(0, 1), a2 + hstepA, voffA);
;             PG8_WAIT_V(8); PG8_WAIT_L(0); PG8_BAR; PG8_MMA(0, 0, At, B0); PG8_MMA(0, 1, At, B1); PG8_BAR; PG8_SCHED;
;             PG8_LDA(At, 1, 1); PG8_STAGE(PG8_SB(1, 0), b3, voffB); PG8_STAGE(PG8_SB(1, 1), b3 + hstep, voffB); PG8_STAGE(PG8_SA(1, 0), a3, voffA);
;             PG8_WAIT_V(8); PG8_WAIT_L(0); PG8_BAR; PG8_MMA(1, 0, At, B0); PG8_MMA(1, 1, At, B1); PG8_BAR; PG8_SCHED;
;             } else {
;             PG8_LDB(B0, 0, 0); PG8_SCHED; PG8_LDA(At, 0, 0); PG8_STAGE(PG8_SA(1, 1), a1 + hstepA, voffA);
;             PG8_WAIT_L(8); PG8_BAR; PG8_WAIT_L(0); PG8_MMA(0, 0, At, B0); PG8_BAR; PG8_SCHED;
;             PG8_LDB(B1, 0, 1); PG8_STAGE(PG8_SB(0, 0), b2, voffB);
;             PG8_BAR; PG8_WAIT_L(0); PG8_MMA(0, 1, At, B1); PG8_BAR;
;             PG8_LDA(At, 0, 1); PG8_STAGE(PG8_SA(0, 0), a2, voffA);
;             PG8_BAR; PG8_WAIT_L(0); PG8_MMA(1, 0, At, B0); PG8_BAR; PG8_SCHED;
;             PG8_STAGE(PG8_SB(0, 1), b2 + hstep, voffB);
;             PG8_WAIT_V(6); PG8_BAR; PG8_MMA(1, 1, At, B1); PG8_BAR;
;             PG8_LDB(B0, 1, 0); PG8_SCHED; PG8_LDA(At, 1, 0); PG8_STAGE(PG8_SA(0, 1), a2 + hstepA, voffA);
;             PG8_WAIT_L(8); PG8_BAR; PG8_WAIT_L(0); PG8_MMA(0, 0, At, B0); PG8_BAR; PG8_SCHED;
;             PG8_LDB(B1, 1, 1); PG8_STAGE(PG8_SB(1, 0), b3, voffB);
;             PG8_BAR; PG8_WAIT_L(0); PG8_MMA(0, 1, At, B1); PG8_BAR;
;             PG8_LDA(At, 1, 1); PG8_STAGE(PG8_SA(1, 0), a3, voffA);
;             PG8_BAR; PG8_WAIT_L(0); PG8_MMA(1, 0, At, B0); PG8_BAR; PG8_SCHED;
	s_setprio 1
	v_mfma_f32_16x16x32_bf16 v[124:127], v[138:141], v[196:199], v[124:127]
	v_mfma_f32_16x16x32_bf16 v[120:123], v[150:153], v[196:199], v[120:123]
	v_mfma_f32_16x16x32_bf16 v[108:111], v[138:141], v[204:207], v[108:111]
	v_mfma_f32_16x16x32_bf16 v[104:107], v[150:153], v[204:207], v[104:107]
	v_mfma_f32_16x16x32_bf16 v[92:95], v[138:141], v[212:215], v[92:95]
	v_mfma_f32_16x16x32_bf16 v[88:91], v[150:153], v[212:215], v[88:91]
	v_mfma_f32_16x16x32_bf16 v[76:79], v[138:141], v[220:223], v[76:79]
	v_mfma_f32_16x16x32_bf16 v[72:75], v[150:153], v[220:223], v[72:75]
	v_mfma_f32_16x16x32_bf16 v[124:127], v[146:149], v[200:203], v[124:127]
	v_mfma_f32_16x16x32_bf16 v[120:123], v[154:157], v[200:203], v[120:123]
	v_mfma_f32_16x16x32_bf16 v[108:111], v[146:149], v[208:211], v[108:111]
	v_mfma_f32_16x16x32_bf16 v[104:107], v[154:157], v[208:211], v[104:107]
	v_mfma_f32_16x16x32_bf16 v[92:95], v[146:149], v[216:219], v[92:95]
	v_mfma_f32_16x16x32_bf16 v[88:91], v[154:157], v[216:219], v[88:91]
	v_mfma_f32_16x16x32_bf16 v[76:79], v[146:149], v[234:237], v[76:79]
	v_mfma_f32_16x16x32_bf16 v[72:75], v[154:157], v[234:237], v[72:75]
	s_setprio 0
	s_setprio 1
	v_mfma_f32_16x16x32_bf16 v[116:119], v[158:161], v[196:199], v[116:119]
	v_mfma_f32_16x16x32_bf16 v[112:115], v[188:191], v[196:199], v[112:115]
	v_mfma_f32_16x16x32_bf16 v[100:103], v[158:161], v[204:207], v[100:103]
	v_mfma_f32_16x16x32_bf16 v[96:99], v[188:191], v[204:207], v[96:99]
	v_mfma_f32_16x16x32_bf16 v[84:87], v[158:161], v[212:215], v[84:87]
	v_mfma_f32_16x16x32_bf16 v[80:83], v[188:191], v[212:215], v[80:83]
	v_mfma_f32_16x16x32_bf16 v[68:71], v[158:161], v[220:223], v[68:71]
	v_mfma_f32_16x16x32_bf16 v[64:67], v[188:191], v[220:223], v[64:67]
	v_mfma_f32_16x16x32_bf16 v[116:119], v[162:165], v[200:203], v[116:119]
	v_mfma_f32_16x16x32_bf16 v[112:115], v[192:195], v[200:203], v[112:115]
	v_mfma_f32_16x16x32_bf16 v[100:103], v[162:165], v[208:211], v[100:103]
	v_mfma_f32_16x16x32_bf16 v[96:99], v[192:195], v[208:211], v[96:99]
	v_mfma_f32_16x16x32_bf16 v[84:87], v[162:165], v[216:219], v[84:87]
	s_add_i32 s46, s59, s7
	v_mfma_f32_16x16x32_bf16 v[80:83], v[192:195], v[216:219], v[80:83]
	v_lshl_add_u64 v[166:167], v[166:167], 0, s[30:31]
	v_mfma_f32_16x16x32_bf16 v[68:71], v[162:165], v[234:237], v[68:71]
	s_mov_b32 m0, s46
	v_mfma_f32_16x16x32_bf16 v[64:67], v[192:195], v[234:237], v[64:67]
	s_setprio 0
	s_barrier
	ds_read_b128 v[196:199], v145 offset:49152
	ds_read_b128 v[200:203], v145 offset:50176
	ds_read_b128 v[204:207], v145 offset:51200
	ds_read_b128 v[208:211], v145 offset:52224
	ds_read_b128 v[212:215], v145 offset:53248
	ds_read_b128 v[216:219], v145 offset:54272
	ds_read_b128 v[220:223], v145 offset:55296
	ds_read_b128 v[234:237], v145 offset:56320
	global_load_lds_dwordx4 v[166:167], off
	s_add_i32 m0, s46, 0x2000
	s_add_u32 s38, s38, 0x40080
	v_lshl_add_u64 v[166:167], v[170:171], 0, s[30:31]
	s_addc_u32 s39, s39, 0
	s_add_i32 s46, s60, s7
	global_load_lds_dwordx4 v[166:167], off
	v_lshl_add_u64 v[166:167], s[38:39], 0, v[168:169]
	s_mov_b32 m0, s46
	s_nop 0
	global_load_lds_dwordx4 v[166:167], off
	v_lshl_add_u64 v[166:167], s[38:39], 0, v[128:129]
	s_add_i32 m0, s46, 0x2000
	s_nop 0
	global_load_lds_dwordx4 v[166:167], off
	v_lshl_add_u64 v[166:167], v[172:173], 0, s[30:31]
	s_mov_b32 m0, s49
	s_nop 0
	global_load_lds_dwordx4 v[166:167], off
	v_lshl_add_u64 v[166:167], v[224:225], 0, s[30:31]
	s_mov_b32 m0, s50
	s_nop 0
	global_load_lds_dwordx4 v[166:167], off
	s_waitcnt vmcnt(8)
	s_waitcnt lgkmcnt(0)
	s_barrier
	s_setprio 1
	v_mfma_f32_16x16x32_bf16 v[60:63], v[138:141], v[196:199], v[60:63]
	v_mfma_f32_16x16x32_bf16 v[56:59], v[150:153], v[196:199], v[56:59]
	v_mfma_f32_16x16x32_bf16 v[44:47], v[138:141], v[204:207], v[44:47]
	v_mfma_f32_16x16x32_bf16 v[40:43], v[150:153], v[204:207], v[40:43]
	v_mfma_f32_16x16x32_bf16 v[28:31], v[138:141], v[212:215], v[28:31]
	v_mfma_f32_16x16x32_bf16 v[24:27], v[150:153], v[212:215], v[24:27]
	v_mfma_f32_16x16x32_bf16 v[12:15], v[138:141], v[220:223], v[12:15]
	v_mfma_f32_16x16x32_bf16 v[8:11], v[150:153], v[220:223], v[8:11]
	v_mfma_f32_16x16x32_bf16 v[60:63], v[146:149], v[200:203], v[60:63]
	v_mfma_f32_16x16x32_bf16 v[56:59], v[154:157], v[200:203], v[56:59]
	v_mfma_f32_16x16x32_bf16 v[44:47], v[146:149], v[208:211], v[44:47]
	v_mfma_f32_16x16x32_bf16 v[40:43], v[154:157], v[208:211], v[40:43]
	v_mfma_f32_16x16x32_bf16 v[28:31], v[146:149], v[216:219], v[28:31]
	v_mfma_f32_16x16x32_bf16 v[24:27], v[154:157], v[216:219], v[24:27]
	v_mfma_f32_16x16x32_bf16 v[12:15], v[146:149], v[234:237], v[12:15]
	s_add_i32 s58, s58, 2
	v_mfma_f32_16x16x32_bf16 v[8:11], v[154:157], v[234:237], v[8:11]
	s_add_u32 s56, s56, 0x100
	s_setprio 0
	s_setprio 1
	v_mfma_f32_16x16x32_bf16 v[52:55], v[158:161], v[196:199], v[52:55]
	s_addc_u32 s57, s57, 0
	v_mfma_f32_16x16x32_bf16 v[48:51], v[188:191], v[196:199], v[48:51]
	s_add_u32 s4, s4, 0x100
	v_mfma_f32_16x16x32_bf16 v[36:39], v[158:161], v[204:207], v[36:39]
	s_addc_u32 s5, s5, 0
	v_mfma_f32_16x16x32_bf16 v[32:35], v[188:191], v[204:207], v[32:35]
	s_add_u32 s38, s4, 0xfffc0080
	v_mfma_f32_16x16x32_bf16 v[20:23], v[158:161], v[212:215], v[20:23]
	s_addc_u32 s39, s5, -1
	v_mfma_f32_16x16x32_bf16 v[16:19], v[188:191], v[212:215], v[16:19]
	s_add_i32 s59, 0, 0x10000
	v_mfma_f32_16x16x32_bf16 v[4:7], v[158:161], v[220:223], v[4:7]
	s_cmp_eq_u32 s58, 12
	v_mfma_f32_16x16x32_bf16 v[0:3], v[188:191], v[220:223], v[0:3]
	s_cselect_b32 s47, s41, s39
	v_mfma_f32_16x16x32_bf16 v[52:55], v[162:165], v[200:203], v[52:55]
	s_cselect_b32 s46, s54, s38
	v_mfma_f32_16x16x32_bf16 v[48:51], v[192:195], v[200:203], v[48:51]
	s_cselect_b32 s39, s27, s57
	v_mfma_f32_16x16x32_bf16 v[36:39], v[162:165], v[208:211], v[36:39]
	s_cselect_b32 s38, s55, s56
	v_mfma_f32_16x16x32_bf16 v[32:35], v[192:195], v[208:211], v[32:35]
	s_add_i32 s62, 0, 0x14000
	v_mfma_f32_16x16x32_bf16 v[20:23], v[162:165], v[216:219], v[20:23]
	v_add_u32_e32 v241, s59, v143
	v_mfma_f32_16x16x32_bf16 v[16:19], v[192:195], v[216:219], v[16:19]
	v_add_u32_e32 v166, s62, v143
	v_mfma_f32_16x16x32_bf16 v[4:7], v[162:165], v[234:237], v[4:7]
	s_cmp_gt_u32 s58, 13
	v_mfma_f32_16x16x32_bf16 v[0:3], v[192:195], v[234:237], v[0:3]
	s_setprio 0
	s_barrier
	s_cbranch_scc0 .LBB0_434
	s_and_b64 vcc, exec, s[24:25]
	s_cbranch_vccz .LBB0_437
	s_barrier

; #define PG8_STAGE(bufoff, gbase, voff) do { _Pragma("unroll") for (int _i = 0; _i < 2; ++_i) \
;         __builtin_amdgcn_global_load_lds((const unsigned*)((const char*)(gbase) + (voff)[_i]), (PG8_LAS unsigned*)(lds + (bufoff) + ldsw + _i * 8192), 16, 0, 0); } while (0)
; #define PG8_LDA(dst, b, h) do { _Pragma("unroll") for (int m = 0; m < 4; ++m) _Pragma("unroll") for (int k = 0; k < 2; ++k) dst[m][k] = *(const PG8_LAS bf16x8*)(lds + PG8_SA(b, h) + aoff + m * 2048 + k * 1024); } while (0)
; template <class Epi, class Sched, bool ALIGN_EPI = false, bool SP2 = false>
; __device__ __forceinline__ void gemm_phase(PG8_LAS unsigned char* lds, const Gemm g, const Sched& S, const Epi& E) {
;     ...
;         const bool has_next = S.next(ui + 1, nxt);
;         const char* nA = has_next ? (const char*)g.A + (size_t)nxt.pm * tstepA : cA; const char* nB = has_next ? (const char*)g.Bt + (size_t)nxt.pn * tstep : cB;
;         for (int t = 0; t < nt; t += 2) {
;             const bool last = (t == nt - 2);
;             const char* a1 = cA + (size_t)(t + 1) * kstepA;
;             const char* a2 = last ? nA : cA + (size_t)(t + 2) * kstepA; const char* b2 = last ? nB : cB + (size_t)(t + 2) * kstep;
;             const char* a3 = a2 + kstepA; const char* b3 = b2 + kstep;
;             if (last && has_next) S.a_ready(nxt);
;             if constexpr (SP2) {
;             PG8_LDB(B0, 0, 0); PG8_LDB(B1, 0, 1); PG8_SCHED; PG8_LDA(At, 0, 0); PG8_STAGE(PG8_SA(1, 1), a1 + hstepA, voffA);
;             PG8_WAIT_V(8); PG8_WAIT_L(0); PG8_BAR; PG8_MMA(0, 0, At, B0); PG8_MMA(0, 1, At, B1); PG8_BAR; PG8_SCHED;
;             PG8_LDA(At, 0, 1); PG8_STAGE(PG8_SB(0, 0), b2, voffB); PG8_STAGE(PG8_SB(0, 1), b2 + hstep, voffB); PG8_STAGE(PG8_SA(0, 0), a2, voffA);
;             PG8_WAIT_V(8); PG8_WAIT_L(0); PG8_BAR; PG8_MMA(1, 0, At, B0); PG8_MMA(1, 1, At, B1); PG8_BAR; PG8_SCHED;
;             PG8_LDB(B0, 1, 0); PG8_LDB(B1, 1, 1); PG8_SCHED; PG8_LDA(At, 1, 0); PG8_STAGE(PG8_SA(0, 1), a2 + hstepA, voffA);
;             PG8_WAIT_V(8); PG8_WAIT_L(0); PG8_BAR; PG8_MMA(0, 0, At, B0); PG8_MMA(0, 1, At, B1); PG8_BAR; PG8_SCHED;
;             PG8_LDA(At, 1, 1); PG8_STAGE(PG8_SB(1, 0), b3, voffB); PG8_STAGE(PG8_SB(1, 1), b3 + hstep, voffB); PG8_STAGE(PG8_SA(1, 0), a3, voffA);
;             PG8_WAIT_V(8); PG8_WAIT_L(0); PG8_BAR; PG8_MMA(1, 0, At, B0); PG8_MMA(1, 1, At, B1); PG8_BAR; PG8_SCHED;
.LBB0_732:
	s_ashr_i32 s53, s52, 31
	s_lshl_b64 s[6:7], s[52:53], 19
	s_add_u32 s54, s78, s6
	s_addc_u32 s55, s79, s7
	s_and_b64 s[6:7], s[38:39], exec
	s_cselect_b32 s5, s55, s37
	s_cselect_b32 s6, s54, s36
	s_ashr_i32 s51, s50, 31
	s_lshl_b64 s[56:57], s[50:51], 19
	s_add_u32 s56, s2, s56
	s_addc_u32 s57, s3, s57
	s_and_b64 s[60:61], s[38:39], exec
	s_cselect_b32 s7, s57, s41
	s_cselect_b32 s51, s56, s40
	s_add_u32 s53, s40, 0x100
	s_addc_u32 s64, s41, 0
	s_add_u32 s40, s36, 0x40080
	s_addc_u32 s41, s37, 0
	s_mov_b32 s65, -2
	s_add_u32 s58, s40, 0xfffc0080
	s_addc_u32 s59, s41, -1
	s_add_i32 s74, 0, 0x10000
	s_cmp_eq_u32 s65, 12
	s_cselect_b32 s61, s5, s59
	s_cselect_b32 s60, s6, s58
	s_cselect_b32 s59, s7, s64
	s_cselect_b32 s58, s51, s53
	s_add_i32 s91, 0, 0x14000
	s_add_i32 m0, s35, 0xc000
	v_lshl_add_u64 v[178:179], s[40:41], 0, v[196:197]
	global_load_lds_dwordx4 v[178:179], off
	v_lshl_add_u64 v[178:179], s[40:41], 0, v[194:195]
	s_add_i32 m0, s35, 0xe000
	s_nop 0
	global_load_lds_dwordx4 v[178:179], off
	s_waitcnt vmcnt(8)
	s_waitcnt lgkmcnt(0)
	s_barrier
	s_setprio 1
	v_mfma_f32_16x16x32_bf16 v[124:127], v[128:131], v[160:163], 0
	v_mfma_f32_16x16x32_bf16 v[120:123], v[136:139], v[160:163], 0
	v_mfma_f32_16x16x32_bf16 v[108:111], v[128:131], v[170:173], 0
	v_mfma_f32_16x16x32_bf16 v[104:107], v[136:139], v[170:173], 0
	v_mfma_f32_16x16x32_bf16 v[92:95], v[128:131], v[202:205], 0
	v_mfma_f32_16x16x32_bf16 v[88:91], v[136:139], v[202:205], 0
	v_mfma_f32_16x16x32_bf16 v[76:79], v[128:131], v[210:213], 0
	v_mfma_f32_16x16x32_bf16 v[72:75], v[136:139], v[210:213], 0
	v_mfma_f32_16x16x32_bf16 v[124:127], v[132:135], v[164:167], v[124:127]
	v_mfma_f32_16x16x32_bf16 v[120:123], v[140:143], v[164:167], v[120:123]
	v_mfma_f32_16x16x32_bf16 v[108:111], v[132:135], v[198:201], v[108:111]
	v_mfma_f32_16x16x32_bf16 v[104:107], v[140:143], v[198:201], v[104:107]
	v_mfma_f32_16x16x32_bf16 v[92:95], v[132:135], v[206:209], v[92:95]
	v_mfma_f32_16x16x32_bf16 v[88:91], v[140:143], v[206:209], v[88:91]
	v_mfma_f32_16x16x32_bf16 v[76:79], v[132:135], v[214:217], v[76:79]
	v_mfma_f32_16x16x32_bf16 v[72:75], v[140:143], v[214:217], v[72:75]
	s_setprio 0
	s_setprio 1
	v_mfma_f32_16x16x32_bf16 v[116:119], v[144:147], v[160:163], 0
	v_mfma_f32_16x16x32_bf16 v[112:115], v[152:155], v[160:163], 0
	v_mfma_f32_16x16x32_bf16 v[100:103], v[144:147], v[170:173], 0
	v_mfma_f32_16x16x32_bf16 v[96:99], v[152:155], v[170:173], 0
	v_mfma_f32_16x16x32_bf16 v[84:87], v[144:147], v[202:205], 0
	v_mfma_f32_16x16x32_bf16 v[80:83], v[152:155], v[202:205], 0
	v_mfma_f32_16x16x32_bf16 v[68:71], v[144:147], v[210:213], 0
	v_mfma_f32_16x16x32_bf16 v[64:67], v[152:155], v[210:213], 0
	v_mfma_f32_16x16x32_bf16 v[116:119], v[148:151], v[164:167], v[116:119]
	v_mfma_f32_16x16x32_bf16 v[112:115], v[156:159], v[164:167], v[112:115]
	v_mfma_f32_16x16x32_bf16 v[100:103], v[148:151], v[198:201], v[100:103]
	v_mfma_f32_16x16x32_bf16 v[96:99], v[156:159], v[198:201], v[96:99]
	v_mfma_f32_16x16x32_bf16 v[84:87], v[148:151], v[206:209], v[84:87]
	s_add_i32 s74, s74, s34
	v_mfma_f32_16x16x32_bf16 v[80:83], v[156:159], v[206:209], v[80:83]
	v_lshl_add_u64 v[178:179], s[58:59], 0, v[168:169]
	v_mfma_f32_16x16x32_bf16 v[68:71], v[148:151], v[214:217], v[68:71]
	s_mov_b32 m0, s74
	v_mfma_f32_16x16x32_bf16 v[64:67], v[156:159], v[214:217], v[64:67]
	s_setprio 0
	s_barrier
	ds_read_b128 v[160:163], v225 offset:16384
	ds_read_b128 v[164:167], v225 offset:17408
	ds_read_b128 v[170:173], v225 offset:18432
	ds_read_b128 v[198:201], v225 offset:19456
	ds_read_b128 v[202:205], v225 offset:20480
	ds_read_b128 v[206:209], v225 offset:21504
	ds_read_b128 v[210:213], v225 offset:22528
	ds_read_b128 v[214:217], v225 offset:23552
	global_load_lds_dwordx4 v[178:179], off
	s_add_i32 m0, s74, 0x2000
	s_add_u32 s74, s58, 0x40000
	v_lshl_add_u64 v[218:219], s[58:59], 0, v[188:189]
	s_addc_u32 s75, s59, 0
	s_add_i32 s91, s91, s34
	global_load_lds_dwordx4 v[218:219], off
	v_lshl_add_u64 v[220:221], s[74:75], 0, v[168:169]
	s_mov_b32 m0, s91
	v_lshl_add_u64 v[234:235], s[60:61], 0, v[190:191]
	global_load_lds_dwordx4 v[220:221], off
	v_lshl_add_u64 v[220:221], s[74:75], 0, v[188:189]
	s_add_i32 m0, s91, 0x2000
	s_nop 0
	global_load_lds_dwordx4 v[220:221], off
	v_lshl_add_u64 v[220:221], s[60:61], 0, v[192:193]
	s_mov_b32 m0, s35
	s_nop 0
	global_load_lds_dwordx4 v[220:221], off
	s_mov_b32 m0, s69
	s_nop 0
	global_load_lds_dwordx4 v[234:235], off
	s_waitcnt vmcnt(8)
	s_waitcnt lgkmcnt(0)
	s_barrier
	s_setprio 1
	v_mfma_f32_16x16x32_bf16 v[60:63], v[128:131], v[160:163], 0
	v_mfma_f32_16x16x32_bf16 v[56:59], v[136:139], v[160:163], 0
	v_mfma_f32_16x16x32_bf16 v[44:47], v[128:131], v[170:173], 0
	v_mfma_f32_16x16x32_bf16 v[40:43], v[136:139], v[170:173], 0
	v_mfma_f32_16x16x32_bf16 v[28:31], v[128:131], v[202:205], 0
	v_mfma_f32_16x16x32_bf16 v[24:27], v[136:139], v[202:205], 0
	v_mfma_f32_16x16x32_bf16 v[12:15], v[128:131], v[210:213], 0
	v_mfma_f32_16x16x32_bf16 v[8:11], v[136:139], v[210:213], 0
	v_mfma_f32_16x16x32_bf16 v[60:63], v[132:135], v[164:167], v[60:63]
	v_mfma_f32_16x16x32_bf16 v[56:59], v[140:143], v[164:167], v[56:59]
	v_mfma_f32_16x16x32_bf16 v[44:47], v[132:135], v[198:201], v[44:47]
	v_mfma_f32_16x16x32_bf16 v[40:43], v[140:143], v[198:201], v[40:43]
	v_mfma_f32_16x16x32_bf16 v[28:31], v[132:135], v[206:209], v[28:31]
	v_mfma_f32_16x16x32_bf16 v[24:27], v[140:143], v[206:209], v[24:27]
	v_mfma_f32_16x16x32_bf16 v[12:15], v[132:135], v[214:217], v[12:15]
	v_mfma_f32_16x16x32_bf16 v[8:11], v[140:143], v[214:217], v[8:11]
	s_setprio 0
	s_setprio 1
	v_mfma_f32_16x16x32_bf16 v[52:55], v[144:147], v[160:163], 0
	v_mfma_f32_16x16x32_bf16 v[48:51], v[152:155], v[160:163], 0
	v_mfma_f32_16x16x32_bf16 v[36:39], v[144:147], v[170:173], 0
	v_mfma_f32_16x16x32_bf16 v[32:35], v[152:155], v[170:173], 0
	v_mfma_f32_16x16x32_bf16 v[20:23], v[144:147], v[202:205], 0
	v_mfma_f32_16x16x32_bf16 v[16:19], v[152:155], v[202:205], 0
	v_mfma_f32_16x16x32_bf16 v[4:7], v[144:147], v[210:213], 0
	v_mfma_f32_16x16x32_bf16 v[0:3], v[152:155], v[210:213], 0
	v_mfma_f32_16x16x32_bf16 v[52:55], v[148:151], v[164:167], v[52:55]
	v_mfma_f32_16x16x32_bf16 v[48:51], v[156:159], v[164:167], v[48:51]
	v_mfma_f32_16x16x32_bf16 v[36:39], v[148:151], v[198:201], v[36:39]
	v_mfma_f32_16x16x32_bf16 v[32:35], v[156:159], v[198:201], v[32:35]
	s_add_i32 s74, 0, 0x18000
	v_mfma_f32_16x16x32_bf16 v[20:23], v[148:151], v[206:209], v[20:23]
	s_add_i32 s75, 0, 0x1c000
	v_mfma_f32_16x16x32_bf16 v[16:19], v[156:159], v[206:209], v[16:19]
	v_add_u32_e32 v240, s74, v224
	v_mfma_f32_16x16x32_bf16 v[4:7], v[148:151], v[214:217], v[4:7]
	v_add_u32_e32 v241, s75, v224
	v_mfma_f32_16x16x32_bf16 v[0:3], v[156:159], v[214:217], v[0:3]
	s_setprio 0
	s_barrier
; #define PG8_STAGE(bufoff, gbase, voff) do { _Pragma("unroll") for (int _i = 0; _i < 2; ++_i) \
;         __builtin_amdgcn_global_load_lds((const unsigned*)((const char*)(gbase) + (voff)[_i]), (PG8_LAS unsigned*)(lds + (bufoff) + ldsw + _i * 8192), 16, 0, 0); } while (0)
; #define PG8_LDA(dst, b, h) do { _Pragma("unroll") for (int m = 0; m < 4; ++m) _Pragma("unroll") for (int k = 0; k < 2; ++k) dst[m][k] = *(const PG8_LAS bf16x8*)(lds + PG8_SA(b, h) + aoff + m * 2048 + k * 1024); } while (0)
; #define PG8_LDB(dst, b, h) do { _Pragma("unroll") for (int n = 0; n < 2; ++n) _Pragma("unroll") for (int k = 0; k < 2; ++k) dst[n][k] = *(const PG8_LAS bf16x8*)(lds + PG8_SB(b, h) + boff + n * 2048 + k * 1024); } while (0)
; #define PG8_MMA(ai, bj, At, Bt) do { __builtin_amdgcn_s_setprio(1); _Pragma("unroll") for (int m = 0; m < 4; ++m) _Pragma("unroll") for (int n = 0; n < 2; ++n) _Pragma("unroll") for (int k = 0; k < 2; ++k) \
;         acc[ai][bj][m][n] = __builtin_amdgcn_mfma_f32_16x16x32_bf16(Bt[n][k], At[m][k], acc[ai][bj][m][n], 0, 0, 0); __builtin_amdgcn_s_setprio(0); } while (0)
; #define PG8_WAIT_V(n) asm volatile("s_waitcnt vmcnt(" #n ")" ::: "memory")
; template <class Epi, class Sched, bool ALIGN_EPI = false, bool SP2 = false>
; __device__ __forceinline__ void gemm_phase(PG8_LAS unsigned char* lds, const Gemm g, const Sched& S, const Epi& E) {
;     ...
;             PG8_LDB(B0, 0, 0); PG8_LDB(B1, 0, 1); PG8_SCHED; PG8_LDA(At, 0, 0); PG8_STAGE(PG8_SA(1, 1), a1 + hstepA, voffA);
;             PG8_WAIT_V(8); PG8_WAIT_L(0); PG8_BAR; PG8_MMA(0, 0, At, B0); PG8_MMA(0, 1, At, B1); PG8_BAR; PG8_SCHED;
;             PG8_LDA(At, 0, 1); PG8_STAGE(PG8_SB(0, 0), b2, voffB); PG8_STAGE(PG8_SB(0, 1), b2 + hstep, voffB); PG8_STAGE(PG8_SA(0, 0), a2, voffA);
;             PG8_WAIT_V(8); PG8_WAIT_L(0); PG8_BAR; PG8_MMA(1, 0, At, B0); PG8_MMA(1, 1, At, B1); PG8_BAR; PG8_SCHED;
;             PG8_LDB(B0, 1, 0); PG8_LDB(B1, 1, 1); PG8_SCHED; PG8_LDA(At, 1, 0); PG8_STAGE(PG8_SA(0, 1), a2 + hstepA, voffA);
;             PG8_WAIT_V(8); PG8_WAIT_L(0); PG8_BAR; PG8_MMA(0, 0, At, B0); PG8_MMA(0, 1, At, B1); PG8_BAR; PG8_SCHED;
;             PG8_LDA(At, 1, 1); PG8_STAGE(PG8_SB(1, 0), b3, voffB); PG8_STAGE(PG8_SB(1, 1), b3 + hstep, voffB); PG8_STAGE(PG8_SA(1, 0), a3, voffA);
;             PG8_WAIT_V(8); PG8_WAIT_L(0); PG8_BAR; PG8_MMA(1, 0, At, B0); PG8_MMA(1, 1, At, B1); PG8_BAR; PG8_SCHED;
	ds_read_b128 v[128:131], v240
	ds_read_b128 v[132:135], v240 offset:1024
	ds_read_b128 v[136:139], v240 offset:2048
	ds_read_b128 v[140:143], v240 offset:3072
	ds_read_b128 v[144:147], v241
	ds_read_b128 v[148:151], v241 offset:1024
	ds_read_b128 v[152:155], v241 offset:2048
	ds_read_b128 v[156:159], v241 offset:3072
	ds_read_b128 v[160:163], v225 offset:32768
	ds_read_b128 v[164:167], v225 offset:33792
	ds_read_b128 v[170:173], v225 offset:34816
	ds_read_b128 v[198:201], v225 offset:35840
	ds_read_b128 v[202:205], v225 offset:36864
	ds_read_b128 v[206:209], v225 offset:37888
	ds_read_b128 v[210:213], v225 offset:38912
	ds_read_b128 v[214:217], v225 offset:39936
	s_add_u32 s60, s60, 0x40000
	s_addc_u32 s61, s61, 0
	s_mov_b32 m0, s73
	v_lshl_add_u64 v[236:237], s[60:61], 0, v[192:193]
	global_load_lds_dwordx4 v[236:237], off
	v_lshl_add_u64 v[236:237], s[60:61], 0, v[190:191]
	s_mov_b32 m0, s80
	s_nop 0
	global_load_lds_dwordx4 v[236:237], off
	s_waitcnt vmcnt(8)
	s_waitcnt lgkmcnt(0)
	s_barrier
	s_setprio 1
	v_mfma_f32_16x16x32_bf16 v[124:127], v[128:131], v[160:163], v[124:127]
	v_mfma_f32_16x16x32_bf16 v[120:123], v[136:139], v[160:163], v[120:123]
	v_mfma_f32_16x16x32_bf16 v[108:111], v[128:131], v[170:173], v[108:111]
	v_mfma_f32_16x16x32_bf16 v[104:107], v[136:139], v[170:173], v[104:107]
	v_mfma_f32_16x16x32_bf16 v[92:95], v[128:131], v[202:205], v[92:95]
	v_mfma_f32_16x16x32_bf16 v[88:91], v[136:139], v[202:205], v[88:91]
	v_mfma_f32_16x16x32_bf16 v[76:79], v[128:131], v[210:213], v[76:79]
	v_mfma_f32_16x16x32_bf16 v[72:75], v[136:139], v[210:213], v[72:75]
	v_mfma_f32_16x16x32_bf16 v[124:127], v[132:135], v[164:167], v[124:127]
	v_mfma_f32_16x16x32_bf16 v[120:123], v[140:143], v[164:167], v[120:123]
	v_mfma_f32_16x16x32_bf16 v[108:111], v[132:135], v[198:201], v[108:111]
	v_mfma_f32_16x16x32_bf16 v[104:107], v[140:143], v[198:201], v[104:107]
	v_mfma_f32_16x16x32_bf16 v[92:95], v[132:135], v[206:209], v[92:95]
	v_mfma_f32_16x16x32_bf16 v[88:91], v[140:143], v[206:209], v[88:91]
	v_mfma_f32_16x16x32_bf16 v[76:79], v[132:135], v[214:217], v[76:79]
	v_mfma_f32_16x16x32_bf16 v[72:75], v[140:143], v[214:217], v[72:75]
	s_setprio 0
	s_setprio 1
	v_mfma_f32_16x16x32_bf16 v[116:119], v[144:147], v[160:163], v[116:119]
	v_mfma_f32_16x16x32_bf16 v[112:115], v[152:155], v[160:163], v[112:115]
	v_mfma_f32_16x16x32_bf16 v[100:103], v[144:147], v[170:173], v[100:103]
	v_mfma_f32_16x16x32_bf16 v[96:99], v[152:155], v[170:173], v[96:99]
	v_mfma_f32_16x16x32_bf16 v[84:87], v[144:147], v[202:205], v[84:87]
	v_mfma_f32_16x16x32_bf16 v[80:83], v[152:155], v[202:205], v[80:83]
	v_mfma_f32_16x16x32_bf16 v[68:71], v[144:147], v[210:213], v[68:71]
	v_mfma_f32_16x16x32_bf16 v[64:67], v[152:155], v[210:213], v[64:67]
	v_mfma_f32_16x16x32_bf16 v[116:119], v[148:151], v[164:167], v[116:119]
	v_mfma_f32_16x16x32_bf16 v[112:115], v[156:159], v[164:167], v[112:115]
	v_mfma_f32_16x16x32_bf16 v[100:103], v[148:151], v[198:201], v[100:103]
	v_mfma_f32_16x16x32_bf16 v[96:99], v[156:159], v[198:201], v[96:99]
	v_mfma_f32_16x16x32_bf16 v[84:87], v[148:151], v[206:209], v[84:87]
	s_add_i32 s60, s74, s34
	v_mfma_f32_16x16x32_bf16 v[80:83], v[156:159], v[206:209], v[80:83]
	v_lshl_add_u64 v[178:179], v[178:179], 0, s[30:31]
	v_mfma_f32_16x16x32_bf16 v[68:71], v[148:151], v[214:217], v[68:71]
	s_mov_b32 m0, s60
	v_mfma_f32_16x16x32_bf16 v[64:67], v[156:159], v[214:217], v[64:67]
	s_setprio 0
	s_barrier
	ds_read_b128 v[160:163], v225 offset:49152
	ds_read_b128 v[164:167], v225 offset:50176
	ds_read_b128 v[170:173], v225 offset:51200
	ds_read_b128 v[198:201], v225 offset:52224
	ds_read_b128 v[202:205], v225 offset:53248
	ds_read_b128 v[206:209], v225 offset:54272
	ds_read_b128 v[210:213], v225 offset:55296
	ds_read_b128 v[214:217], v225 offset:56320
	global_load_lds_dwordx4 v[178:179], off
	s_add_i32 m0, s60, 0x2000
	s_add_u32 s58, s58, 0x40080
	v_lshl_add_u64 v[178:179], v[218:219], 0, s[30:31]
	s_addc_u32 s59, s59, 0
	s_add_i32 s60, s75, s34
	global_load_lds_dwordx4 v[178:179], off
	v_lshl_add_u64 v[178:179], s[58:59], 0, v[168:169]
	s_mov_b32 m0, s60
	s_nop 0
	global_load_lds_dwordx4 v[178:179], off
	v_lshl_add_u64 v[178:179], s[58:59], 0, v[188:189]
	s_add_i32 m0, s60, 0x2000
	s_nop 0
	global_load_lds_dwordx4 v[178:179], off
	v_lshl_add_u64 v[178:179], v[220:221], 0, s[30:31]
	s_mov_b32 m0, s84
	s_nop 0
	global_load_lds_dwordx4 v[178:179], off
	v_lshl_add_u64 v[178:179], v[234:235], 0, s[30:31]
	s_mov_b32 m0, s85
	s_nop 0
	global_load_lds_dwordx4 v[178:179], off
	s_waitcnt vmcnt(8)
	s_waitcnt lgkmcnt(0)
	s_barrier
; #define PG8_STAGE(bufoff, gbase, voff) do { _Pragma("unroll") for (int _i = 0; _i < 2; ++_i) \
;         __builtin_amdgcn_global_load_lds((const unsigned*)((const char*)(gbase) + (voff)[_i]), (PG8_LAS unsigned*)(lds + (bufoff) + ldsw + _i * 8192), 16, 0, 0); } while (0)
; #define PG8_LDA(dst, b, h) do { _Pragma("unroll") for (int m = 0; m < 4; ++m) _Pragma("unroll") for (int k = 0; k < 2; ++k) dst[m][k] = *(const PG8_LAS bf16x8*)(lds + PG8_SA(b, h) + aoff + m * 2048 + k * 1024); } while (0)
; #define PG8_LDB(dst, b, h) do { _Pragma("unroll") for (int n = 0; n < 2; ++n) _Pragma("unroll") for (int k = 0; k < 2; ++k) dst[n][k] = *(const PG8_LAS bf16x8*)(lds + PG8_SB(b, h) + boff + n * 2048 + k * 1024); } while (0)
; #define PG8_MMA(ai, bj, At, Bt) do { __builtin_amdgcn_s_setprio(1); _Pragma("unroll") for (int m = 0; m < 4; ++m) _Pragma("unroll") for (int n = 0; n < 2; ++n) _Pragma("unroll") for (int k = 0; k < 2; ++k) \
;         acc[ai][bj][m][n] = __builtin_amdgcn_mfma_f32_16x16x32_bf16(Bt[n][k], At[m][k], acc[ai][bj][m][n], 0, 0, 0); __builtin_amdgcn_s_setprio(0); } while (0)
; #define PG8_WAIT_V(n) asm volatile("s_waitcnt vmcnt(" #n ")" ::: "memory")
; template <class Epi, class Sched, bool ALIGN_EPI = false, bool SP2 = false>
; __device__ __forceinline__ void gemm_phase(PG8_LAS unsigned char* lds, const Gemm g, const Sched& S, const Epi& E) {
;     ...
;             PG8_LDB(B0, 0, 0); PG8_LDB(B1, 0, 1); PG8_SCHED; PG8_LDA(At, 0, 0); PG8_STAGE(PG8_SA(1, 1), a1 + hstepA, voffA);
;             PG8_WAIT_V(8); PG8_WAIT_L(0); PG8_BAR; PG8_MMA(0, 0, At, B0); PG8_MMA(0, 1, At, B1); PG8_BAR; PG8_SCHED;
;             PG8_LDA(At, 0, 1); PG8_STAGE(PG8_SB(0, 0), b2, voffB); PG8_STAGE(PG8_SB(0, 1), b2 + hstep, voffB); PG8_STAGE(PG8_SA(0, 0), a2, voffA);
;             PG8_WAIT_V(8); PG8_WAIT_L(0); PG8_BAR; PG8_MMA(1, 0, At, B0); PG8_MMA(1, 1, At, B1); PG8_BAR; PG8_SCHED;
;             PG8_LDB(B0, 1, 0); PG8_LDB(B1, 1, 1); PG8_SCHED; PG8_LDA(At, 1, 0); PG8_STAGE(PG8_SA(0, 1), a2 + hstepA, voffA);
;             PG8_WAIT_V(8); PG8_WAIT_L(0); PG8_BAR; PG8_MMA(0, 0, At, B0); PG8_MMA(0, 1, At, B1); PG8_BAR; PG8_SCHED;
;             PG8_LDA(At, 1, 1); PG8_STAGE(PG8_SB(1, 0), b3, voffB); PG8_STAGE(PG8_SB(1, 1), b3 + hstep, voffB); PG8_STAGE(PG8_SA(1, 0), a3, voffA);
;             PG8_WAIT_V(8); PG8_WAIT_L(0); PG8_BAR; PG8_MMA(1, 0, At, B0); PG8_MMA(1, 1, At, B1); PG8_BAR; PG8_SCHED;
	s_setprio 1
	v_mfma_f32_16x16x32_bf16 v[60:63], v[128:131], v[160:163], v[60:63]
	v_mfma_f32_16x16x32_bf16 v[56:59], v[136:139], v[160:163], v[56:59]
	v_mfma_f32_16x16x32_bf16 v[44:47], v[128:131], v[170:173], v[44:47]
	v_mfma_f32_16x16x32_bf16 v[40:43], v[136:139], v[170:173], v[40:43]
	v_mfma_f32_16x16x32_bf16 v[28:31], v[128:131], v[202:205], v[28:31]
	v_mfma_f32_16x16x32_bf16 v[24:27], v[136:139], v[202:205], v[24:27]
	v_mfma_f32_16x16x32_bf16 v[12:15], v[128:131], v[210:213], v[12:15]
	v_mfma_f32_16x16x32_bf16 v[8:11], v[136:139], v[210:213], v[8:11]
	v_mfma_f32_16x16x32_bf16 v[60:63], v[132:135], v[164:167], v[60:63]
	v_mfma_f32_16x16x32_bf16 v[56:59], v[140:143], v[164:167], v[56:59]
	v_mfma_f32_16x16x32_bf16 v[44:47], v[132:135], v[198:201], v[44:47]
	v_mfma_f32_16x16x32_bf16 v[40:43], v[140:143], v[198:201], v[40:43]
	v_mfma_f32_16x16x32_bf16 v[28:31], v[132:135], v[206:209], v[28:31]
	v_mfma_f32_16x16x32_bf16 v[24:27], v[140:143], v[206:209], v[24:27]
	v_mfma_f32_16x16x32_bf16 v[12:15], v[132:135], v[214:217], v[12:15]
	v_mfma_f32_16x16x32_bf16 v[8:11], v[140:143], v[214:217], v[8:11]
	s_add_i32 s65, s65, 2
	s_setprio 0
	s_setprio 1
	v_mfma_f32_16x16x32_bf16 v[52:55], v[144:147], v[160:163], v[52:55]
	s_add_u32 s53, s53, 0x100
	v_mfma_f32_16x16x32_bf16 v[48:51], v[152:155], v[160:163], v[48:51]
	s_addc_u32 s64, s64, 0
	v_mfma_f32_16x16x32_bf16 v[36:39], v[144:147], v[170:173], v[36:39]
	s_add_u32 s40, s40, 0x100
	v_mfma_f32_16x16x32_bf16 v[32:35], v[152:155], v[170:173], v[32:35]
	s_addc_u32 s41, s41, 0
	v_mfma_f32_16x16x32_bf16 v[20:23], v[144:147], v[202:205], v[20:23]
	s_add_u32 s58, s40, 0xfffc0080
	v_mfma_f32_16x16x32_bf16 v[16:19], v[152:155], v[202:205], v[16:19]
	s_addc_u32 s59, s41, -1
	v_mfma_f32_16x16x32_bf16 v[4:7], v[144:147], v[210:213], v[4:7]
	s_add_i32 s74, 0, 0x10000
	v_mfma_f32_16x16x32_bf16 v[0:3], v[152:155], v[210:213], v[0:3]
	s_cmp_eq_u32 s65, 12
	v_mfma_f32_16x16x32_bf16 v[52:55], v[148:151], v[164:167], v[52:55]
	s_cselect_b32 s61, s5, s59
	v_mfma_f32_16x16x32_bf16 v[48:51], v[156:159], v[164:167], v[48:51]
	s_cselect_b32 s60, s6, s58
	v_mfma_f32_16x16x32_bf16 v[36:39], v[148:151], v[198:201], v[36:39]
	s_cselect_b32 s59, s7, s64
	v_mfma_f32_16x16x32_bf16 v[32:35], v[156:159], v[198:201], v[32:35]
	s_cselect_b32 s58, s51, s53
	v_mfma_f32_16x16x32_bf16 v[20:23], v[148:151], v[206:209], v[20:23]
	s_add_i32 s91, 0, 0x14000
	v_mfma_f32_16x16x32_bf16 v[16:19], v[156:159], v[206:209], v[16:19]
	v_add_u32_e32 v242, s74, v224
	v_mfma_f32_16x16x32_bf16 v[4:7], v[148:151], v[214:217], v[4:7]
	v_add_u32_e32 v243, s91, v224
	v_mfma_f32_16x16x32_bf16 v[0:3], v[156:159], v[214:217], v[0:3]
	s_setprio 0
	s_barrier
.LBB0_733:
	ds_read_b128 v[128:131], v242
	ds_read_b128 v[132:135], v242 offset:1024
	ds_read_b128 v[136:139], v242 offset:2048
	ds_read_b128 v[140:143], v242 offset:3072
	ds_read_b128 v[144:147], v243
	ds_read_b128 v[148:151], v243 offset:1024
	ds_read_b128 v[152:155], v243 offset:2048
	ds_read_b128 v[156:159], v243 offset:3072
	ds_read_b128 v[160:163], v225
	ds_read_b128 v[164:167], v225 offset:1024
	ds_read_b128 v[170:173], v225 offset:2048
	ds_read_b128 v[198:201], v225 offset:3072
	ds_read_b128 v[202:205], v225 offset:4096
	ds_read_b128 v[206:209], v225 offset:5120
	ds_read_b128 v[210:213], v225 offset:6144
	ds_read_b128 v[214:217], v225 offset:7168
	s_add_i32 m0, s35, 0xc000
	v_lshl_add_u64 v[178:179], s[40:41], 0, v[196:197]
	global_load_lds_dwordx4 v[178:179], off
	v_lshl_add_u64 v[178:179], s[40:41], 0, v[194:195]
	s_add_i32 m0, s35, 0xe000
	s_nop 0
	global_load_lds_dwordx4 v[178:179], off
	s_waitcnt vmcnt(8)
	s_waitcnt lgkmcnt(0)
	s_barrier
	s_setprio 1
	v_mfma_f32_16x16x32_bf16 v[124:127], v[128:131], v[160:163], v[124:127]
	v_mfma_f32_16x16x32_bf16 v[120:123], v[136:139], v[160:163], v[120:123]
	v_mfma_f32_16x16x32_bf16 v[108:111], v[128:131], v[170:173], v[108:111]
	v_mfma_f32_16x16x32_bf16 v[104:107], v[136:139], v[170:173], v[104:107]
	v_mfma_f32_16x16x32_bf16 v[92:95], v[128:131], v[202:205], v[92:95]
	v_mfma_f32_16x16x32_bf16 v[88:91], v[136:139], v[202:205], v[88:91]
	v_mfma_f32_16x16x32_bf16 v[76:79], v[128:131], v[210:213], v[76:79]
	v_mfma_f32_16x16x32_bf16 v[72:75], v[136:139], v[210:213], v[72:75]
	v_mfma_f32_16x16x32_bf16 v[124:127], v[132:135], v[164:167], v[124:127]
	v_mfma_f32_16x16x32_bf16 v[120:123], v[140:143], v[164:167], v[120:123]
	v_mfma_f32_16x16x32_bf16 v[108:111], v[132:135], v[198:201], v[108:111]
	v_mfma_f32_16x16x32_bf16 v[104:107], v[140:143], v[198:201], v[104:107]
	v_mfma_f32_16x16x32_bf16 v[92:95], v[132:135], v[206:209], v[92:95]
	v_mfma_f32_16x16x32_bf16 v[88:91], v[140:143], v[206:209], v[88:91]
	v_mfma_f32_16x16x32_bf16 v[76:79], v[132:135], v[214:217], v[76:79]
	v_mfma_f32_16x16x32_bf16 v[72:75], v[140:143], v[214:217], v[72:75]
	s_setprio 0
	s_setprio 1
	v_mfma_f32_16x16x32_bf16 v[116:119], v[144:147], v[160:163], v[116:119]
	v_mfma_f32_16x16x32_bf16 v[112:115], v[152:155], v[160:163], v[112:115]
	v_mfma_f32_16x16x32_bf16 v[100:103], v[144:147], v[170:173], v[100:103]
	v_mfma_f32_16x16x32_bf16 v[96:99], v[152:155], v[170:173], v[96:99]
	v_mfma_f32_16x16x32_bf16 v[84:87], v[144:147], v[202:205], v[84:87]
	v_mfma_f32_16x16x32_bf16 v[80:83], v[152:155], v[202:205], v[80:83]
	v_mfma_f32_16x16x32_bf16 v[68:71], v[144:147], v[210:213], v[68:71]
	v_mfma_f32_16x16x32_bf16 v[64:67], v[152:155], v[210:213], v[64:67]
	v_mfma_f32_16x16x32_bf16 v[116:119], v[148:151], v[164:167], v[116:119]
	v_mfma_f32_16x16x32_bf16 v[112:115], v[156:159], v[164:167], v[112:115]
	v_mfma_f32_16x16x32_bf16 v[100:103], v[148:151], v[198:201], v[100:103]
	v_mfma_f32_16x16x32_bf16 v[96:99], v[156:159], v[198:201], v[96:99]
	v_mfma_f32_16x16x32_bf16 v[84:87], v[148:151], v[206:209], v[84:87]
	s_add_i32 s74, s74, s34
	v_mfma_f32_16x16x32_bf16 v[80:83], v[156:159], v[206:209], v[80:83]
	v_lshl_add_u64 v[178:179], s[58:59], 0, v[168:169]
	v_mfma_f32_16x16x32_bf16 v[68:71], v[148:151], v[214:217], v[68:71]
	s_mov_b32 m0, s74
	v_mfma_f32_16x16x32_bf16 v[64:67], v[156:159], v[214:217], v[64:67]
	s_setprio 0
	s_barrier
; #define PG8_STAGE(bufoff, gbase, voff) do { _Pragma("unroll") for (int _i = 0; _i < 2; ++_i) \
;         __builtin_amdgcn_global_load_lds((const unsigned*)((const char*)(gbase) + (voff)[_i]), (PG8_LAS unsigned*)(lds + (bufoff) + ldsw + _i * 8192), 16, 0, 0); } while (0)
; #define PG8_LDA(dst, b, h) do { _Pragma("unroll") for (int m = 0; m < 4; ++m) _Pragma("unroll") for (int k = 0; k < 2; ++k) dst[m][k] = *(const PG8_LAS bf16x8*)(lds + PG8_SA(b, h) + aoff + m * 2048 + k * 1024); } while (0)
; #define PG8_LDB(dst, b, h) do { _Pragma("unroll") for (int n = 0; n < 2; ++n) _Pragma("unroll") for (int k = 0; k < 2; ++k) dst[n][k] = *(const PG8_LAS bf16x8*)(lds + PG8_SB(b, h) + boff + n * 2048 + k * 1024); } while (0)
; #define PG8_MMA(ai, bj, At, Bt) do { __builtin_amdgcn_s_setprio(1); _Pragma("unroll") for (int m = 0; m < 4; ++m) _Pragma("unroll") for (int n = 0; n < 2; ++n) _Pragma("unroll") for (int k = 0; k < 2; ++k) \
;         acc[ai][bj][m][n] = __builtin_amdgcn_mfma_f32_16x16x32_bf16(Bt[n][k], At[m][k], acc[ai][bj][m][n], 0, 0, 0); __builtin_amdgcn_s_setprio(0); } while (0)
; #define PG8_WAIT_V(n) asm volatile("s_waitcnt vmcnt(" #n ")" ::: "memory")
; template <class Epi, class Sched, bool ALIGN_EPI = false, bool SP2 = false>
; __device__ __forceinline__ void gemm_phase(PG8_LAS unsigned char* lds, const Gemm g, const Sched& S, const Epi& E) {
;     ...
;             PG8_LDB(B0, 0, 0); PG8_LDB(B1, 0, 1); PG8_SCHED; PG8_LDA(At, 0, 0); PG8_STAGE(PG8_SA(1, 1), a1 + hstepA, voffA);
;             PG8_WAIT_V(8); PG8_WAIT_L(0); PG8_BAR; PG8_MMA(0, 0, At, B0); PG8_MMA(0, 1, At, B1); PG8_BAR; PG8_SCHED;
;             PG8_LDA(At, 0, 1); PG8_STAGE(PG8_SB(0, 0), b2, voffB); PG8_STAGE(PG8_SB(0, 1), b2 + hstep, voffB); PG8_STAGE(PG8_SA(0, 0), a2, voffA);
;             PG8_WAIT_V(8); PG8_WAIT_L(0); PG8_BAR; PG8_MMA(1, 0, At, B0); PG8_MMA(1, 1, At, B1); PG8_BAR; PG8_SCHED;
;             PG8_LDB(B0, 1, 0); PG8_LDB(B1, 1, 1); PG8_SCHED; PG8_LDA(At, 1, 0); PG8_STAGE(PG8_SA(0, 1), a2 + hstepA, voffA);
;             PG8_WAIT_V(8); PG8_WAIT_L(0); PG8_BAR; PG8_MMA(0, 0, At, B0); PG8_MMA(0, 1, At, B1); PG8_BAR; PG8_SCHED;
;             PG8_LDA(At, 1, 1); PG8_STAGE(PG8_SB(1, 0), b3, voffB); PG8_STAGE(PG8_SB(1, 1), b3 + hstep, voffB); PG8_STAGE(PG8_SA(1, 0), a3, voffA);
;             PG8_WAIT_V(8); PG8_WAIT_L(0); PG8_BAR; PG8_MMA(1, 0, At, B0); PG8_MMA(1, 1, At, B1); PG8_BAR; PG8_SCHED;
	ds_read_b128 v[160:163], v225 offset:16384
	ds_read_b128 v[164:167], v225 offset:17408
	ds_read_b128 v[170:173], v225 offset:18432
	ds_read_b128 v[198:201], v225 offset:19456
	ds_read_b128 v[202:205], v225 offset:20480
	ds_read_b128 v[206:209], v225 offset:21504
	ds_read_b128 v[210:213], v225 offset:22528
	ds_read_b128 v[214:217], v225 offset:23552
	global_load_lds_dwordx4 v[178:179], off
	s_add_i32 m0, s74, 0x2000
	s_add_u32 s74, s58, 0x40000
	v_lshl_add_u64 v[218:219], s[58:59], 0, v[188:189]
	s_addc_u32 s75, s59, 0
	s_add_i32 s91, s91, s34
	global_load_lds_dwordx4 v[218:219], off
	v_lshl_add_u64 v[220:221], s[74:75], 0, v[168:169]
	s_mov_b32 m0, s91
	v_lshl_add_u64 v[234:235], s[60:61], 0, v[190:191]
	global_load_lds_dwordx4 v[220:221], off
	v_lshl_add_u64 v[220:221], s[74:75], 0, v[188:189]
	s_add_i32 m0, s91, 0x2000
	s_nop 0
	global_load_lds_dwordx4 v[220:221], off
	v_lshl_add_u64 v[220:221], s[60:61], 0, v[192:193]
	s_mov_b32 m0, s35
	s_nop 0
	global_load_lds_dwordx4 v[220:221], off
	s_mov_b32 m0, s69
	s_nop 0
	global_load_lds_dwordx4 v[234:235], off
	s_waitcnt vmcnt(8)
	s_waitcnt lgkmcnt(0)
	s_barrier
	s_setprio 1
	v_mfma_f32_16x16x32_bf16 v[60:63], v[128:131], v[160:163], v[60:63]
	v_mfma_f32_16x16x32_bf16 v[56:59], v[136:139], v[160:163], v[56:59]
	v_mfma_f32_16x16x32_bf16 v[44:47], v[128:131], v[170:173], v[44:47]
	v_mfma_f32_16x16x32_bf16 v[40:43], v[136:139], v[170:173], v[40:43]
	v_mfma_f32_16x16x32_bf16 v[28:31], v[128:131], v[202:205], v[28:31]
	v_mfma_f32_16x16x32_bf16 v[24:27], v[136:139], v[202:205], v[24:27]
	v_mfma_f32_16x16x32_bf16 v[12:15], v[128:131], v[210:213], v[12:15]
	v_mfma_f32_16x16x32_bf16 v[8:11], v[136:139], v[210:213], v[8:11]
	v_mfma_f32_16x16x32_bf16 v[60:63], v[132:135], v[164:167], v[60:63]
	v_mfma_f32_16x16x32_bf16 v[56:59], v[140:143], v[164:167], v[56:59]
	v_mfma_f32_16x16x32_bf16 v[44:47], v[132:135], v[198:201], v[44:47]
	v_mfma_f32_16x16x32_bf16 v[40:43], v[140:143], v[198:201], v[40:43]
	v_mfma_f32_16x16x32_bf16 v[28:31], v[132:135], v[206:209], v[28:31]
	v_mfma_f32_16x16x32_bf16 v[24:27], v[140:143], v[206:209], v[24:27]
	v_mfma_f32_16x16x32_bf16 v[12:15], v[132:135], v[214:217], v[12:15]
	v_mfma_f32_16x16x32_bf16 v[8:11], v[140:143], v[214:217], v[8:11]
	s_setprio 0
	s_setprio 1
	v_mfma_f32_16x16x32_bf16 v[52:55], v[144:147], v[160:163], v[52:55]
	v_mfma_f32_16x16x32_bf16 v[48:51], v[152:155], v[160:163], v[48:51]
	v_mfma_f32_16x16x32_bf16 v[36:39], v[144:147], v[170:173], v[36:39]
	v_mfma_f32_16x16x32_bf16 v[32:35], v[152:155], v[170:173], v[32:35]
	v_mfma_f32_16x16x32_bf16 v[20:23], v[144:147], v[202:205], v[20:23]
	v_mfma_f32_16x16x32_bf16 v[16:19], v[152:155], v[202:205], v[16:19]
	v_mfma_f32_16x16x32_bf16 v[4:7], v[144:147], v[210:213], v[4:7]
	v_mfma_f32_16x16x32_bf16 v[0:3], v[152:155], v[210:213], v[0:3]
	v_mfma_f32_16x16x32_bf16 v[52:55], v[148:151], v[164:167], v[52:55]
	v_mfma_f32_16x16x32_bf16 v[48:51], v[156:159], v[164:167], v[48:51]
	v_mfma_f32_16x16x32_bf16 v[36:39], v[148:151], v[198:201], v[36:39]
	v_mfma_f32_16x16x32_bf16 v[32:35], v[156:159], v[198:201], v[32:35]
	s_add_i32 s74, 0, 0x18000
	v_mfma_f32_16x16x32_bf16 v[20:23], v[148:151], v[206:209], v[20:23]
	s_add_i32 s75, 0, 0x1c000
	v_mfma_f32_16x16x32_bf16 v[16:19], v[156:159], v[206:209], v[16:19]
	v_add_u32_e32 v240, s74, v224
	v_mfma_f32_16x16x32_bf16 v[4:7], v[148:151], v[214:217], v[4:7]
	v_add_u32_e32 v241, s75, v224
	v_mfma_f32_16x16x32_bf16 v[0:3], v[156:159], v[214:217], v[0:3]
	s_setprio 0
	s_barrier
	ds_read_b128 v[128:131], v240
	ds_read_b128 v[132:135], v240 offset:1024
	ds_read_b128 v[136:139], v240 offset:2048
	ds_read_b128 v[140:143], v240 offset:3072
	ds_read_b128 v[144:147], v241
	ds_read_b128 v[148:151], v241 offset:1024
	ds_read_b128 v[152:155], v241 offset:2048
	ds_read_b128 v[156:159], v241 offset:3072
	ds_read_b128 v[160:163], v225 offset:32768
	ds_read_b128 v[164:167], v225 offset:33792
	ds_read_b128 v[170:173], v225 offset:34816
	ds_read_b128 v[198:201], v225 offset:35840
	ds_read_b128 v[202:205], v225 offset:36864
	ds_read_b128 v[206:209], v225 offset:37888
	ds_read_b128 v[210:213], v225 offset:38912
	ds_read_b128 v[214:217], v225 offset:39936
	s_add_u32 s60, s60, 0x40000
	s_addc_u32 s61, s61, 0
	s_mov_b32 m0, s73
	v_lshl_add_u64 v[236:237], s[60:61], 0, v[192:193]
	global_load_lds_dwordx4 v[236:237], off
	v_lshl_add_u64 v[236:237], s[60:61], 0, v[190:191]
	s_mov_b32 m0, s80
	s_nop 0
	global_load_lds_dwordx4 v[236:237], off
	s_waitcnt vmcnt(8)
	s_waitcnt lgkmcnt(0)
	s_barrier
; #define PG8_STAGE(bufoff, gbase, voff) do { _Pragma("unroll") for (int _i = 0; _i < 2; ++_i) \
;         __builtin_amdgcn_global_load_lds((const unsigned*)((const char*)(gbase) + (voff)[_i]), (PG8_LAS unsigned*)(lds + (bufoff) + ldsw + _i * 8192), 16, 0, 0); } while (0)
; #define PG8_LDA(dst, b, h) do { _Pragma("unroll") for (int m = 0; m < 4; ++m) _Pragma("unroll") for (int k = 0; k < 2; ++k) dst[m][k] = *(const PG8_LAS bf16x8*)(lds + PG8_SA(b, h) + aoff + m * 2048 + k * 1024); } while (0)
; #define PG8_LDB(dst, b, h) do { _Pragma("unroll") for (int n = 0; n < 2; ++n) _Pragma("unroll") for (int k = 0; k < 2; ++k) dst[n][k] = *(const PG8_LAS bf16x8*)(lds + PG8_SB(b, h) + boff + n * 2048 + k * 1024); } while (0)
; template <class Epi, class Sched, bool ALIGN_EPI = false, bool SP2 = false>
; __device__ __forceinline__ void gemm_phase(PG8_LAS unsigned char* lds, const Gemm g, const Sched& S, const Epi& E) {
;     ...
;         for (int t = 0; t < nt; t += 2) {
;             const bool last = (t == nt - 2);
;             const char* a1 = cA + (size_t)(t + 1) * kstepA;
;             const char* a2 = last ? nA : cA + (size_t)(t + 2) * kstepA; const char* b2 = last ? nB : cB + (size_t)(t + 2) * kstep;
;             const char* a3 = a2 + kstepA; const char* b3 = b2 + kstep;
;             if (last && has_next) S.a_ready(nxt);
;             if constexpr (SP2) {
;             PG8_LDB(B0, 0, 0); PG8_LDB(B1, 0, 1); PG8_SCHED; PG8_LDA(At, 0, 0); PG8_STAGE(PG8_SA(1, 1), a1 + hstepA, voffA);
;             PG8_WAIT_V(8); PG8_WAIT_L(0); PG8_BAR; PG8_MMA(0, 0, At, B0); PG8_MMA(0, 1, At, B1); PG8_BAR; PG8_SCHED;
;             PG8_LDA(At, 0, 1); PG8_STAGE(PG8_SB(0, 0), b2, voffB); PG8_STAGE(PG8_SB(0, 1), b2 + hstep, voffB); PG8_STAGE(PG8_SA(0, 0), a2, voffA);
;             PG8_WAIT_V(8); PG8_WAIT_L(0); PG8_BAR; PG8_MMA(1, 0, At, B0); PG8_MMA(1, 1, At, B1); PG8_BAR; PG8_SCHED;
;             PG8_LDB(B0, 1, 0); PG8_LDB(B1, 1, 1); PG8_SCHED; PG8_LDA(At, 1, 0); PG8_STAGE(PG8_SA(0, 1), a2 + hstepA, voffA);
;             PG8_WAIT_V(8); PG8_WAIT_L(0); PG8_BAR; PG8_MMA(0, 0, At, B0); PG8_MMA(0, 1, At, B1); PG8_BAR; PG8_SCHED;
;             PG8_LDA(At, 1, 1); PG8_STAGE(PG8_SB(1, 0), b3, voffB); PG8_STAGE(PG8_SB(1, 1), b3 + hstep, voffB); PG8_STAGE(PG8_SA(1, 0), a3, voffA);
;             PG8_WAIT_V(8); PG8_WAIT_L(0); PG8_BAR; PG8_MMA(1, 0, At, B0); PG8_MMA(1, 1, At, B1); PG8_BAR; PG8_SCHED;
	s_setprio 1
	v_mfma_f32_16x16x32_bf16 v[124:127], v[128:131], v[160:163], v[124:127]
	v_mfma_f32_16x16x32_bf16 v[120:123], v[136:139], v[160:163], v[120:123]
	v_mfma_f32_16x16x32_bf16 v[108:111], v[128:131], v[170:173], v[108:111]
	v_mfma_f32_16x16x32_bf16 v[104:107], v[136:139], v[170:173], v[104:107]
	v_mfma_f32_16x16x32_bf16 v[92:95], v[128:131], v[202:205], v[92:95]
	v_mfma_f32_16x16x32_bf16 v[88:91], v[136:139], v[202:205], v[88:91]
	v_mfma_f32_16x16x32_bf16 v[76:79], v[128:131], v[210:213], v[76:79]
	v_mfma_f32_16x16x32_bf16 v[72:75], v[136:139], v[210:213], v[72:75]
	v_mfma_f32_16x16x32_bf16 v[124:127], v[132:135], v[164:167], v[124:127]
	v_mfma_f32_16x16x32_bf16 v[120:123], v[140:143], v[164:167], v[120:123]
	v_mfma_f32_16x16x32_bf16 v[108:111], v[132:135], v[198:201], v[108:111]
	v_mfma_f32_16x16x32_bf16 v[104:107], v[140:143], v[198:201], v[104:107]
	v_mfma_f32_16x16x32_bf16 v[92:95], v[132:135], v[206:209], v[92:95]
	v_mfma_f32_16x16x32_bf16 v[88:91], v[140:143], v[206:209], v[88:91]
	v_mfma_f32_16x16x32_bf16 v[76:79], v[132:135], v[214:217], v[76:79]
	v_mfma_f32_16x16x32_bf16 v[72:75], v[140:143], v[214:217], v[72:75]
	s_setprio 0
	s_setprio 1
	v_mfma_f32_16x16x32_bf16 v[116:119], v[144:147], v[160:163], v[116:119]
	v_mfma_f32_16x16x32_bf16 v[112:115], v[152:155], v[160:163], v[112:115]
	v_mfma_f32_16x16x32_bf16 v[100:103], v[144:147], v[170:173], v[100:103]
	v_mfma_f32_16x16x32_bf16 v[96:99], v[152:155], v[170:173], v[96:99]
	v_mfma_f32_16x16x32_bf16 v[84:87], v[144:147], v[202:205], v[84:87]
	v_mfma_f32_16x16x32_bf16 v[80:83], v[152:155], v[202:205], v[80:83]
	v_mfma_f32_16x16x32_bf16 v[68:71], v[144:147], v[210:213], v[68:71]
	v_mfma_f32_16x16x32_bf16 v[64:67], v[152:155], v[210:213], v[64:67]
	v_mfma_f32_16x16x32_bf16 v[116:119], v[148:151], v[164:167], v[116:119]
	v_mfma_f32_16x16x32_bf16 v[112:115], v[156:159], v[164:167], v[112:115]
	v_mfma_f32_16x16x32_bf16 v[100:103], v[148:151], v[198:201], v[100:103]
	v_mfma_f32_16x16x32_bf16 v[96:99], v[156:159], v[198:201], v[96:99]
	v_mfma_f32_16x16x32_bf16 v[84:87], v[148:151], v[206:209], v[84:87]
	s_add_i32 s60, s74, s34
	v_mfma_f32_16x16x32_bf16 v[80:83], v[156:159], v[206:209], v[80:83]
	v_lshl_add_u64 v[178:179], v[178:179], 0, s[30:31]
	v_mfma_f32_16x16x32_bf16 v[68:71], v[148:151], v[214:217], v[68:71]
	s_mov_b32 m0, s60
	v_mfma_f32_16x16x32_bf16 v[64:67], v[156:159], v[214:217], v[64:67]
	s_setprio 0
	s_barrier
	ds_read_b128 v[160:163], v225 offset:49152
	ds_read_b128 v[164:167], v225 offset:50176
	ds_read_b128 v[170:173], v225 offset:51200
	ds_read_b128 v[198:201], v225 offset:52224
	ds_read_b128 v[202:205], v225 offset:53248
	ds_read_b128 v[206:209], v225 offset:54272
	ds_read_b128 v[210:213], v225 offset:55296
	ds_read_b128 v[214:217], v225 offset:56320
	global_load_lds_dwordx4 v[178:179], off
	s_add_i32 m0, s60, 0x2000
	s_add_u32 s58, s58, 0x40080
	v_lshl_add_u64 v[178:179], v[218:219], 0, s[30:31]
	s_addc_u32 s59, s59, 0
	s_add_i32 s60, s75, s34
	global_load_lds_dwordx4 v[178:179], off
	v_lshl_add_u64 v[178:179], s[58:59], 0, v[168:169]
	s_mov_b32 m0, s60
	s_nop 0
	global_load_lds_dwordx4 v[178:179], off
	v_lshl_add_u64 v[178:179], s[58:59], 0, v[188:189]
	s_add_i32 m0, s60, 0x2000
	s_nop 0
	global_load_lds_dwordx4 v[178:179], off
	v_lshl_add_u64 v[178:179], v[220:221], 0, s[30:31]
	s_mov_b32 m0, s84
	s_nop 0
	global_load_lds_dwordx4 v[178:179], off
	v_lshl_add_u64 v[178:179], v[234:235], 0, s[30:31]
	s_mov_b32 m0, s85
	s_nop 0
	global_load_lds_dwordx4 v[178:179], off
	s_waitcnt vmcnt(8)
	s_waitcnt lgkmcnt(0)
	s_barrier
	s_setprio 1
	v_mfma_f32_16x16x32_bf16 v[60:63], v[128:131], v[160:163], v[60:63]
	v_mfma_f32_16x16x32_bf16 v[56:59], v[136:139], v[160:163], v[56:59]
	v_mfma_f32_16x16x32_bf16 v[44:47], v[128:131], v[170:173], v[44:47]
	v_mfma_f32_16x16x32_bf16 v[40:43], v[136:139], v[170:173], v[40:43]
	v_mfma_f32_16x16x32_bf16 v[28:31], v[128:131], v[202:205], v[28:31]
	v_mfma_f32_16x16x32_bf16 v[24:27], v[136:139], v[202:205], v[24:27]
	v_mfma_f32_16x16x32_bf16 v[12:15], v[128:131], v[210:213], v[12:15]
	v_mfma_f32_16x16x32_bf16 v[8:11], v[136:139], v[210:213], v[8:11]
	v_mfma_f32_16x16x32_bf16 v[60:63], v[132:135], v[164:167], v[60:63]
	v_mfma_f32_16x16x32_bf16 v[56:59], v[140:143], v[164:167], v[56:59]
	v_mfma_f32_16x16x32_bf16 v[44:47], v[132:135], v[198:201], v[44:47]
	v_mfma_f32_16x16x32_bf16 v[40:43], v[140:143], v[198:201], v[40:43]
	v_mfma_f32_16x16x32_bf16 v[28:31], v[132:135], v[206:209], v[28:31]
	v_mfma_f32_16x16x32_bf16 v[24:27], v[140:143], v[206:209], v[24:27]
	v_mfma_f32_16x16x32_bf16 v[12:15], v[132:135], v[214:217], v[12:15]
	s_add_i32 s65, s65, 2
	v_mfma_f32_16x16x32_bf16 v[8:11], v[140:143], v[214:217], v[8:11]
	s_add_u32 s53, s53, 0x100
	s_setprio 0
	s_setprio 1
	v_mfma_f32_16x16x32_bf16 v[52:55], v[144:147], v[160:163], v[52:55]
	s_addc_u32 s64, s64, 0
	v_mfma_f32_16x16x32_bf16 v[48:51], v[152:155], v[160:163], v[48:51]
	s_add_u32 s40, s40, 0x100
	v_mfma_f32_16x16x32_bf16 v[36:39], v[144:147], v[170:173], v[36:39]
	s_addc_u32 s41, s41, 0
	v_mfma_f32_16x16x32_bf16 v[32:35], v[152:155], v[170:173], v[32:35]
	s_add_u32 s58, s40, 0xfffc0080
	v_mfma_f32_16x16x32_bf16 v[20:23], v[144:147], v[202:205], v[20:23]
	s_addc_u32 s59, s41, -1
	v_mfma_f32_16x16x32_bf16 v[16:19], v[152:155], v[202:205], v[16:19]
	s_add_i32 s74, 0, 0x10000
	v_mfma_f32_16x16x32_bf16 v[4:7], v[144:147], v[210:213], v[4:7]
	s_cmp_eq_u32 s65, 12
	v_mfma_f32_16x16x32_bf16 v[0:3], v[152:155], v[210:213], v[0:3]
	s_cselect_b32 s61, s5, s59
	v_mfma_f32_16x16x32_bf16 v[52:55], v[148:151], v[164:167], v[52:55]
	s_cselect_b32 s60, s6, s58
	v_mfma_f32_16x16x32_bf16 v[48:51], v[156:159], v[164:167], v[48:51]
	s_cselect_b32 s59, s7, s64
	v_mfma_f32_16x16x32_bf16 v[36:39], v[148:151], v[198:201], v[36:39]
	s_cselect_b32 s58, s51, s53
	v_mfma_f32_16x16x32_bf16 v[32:35], v[156:159], v[198:201], v[32:35]
	s_add_i32 s91, 0, 0x14000
	v_mfma_f32_16x16x32_bf16 v[20:23], v[148:151], v[206:209], v[20:23]
	v_add_u32_e32 v242, s74, v224
	v_mfma_f32_16x16x32_bf16 v[16:19], v[156:159], v[206:209], v[16:19]
	v_add_u32_e32 v243, s91, v224
	v_mfma_f32_16x16x32_bf16 v[4:7], v[148:151], v[214:217], v[4:7]
	s_cmp_gt_u32 s65, 13
	v_mfma_f32_16x16x32_bf16 v[0:3], v[156:159], v[214:217], v[0:3]
	s_setprio 0
	s_barrier
	s_cbranch_scc0 .LBB0_733
	s_and_b64 vcc, exec, s[44:45]
	s_cbranch_vccz .LBB0_736
	s_barrier

; #define PG8_STAGE(bufoff, gbase, voff) do { _Pragma("unroll") for (int _i = 0; _i < 2; ++_i) \
;         __builtin_amdgcn_global_load_lds((const unsigned*)((const char*)(gbase) + (voff)[_i]), (PG8_LAS unsigned*)(lds + (bufoff) + ldsw + _i * 8192), 16, 0, 0); } while (0)
; #define PG8_LDA(dst, b, h) do { _Pragma("unroll") for (int m = 0; m < 4; ++m) _Pragma("unroll") for (int k = 0; k < 2; ++k) dst[m][k] = *(const PG8_LAS bf16x8*)(lds + PG8_SA(b, h) + aoff + m * 2048 + k * 1024); } while (0)
; template <class Epi, class Sched, bool ALIGN_EPI = false, bool SP2 = false>
; __device__ __forceinline__ void gemm_phase(PG8_LAS unsigned char* lds, const Gemm g, const Sched& S, const Epi& E) {
;     ...
;         const bool has_next = S.next(ui + 1, nxt);
;         const char* nA = has_next ? (const char*)g.A + (size_t)nxt.pm * tstepA : cA; const char* nB = has_next ? (const char*)g.Bt + (size_t)nxt.pn * tstep : cB;
;         for (int t = 0; t < nt; t += 2) {
;             const bool last = (t == nt - 2);
;             const char* a1 = cA + (size_t)(t + 1) * kstepA;
;             const char* a2 = last ? nA : cA + (size_t)(t + 2) * kstepA; const char* b2 = last ? nB : cB + (size_t)(t + 2) * kstep;
;             const char* a3 = a2 + kstepA; const char* b3 = b2 + kstep;
;             if (last && has_next) S.a_ready(nxt);
;             if constexpr (SP2) {
;             PG8_LDB(B0, 0, 0); PG8_LDB(B1, 0, 1); PG8_SCHED; PG8_LDA(At, 0, 0); PG8_STAGE(PG8_SA(1, 1), a1 + hstepA, voffA);
;             PG8_WAIT_V(8); PG8_WAIT_L(0); PG8_BAR; PG8_MMA(0, 0, At, B0); PG8_MMA(0, 1, At, B1); PG8_BAR; PG8_SCHED;
;             PG8_LDA(At, 0, 1); PG8_STAGE(PG8_SB(0, 0), b2, voffB); PG8_STAGE(PG8_SB(0, 1), b2 + hstep, voffB); PG8_STAGE(PG8_SA(0, 0), a2, voffA);
;             PG8_WAIT_V(8); PG8_WAIT_L(0); PG8_BAR; PG8_MMA(1, 0, At, B0); PG8_MMA(1, 1, At, B1); PG8_BAR; PG8_SCHED;
;             PG8_LDB(B0, 1, 0); PG8_LDB(B1, 1, 1); PG8_SCHED; PG8_LDA(At, 1, 0); PG8_STAGE(PG8_SA(0, 1), a2 + hstepA, voffA);
;             PG8_WAIT_V(8); PG8_WAIT_L(0); PG8_BAR; PG8_MMA(0, 0, At, B0); PG8_MMA(0, 1, At, B1); PG8_BAR; PG8_SCHED;
;             PG8_LDA(At, 1, 1); PG8_STAGE(PG8_SB(1, 0), b3, voffB); PG8_STAGE(PG8_SB(1, 1), b3 + hstep, voffB); PG8_STAGE(PG8_SA(1, 0), a3, voffA);
;             PG8_WAIT_V(8); PG8_WAIT_L(0); PG8_BAR; PG8_MMA(1, 0, At, B0); PG8_MMA(1, 1, At, B1); PG8_BAR; PG8_SCHED;
.LBB0_835:
	s_ashr_i32 s43, s42, 31
	s_lshl_b64 s[44:45], s[42:43], 19
	s_add_u32 s44, s20, s44
	s_addc_u32 s45, s21, s45
	s_and_b64 s[46:47], s[38:39], exec
	s_cselect_b32 s43, s45, s51
	s_cselect_b32 s61, s44, s50
	s_ashr_i32 s41, s40, 31
	s_lshl_b64 s[46:47], s[40:41], 19
	s_add_u32 s46, s2, s46
	s_addc_u32 s47, s3, s47
	s_and_b64 s[52:53], s[38:39], exec
	s_cselect_b32 s41, s47, s49
	s_cselect_b32 s64, s46, s48
	s_add_u32 s65, s48, 0x100
	s_addc_u32 s69, s49, 0
	s_add_u32 s48, s50, 0x40080
	s_addc_u32 s49, s51, 0
	s_mov_b32 s73, -2
	s_add_u32 s50, s48, 0xfffc0080
	s_addc_u32 s51, s49, -1
	s_add_i32 s74, 0, 0x10000
	s_cmp_eq_u32 s73, 12
	s_cselect_b32 s53, s43, s51
	s_cselect_b32 s52, s61, s50
	s_cselect_b32 s51, s41, s69
	s_cselect_b32 s50, s64, s65
	s_add_i32 s80, 0, 0x14000
	s_add_i32 m0, s7, 0xc000
	v_lshl_add_u64 v[178:179], s[48:49], 0, v[140:141]
	global_load_lds_dwordx4 v[178:179], off
	v_lshl_add_u64 v[178:179], s[48:49], 0, v[138:139]
	s_add_i32 m0, s7, 0xe000
	s_nop 0
	global_load_lds_dwordx4 v[178:179], off
	s_waitcnt vmcnt(8)
	s_waitcnt lgkmcnt(0)
	s_barrier
	s_setprio 1
	v_mfma_f32_16x16x32_bf16 v[124:127], v[144:147], v[192:195], 0
	v_mfma_f32_16x16x32_bf16 v[116:119], v[152:155], v[192:195], 0
	v_mfma_f32_16x16x32_bf16 v[108:111], v[144:147], v[200:203], 0
	v_mfma_f32_16x16x32_bf16 v[100:103], v[152:155], v[200:203], 0
	v_mfma_f32_16x16x32_bf16 v[92:95], v[144:147], v[208:211], 0
	v_mfma_f32_16x16x32_bf16 v[84:87], v[152:155], v[208:211], 0
	v_mfma_f32_16x16x32_bf16 v[76:79], v[144:147], v[216:219], 0
	v_mfma_f32_16x16x32_bf16 v[68:71], v[152:155], v[216:219], 0
	v_mfma_f32_16x16x32_bf16 v[124:127], v[148:151], v[196:199], v[124:127]
	v_mfma_f32_16x16x32_bf16 v[116:119], v[156:159], v[196:199], v[116:119]
	v_mfma_f32_16x16x32_bf16 v[108:111], v[148:151], v[204:207], v[108:111]
	v_mfma_f32_16x16x32_bf16 v[100:103], v[156:159], v[204:207], v[100:103]
	v_mfma_f32_16x16x32_bf16 v[92:95], v[148:151], v[212:215], v[92:95]
	v_mfma_f32_16x16x32_bf16 v[84:87], v[156:159], v[212:215], v[84:87]
	v_mfma_f32_16x16x32_bf16 v[76:79], v[148:151], v[220:223], v[76:79]
	v_mfma_f32_16x16x32_bf16 v[68:71], v[156:159], v[220:223], v[68:71]
	s_setprio 0
	s_setprio 1
	v_mfma_f32_16x16x32_bf16 v[120:123], v[160:163], v[192:195], 0
	v_mfma_f32_16x16x32_bf16 v[112:115], v[170:173], v[192:195], 0
	v_mfma_f32_16x16x32_bf16 v[104:107], v[160:163], v[200:203], 0
	v_mfma_f32_16x16x32_bf16 v[96:99], v[170:173], v[200:203], 0
	v_mfma_f32_16x16x32_bf16 v[88:91], v[160:163], v[208:211], 0
	v_mfma_f32_16x16x32_bf16 v[80:83], v[170:173], v[208:211], 0
	v_mfma_f32_16x16x32_bf16 v[72:75], v[160:163], v[216:219], 0
	v_mfma_f32_16x16x32_bf16 v[64:67], v[170:173], v[216:219], 0
	v_mfma_f32_16x16x32_bf16 v[120:123], v[164:167], v[196:199], v[120:123]
	v_mfma_f32_16x16x32_bf16 v[112:115], v[188:191], v[196:199], v[112:115]
	v_mfma_f32_16x16x32_bf16 v[104:107], v[164:167], v[204:207], v[104:107]
	v_mfma_f32_16x16x32_bf16 v[96:99], v[188:191], v[204:207], v[96:99]
	v_mfma_f32_16x16x32_bf16 v[88:91], v[164:167], v[212:215], v[88:91]
	s_add_i32 s74, s74, s6
	v_mfma_f32_16x16x32_bf16 v[80:83], v[188:191], v[212:215], v[80:83]
	v_lshl_add_u64 v[178:179], s[50:51], 0, v[132:133]
	v_mfma_f32_16x16x32_bf16 v[72:75], v[164:167], v[220:223], v[72:75]
	s_mov_b32 m0, s74
	v_mfma_f32_16x16x32_bf16 v[64:67], v[188:191], v[220:223], v[64:67]
	s_setprio 0
	s_barrier
	ds_read_b128 v[192:195], v143 offset:16384
	ds_read_b128 v[196:199], v143 offset:17408
	ds_read_b128 v[200:203], v143 offset:18432
	ds_read_b128 v[204:207], v143 offset:19456
	ds_read_b128 v[208:211], v143 offset:20480
	ds_read_b128 v[212:215], v143 offset:21504
	ds_read_b128 v[216:219], v143 offset:22528
	ds_read_b128 v[220:223], v143 offset:23552
	global_load_lds_dwordx4 v[178:179], off
	s_add_i32 m0, s74, 0x2000
	s_add_u32 s74, s50, 0x40000
	v_lshl_add_u64 v[224:225], s[50:51], 0, v[128:129]
	s_addc_u32 s75, s51, 0
	s_add_i32 s80, s80, s6
	global_load_lds_dwordx4 v[224:225], off
	v_lshl_add_u64 v[234:235], s[74:75], 0, v[132:133]
	s_mov_b32 m0, s80
	v_lshl_add_u64 v[236:237], s[52:53], 0, v[130:131]
	global_load_lds_dwordx4 v[234:235], off
	v_lshl_add_u64 v[234:235], s[74:75], 0, v[128:129]
	s_add_i32 m0, s80, 0x2000
	s_nop 0
	global_load_lds_dwordx4 v[234:235], off
	v_lshl_add_u64 v[234:235], s[52:53], 0, v[134:135]
	s_mov_b32 m0, s7
	s_nop 0
	global_load_lds_dwordx4 v[234:235], off
	s_mov_b32 m0, s34
	s_nop 0
	global_load_lds_dwordx4 v[236:237], off
	s_waitcnt vmcnt(8)
	s_waitcnt lgkmcnt(0)
	s_barrier
; #define PG8_STAGE(bufoff, gbase, voff) do { _Pragma("unroll") for (int _i = 0; _i < 2; ++_i) \
;         __builtin_amdgcn_global_load_lds((const unsigned*)((const char*)(gbase) + (voff)[_i]), (PG8_LAS unsigned*)(lds + (bufoff) + ldsw + _i * 8192), 16, 0, 0); } while (0)
; #define PG8_LDA(dst, b, h) do { _Pragma("unroll") for (int m = 0; m < 4; ++m) _Pragma("unroll") for (int k = 0; k < 2; ++k) dst[m][k] = *(const PG8_LAS bf16x8*)(lds + PG8_SA(b, h) + aoff + m * 2048 + k * 1024); } while (0)
; #define PG8_LDB(dst, b, h) do { _Pragma("unroll") for (int n = 0; n < 2; ++n) _Pragma("unroll") for (int k = 0; k < 2; ++k) dst[n][k] = *(const PG8_LAS bf16x8*)(lds + PG8_SB(b, h) + boff + n * 2048 + k * 1024); } while (0)
; #define PG8_MMA(ai, bj, At, Bt) do { __builtin_amdgcn_s_setprio(1); _Pragma("unroll") for (int m = 0; m < 4; ++m) _Pragma("unroll") for (int n = 0; n < 2; ++n) _Pragma("unroll") for (int k = 0; k < 2; ++k) \
;         acc[ai][bj][m][n] = __builtin_amdgcn_mfma_f32_16x16x32_bf16(Bt[n][k], At[m][k], acc[ai][bj][m][n], 0, 0, 0); __builtin_amdgcn_s_setprio(0); } while (0)
; #define PG8_WAIT_V(n) asm volatile("s_waitcnt vmcnt(" #n ")" ::: "memory")
; template <class Epi, class Sched, bool ALIGN_EPI = false, bool SP2 = false>
; __device__ __forceinline__ void gemm_phase(PG8_LAS unsigned char* lds, const Gemm g, const Sched& S, const Epi& E) {
;     ...
;             PG8_LDB(B0, 0, 0); PG8_LDB(B1, 0, 1); PG8_SCHED; PG8_LDA(At, 0, 0); PG8_STAGE(PG8_SA(1, 1), a1 + hstepA, voffA);
;             PG8_WAIT_V(8); PG8_WAIT_L(0); PG8_BAR; PG8_MMA(0, 0, At, B0); PG8_MMA(0, 1, At, B1); PG8_BAR; PG8_SCHED;
;             PG8_LDA(At, 0, 1); PG8_STAGE(PG8_SB(0, 0), b2, voffB); PG8_STAGE(PG8_SB(0, 1), b2 + hstep, voffB); PG8_STAGE(PG8_SA(0, 0), a2, voffA);
;             PG8_WAIT_V(8); PG8_WAIT_L(0); PG8_BAR; PG8_MMA(1, 0, At, B0); PG8_MMA(1, 1, At, B1); PG8_BAR; PG8_SCHED;
;             PG8_LDB(B0, 1, 0); PG8_LDB(B1, 1, 1); PG8_SCHED; PG8_LDA(At, 1, 0); PG8_STAGE(PG8_SA(0, 1), a2 + hstepA, voffA);
;             PG8_WAIT_V(8); PG8_WAIT_L(0); PG8_BAR; PG8_MMA(0, 0, At, B0); PG8_MMA(0, 1, At, B1); PG8_BAR; PG8_SCHED;
;             PG8_LDA(At, 1, 1); PG8_STAGE(PG8_SB(1, 0), b3, voffB); PG8_STAGE(PG8_SB(1, 1), b3 + hstep, voffB); PG8_STAGE(PG8_SA(1, 0), a3, voffA);
;             PG8_WAIT_V(8); PG8_WAIT_L(0); PG8_BAR; PG8_MMA(1, 0, At, B0); PG8_MMA(1, 1, At, B1); PG8_BAR; PG8_SCHED;
	s_setprio 1
	v_mfma_f32_16x16x32_bf16 v[60:63], v[144:147], v[192:195], 0
	v_mfma_f32_16x16x32_bf16 v[52:55], v[152:155], v[192:195], 0
	v_mfma_f32_16x16x32_bf16 v[44:47], v[144:147], v[200:203], 0
	v_mfma_f32_16x16x32_bf16 v[36:39], v[152:155], v[200:203], 0
	v_mfma_f32_16x16x32_bf16 v[28:31], v[144:147], v[208:211], 0
	v_mfma_f32_16x16x32_bf16 v[20:23], v[152:155], v[208:211], 0
	v_mfma_f32_16x16x32_bf16 v[12:15], v[144:147], v[216:219], 0
	v_mfma_f32_16x16x32_bf16 v[4:7], v[152:155], v[216:219], 0
	v_mfma_f32_16x16x32_bf16 v[60:63], v[148:151], v[196:199], v[60:63]
	v_mfma_f32_16x16x32_bf16 v[52:55], v[156:159], v[196:199], v[52:55]
	v_mfma_f32_16x16x32_bf16 v[44:47], v[148:151], v[204:207], v[44:47]
	v_mfma_f32_16x16x32_bf16 v[36:39], v[156:159], v[204:207], v[36:39]
	v_mfma_f32_16x16x32_bf16 v[28:31], v[148:151], v[212:215], v[28:31]
	v_mfma_f32_16x16x32_bf16 v[20:23], v[156:159], v[212:215], v[20:23]
	v_mfma_f32_16x16x32_bf16 v[12:15], v[148:151], v[220:223], v[12:15]
	v_mfma_f32_16x16x32_bf16 v[4:7], v[156:159], v[220:223], v[4:7]
	s_setprio 0
	s_setprio 1
	v_mfma_f32_16x16x32_bf16 v[56:59], v[160:163], v[192:195], 0
	v_mfma_f32_16x16x32_bf16 v[48:51], v[170:173], v[192:195], 0
	v_mfma_f32_16x16x32_bf16 v[40:43], v[160:163], v[200:203], 0
	v_mfma_f32_16x16x32_bf16 v[32:35], v[170:173], v[200:203], 0
	v_mfma_f32_16x16x32_bf16 v[24:27], v[160:163], v[208:211], 0
	v_mfma_f32_16x16x32_bf16 v[16:19], v[170:173], v[208:211], 0
	v_mfma_f32_16x16x32_bf16 v[8:11], v[160:163], v[216:219], 0
	v_mfma_f32_16x16x32_bf16 v[0:3], v[170:173], v[216:219], 0
	v_mfma_f32_16x16x32_bf16 v[56:59], v[164:167], v[196:199], v[56:59]
	v_mfma_f32_16x16x32_bf16 v[48:51], v[188:191], v[196:199], v[48:51]
	v_mfma_f32_16x16x32_bf16 v[40:43], v[164:167], v[204:207], v[40:43]
	v_mfma_f32_16x16x32_bf16 v[32:35], v[188:191], v[204:207], v[32:35]
	s_add_i32 s74, 0, 0x18000
	v_mfma_f32_16x16x32_bf16 v[24:27], v[164:167], v[212:215], v[24:27]
	s_add_i32 s75, 0, 0x1c000
	v_mfma_f32_16x16x32_bf16 v[16:19], v[188:191], v[212:215], v[16:19]
	v_add_u32_e32 v240, s74, v142
	v_mfma_f32_16x16x32_bf16 v[8:11], v[164:167], v[220:223], v[8:11]
	v_add_u32_e32 v241, s75, v142
	v_mfma_f32_16x16x32_bf16 v[0:3], v[188:191], v[220:223], v[0:3]
	s_setprio 0
	s_barrier
	ds_read_b128 v[144:147], v240
	ds_read_b128 v[148:151], v240 offset:1024
	ds_read_b128 v[152:155], v240 offset:2048
	ds_read_b128 v[156:159], v240 offset:3072
	ds_read_b128 v[160:163], v241
	ds_read_b128 v[164:167], v241 offset:1024
	ds_read_b128 v[170:173], v241 offset:2048
	ds_read_b128 v[188:191], v241 offset:3072
	ds_read_b128 v[192:195], v143 offset:32768
	ds_read_b128 v[196:199], v143 offset:33792
	ds_read_b128 v[200:203], v143 offset:34816
	ds_read_b128 v[204:207], v143 offset:35840
	ds_read_b128 v[208:211], v143 offset:36864
	ds_read_b128 v[212:215], v143 offset:37888
	ds_read_b128 v[216:219], v143 offset:38912
	ds_read_b128 v[220:223], v143 offset:39936
	s_add_u32 s52, s52, 0x40000
	s_addc_u32 s53, s53, 0
	s_mov_b32 m0, s35
	v_lshl_add_u64 v[238:239], s[52:53], 0, v[134:135]
	global_load_lds_dwordx4 v[238:239], off
	v_lshl_add_u64 v[238:239], s[52:53], 0, v[130:131]
	s_mov_b32 m0, s54
	s_nop 0
	global_load_lds_dwordx4 v[238:239], off
	s_waitcnt vmcnt(8)
	s_waitcnt lgkmcnt(0)
	s_barrier
	s_setprio 1
	v_mfma_f32_16x16x32_bf16 v[124:127], v[144:147], v[192:195], v[124:127]
	v_mfma_f32_16x16x32_bf16 v[116:119], v[152:155], v[192:195], v[116:119]
	v_mfma_f32_16x16x32_bf16 v[108:111], v[144:147], v[200:203], v[108:111]
	v_mfma_f32_16x16x32_bf16 v[100:103], v[152:155], v[200:203], v[100:103]
	v_mfma_f32_16x16x32_bf16 v[92:95], v[144:147], v[208:211], v[92:95]
	v_mfma_f32_16x16x32_bf16 v[84:87], v[152:155], v[208:211], v[84:87]
	v_mfma_f32_16x16x32_bf16 v[76:79], v[144:147], v[216:219], v[76:79]
	v_mfma_f32_16x16x32_bf16 v[68:71], v[152:155], v[216:219], v[68:71]
	v_mfma_f32_16x16x32_bf16 v[124:127], v[148:151], v[196:199], v[124:127]
	v_mfma_f32_16x16x32_bf16 v[116:119], v[156:159], v[196:199], v[116:119]
	v_mfma_f32_16x16x32_bf16 v[108:111], v[148:151], v[204:207], v[108:111]
	v_mfma_f32_16x16x32_bf16 v[100:103], v[156:159], v[204:207], v[100:103]
	v_mfma_f32_16x16x32_bf16 v[92:95], v[148:151], v[212:215], v[92:95]
	v_mfma_f32_16x16x32_bf16 v[84:87], v[156:159], v[212:215], v[84:87]
	v_mfma_f32_16x16x32_bf16 v[76:79], v[148:151], v[220:223], v[76:79]
	v_mfma_f32_16x16x32_bf16 v[68:71], v[156:159], v[220:223], v[68:71]
	s_setprio 0
	s_setprio 1
	v_mfma_f32_16x16x32_bf16 v[120:123], v[160:163], v[192:195], v[120:123]
	v_mfma_f32_16x16x32_bf16 v[112:115], v[170:173], v[192:195], v[112:115]
	v_mfma_f32_16x16x32_bf16 v[104:107], v[160:163], v[200:203], v[104:107]
	v_mfma_f32_16x16x32_bf16 v[96:99], v[170:173], v[200:203], v[96:99]
	v_mfma_f32_16x16x32_bf16 v[88:91], v[160:163], v[208:211], v[88:91]
	v_mfma_f32_16x16x32_bf16 v[80:83], v[170:173], v[208:211], v[80:83]
	v_mfma_f32_16x16x32_bf16 v[72:75], v[160:163], v[216:219], v[72:75]
	v_mfma_f32_16x16x32_bf16 v[64:67], v[170:173], v[216:219], v[64:67]
	v_mfma_f32_16x16x32_bf16 v[120:123], v[164:167], v[196:199], v[120:123]
	v_mfma_f32_16x16x32_bf16 v[112:115], v[188:191], v[196:199], v[112:115]
	v_mfma_f32_16x16x32_bf16 v[104:107], v[164:167], v[204:207], v[104:107]
	v_mfma_f32_16x16x32_bf16 v[96:99], v[188:191], v[204:207], v[96:99]
	v_mfma_f32_16x16x32_bf16 v[88:91], v[164:167], v[212:215], v[88:91]
	s_add_i32 s52, s74, s6
	v_mfma_f32_16x16x32_bf16 v[80:83], v[188:191], v[212:215], v[80:83]
	v_lshl_add_u64 v[178:179], v[178:179], 0, s[30:31]
	v_mfma_f32_16x16x32_bf16 v[72:75], v[164:167], v[220:223], v[72:75]
	s_mov_b32 m0, s52
	v_mfma_f32_16x16x32_bf16 v[64:67], v[188:191], v[220:223], v[64:67]
	s_setprio 0
	s_barrier
; #define PG8_STAGE(bufoff, gbase, voff) do { _Pragma("unroll") for (int _i = 0; _i < 2; ++_i) \
;         __builtin_amdgcn_global_load_lds((const unsigned*)((const char*)(gbase) + (voff)[_i]), (PG8_LAS unsigned*)(lds + (bufoff) + ldsw + _i * 8192), 16, 0, 0); } while (0)
; #define PG8_LDA(dst, b, h) do { _Pragma("unroll") for (int m = 0; m < 4; ++m) _Pragma("unroll") for (int k = 0; k < 2; ++k) dst[m][k] = *(const PG8_LAS bf16x8*)(lds + PG8_SA(b, h) + aoff + m * 2048 + k * 1024); } while (0)
; #define PG8_LDB(dst, b, h) do { _Pragma("unroll") for (int n = 0; n < 2; ++n) _Pragma("unroll") for (int k = 0; k < 2; ++k) dst[n][k] = *(const PG8_LAS bf16x8*)(lds + PG8_SB(b, h) + boff + n * 2048 + k * 1024); } while (0)
; #define PG8_MMA(ai, bj, At, Bt) do { __builtin_amdgcn_s_setprio(1); _Pragma("unroll") for (int m = 0; m < 4; ++m) _Pragma("unroll") for (int n = 0; n < 2; ++n) _Pragma("unroll") for (int k = 0; k < 2; ++k) \
;         acc[ai][bj][m][n] = __builtin_amdgcn_mfma_f32_16x16x32_bf16(Bt[n][k], At[m][k], acc[ai][bj][m][n], 0, 0, 0); __builtin_amdgcn_s_setprio(0); } while (0)
; #define PG8_WAIT_V(n) asm volatile("s_waitcnt vmcnt(" #n ")" ::: "memory")
; template <class Epi, class Sched, bool ALIGN_EPI = false, bool SP2 = false>
; __device__ __forceinline__ void gemm_phase(PG8_LAS unsigned char* lds, const Gemm g, const Sched& S, const Epi& E) {
;     ...
;             PG8_LDB(B0, 0, 0); PG8_LDB(B1, 0, 1); PG8_SCHED; PG8_LDA(At, 0, 0); PG8_STAGE(PG8_SA(1, 1), a1 + hstepA, voffA);
;             PG8_WAIT_V(8); PG8_WAIT_L(0); PG8_BAR; PG8_MMA(0, 0, At, B0); PG8_MMA(0, 1, At, B1); PG8_BAR; PG8_SCHED;
;             PG8_LDA(At, 0, 1); PG8_STAGE(PG8_SB(0, 0), b2, voffB); PG8_STAGE(PG8_SB(0, 1), b2 + hstep, voffB); PG8_STAGE(PG8_SA(0, 0), a2, voffA);
;             PG8_WAIT_V(8); PG8_WAIT_L(0); PG8_BAR; PG8_MMA(1, 0, At, B0); PG8_MMA(1, 1, At, B1); PG8_BAR; PG8_SCHED;
;             PG8_LDB(B0, 1, 0); PG8_LDB(B1, 1, 1); PG8_SCHED; PG8_LDA(At, 1, 0); PG8_STAGE(PG8_SA(0, 1), a2 + hstepA, voffA);
;             PG8_WAIT_V(8); PG8_WAIT_L(0); PG8_BAR; PG8_MMA(0, 0, At, B0); PG8_MMA(0, 1, At, B1); PG8_BAR; PG8_SCHED;
;             PG8_LDA(At, 1, 1); PG8_STAGE(PG8_SB(1, 0), b3, voffB); PG8_STAGE(PG8_SB(1, 1), b3 + hstep, voffB); PG8_STAGE(PG8_SA(1, 0), a3, voffA);
;             PG8_WAIT_V(8); PG8_WAIT_L(0); PG8_BAR; PG8_MMA(1, 0, At, B0); PG8_MMA(1, 1, At, B1); PG8_BAR; PG8_SCHED;
	ds_read_b128 v[192:195], v143 offset:49152
	ds_read_b128 v[196:199], v143 offset:50176
	ds_read_b128 v[200:203], v143 offset:51200
	ds_read_b128 v[204:207], v143 offset:52224
	ds_read_b128 v[208:211], v143 offset:53248
	ds_read_b128 v[212:215], v143 offset:54272
	ds_read_b128 v[216:219], v143 offset:55296
	ds_read_b128 v[220:223], v143 offset:56320
	global_load_lds_dwordx4 v[178:179], off
	s_add_i32 m0, s52, 0x2000
	s_add_u32 s50, s50, 0x40080
	v_lshl_add_u64 v[178:179], v[224:225], 0, s[30:31]
	s_addc_u32 s51, s51, 0
	s_add_i32 s52, s75, s6
	global_load_lds_dwordx4 v[178:179], off
	v_lshl_add_u64 v[178:179], s[50:51], 0, v[132:133]
	s_mov_b32 m0, s52
	s_nop 0
	global_load_lds_dwordx4 v[178:179], off
	v_lshl_add_u64 v[178:179], s[50:51], 0, v[128:129]
	s_add_i32 m0, s52, 0x2000
	s_nop 0
	global_load_lds_dwordx4 v[178:179], off
	v_lshl_add_u64 v[178:179], v[234:235], 0, s[30:31]
	s_mov_b32 m0, s55
	s_nop 0
	global_load_lds_dwordx4 v[178:179], off
	v_lshl_add_u64 v[178:179], v[236:237], 0, s[30:31]
	s_mov_b32 m0, s56
	s_nop 0
	global_load_lds_dwordx4 v[178:179], off
	s_waitcnt vmcnt(8)
	s_waitcnt lgkmcnt(0)
	s_barrier
	s_setprio 1
	v_mfma_f32_16x16x32_bf16 v[60:63], v[144:147], v[192:195], v[60:63]
	v_mfma_f32_16x16x32_bf16 v[52:55], v[152:155], v[192:195], v[52:55]
	v_mfma_f32_16x16x32_bf16 v[44:47], v[144:147], v[200:203], v[44:47]
	v_mfma_f32_16x16x32_bf16 v[36:39], v[152:155], v[200:203], v[36:39]
	v_mfma_f32_16x16x32_bf16 v[28:31], v[144:147], v[208:211], v[28:31]
	v_mfma_f32_16x16x32_bf16 v[20:23], v[152:155], v[208:211], v[20:23]
	v_mfma_f32_16x16x32_bf16 v[12:15], v[144:147], v[216:219], v[12:15]
	v_mfma_f32_16x16x32_bf16 v[4:7], v[152:155], v[216:219], v[4:7]
	v_mfma_f32_16x16x32_bf16 v[60:63], v[148:151], v[196:199], v[60:63]
	v_mfma_f32_16x16x32_bf16 v[52:55], v[156:159], v[196:199], v[52:55]
	v_mfma_f32_16x16x32_bf16 v[44:47], v[148:151], v[204:207], v[44:47]
	v_mfma_f32_16x16x32_bf16 v[36:39], v[156:159], v[204:207], v[36:39]
	v_mfma_f32_16x16x32_bf16 v[28:31], v[148:151], v[212:215], v[28:31]
	v_mfma_f32_16x16x32_bf16 v[20:23], v[156:159], v[212:215], v[20:23]
	v_mfma_f32_16x16x32_bf16 v[12:15], v[148:151], v[220:223], v[12:15]
	v_mfma_f32_16x16x32_bf16 v[4:7], v[156:159], v[220:223], v[4:7]
	s_add_i32 s73, s73, 2
	s_setprio 0
	s_setprio 1
	v_mfma_f32_16x16x32_bf16 v[56:59], v[160:163], v[192:195], v[56:59]
	s_add_u32 s65, s65, 0x100
	v_mfma_f32_16x16x32_bf16 v[48:51], v[170:173], v[192:195], v[48:51]
	s_addc_u32 s69, s69, 0
	v_mfma_f32_16x16x32_bf16 v[40:43], v[160:163], v[200:203], v[40:43]
	s_add_u32 s48, s48, 0x100
	v_mfma_f32_16x16x32_bf16 v[32:35], v[170:173], v[200:203], v[32:35]
	s_addc_u32 s49, s49, 0
	v_mfma_f32_16x16x32_bf16 v[24:27], v[160:163], v[208:211], v[24:27]
	s_add_u32 s50, s48, 0xfffc0080
	v_mfma_f32_16x16x32_bf16 v[16:19], v[170:173], v[208:211], v[16:19]
	s_addc_u32 s51, s49, -1
	v_mfma_f32_16x16x32_bf16 v[8:11], v[160:163], v[216:219], v[8:11]
	s_add_i32 s74, 0, 0x10000
	v_mfma_f32_16x16x32_bf16 v[0:3], v[170:173], v[216:219], v[0:3]
	s_cmp_eq_u32 s73, 12
	v_mfma_f32_16x16x32_bf16 v[56:59], v[164:167], v[196:199], v[56:59]
	s_cselect_b32 s53, s43, s51
	v_mfma_f32_16x16x32_bf16 v[48:51], v[188:191], v[196:199], v[48:51]
	s_cselect_b32 s52, s61, s50
	v_mfma_f32_16x16x32_bf16 v[40:43], v[164:167], v[204:207], v[40:43]
	s_cselect_b32 s51, s41, s69
	v_mfma_f32_16x16x32_bf16 v[32:35], v[188:191], v[204:207], v[32:35]
	s_cselect_b32 s50, s64, s65
	v_mfma_f32_16x16x32_bf16 v[24:27], v[164:167], v[212:215], v[24:27]
	s_add_i32 s80, 0, 0x14000
	v_mfma_f32_16x16x32_bf16 v[16:19], v[188:191], v[212:215], v[16:19]
	v_add_u32_e32 v242, s74, v142
	v_mfma_f32_16x16x32_bf16 v[8:11], v[164:167], v[220:223], v[8:11]
	v_add_u32_e32 v178, s80, v142
	v_mfma_f32_16x16x32_bf16 v[0:3], v[188:191], v[220:223], v[0:3]
	s_setprio 0
	s_barrier
.LBB0_836:
	ds_read_b128 v[144:147], v242
	ds_read_b128 v[148:151], v242 offset:1024
	ds_read_b128 v[152:155], v242 offset:2048
	ds_read_b128 v[156:159], v242 offset:3072
	ds_read_b128 v[160:163], v178
	ds_read_b128 v[164:167], v178 offset:1024
	ds_read_b128 v[170:173], v178 offset:2048
	ds_read_b128 v[188:191], v178 offset:3072
	ds_read_b128 v[192:195], v143
	ds_read_b128 v[196:199], v143 offset:1024
	ds_read_b128 v[200:203], v143 offset:2048
	ds_read_b128 v[204:207], v143 offset:3072
	ds_read_b128 v[208:211], v143 offset:4096
	ds_read_b128 v[212:215], v143 offset:5120
	ds_read_b128 v[216:219], v143 offset:6144
	ds_read_b128 v[220:223], v143 offset:7168
	s_add_i32 m0, s7, 0xc000
	v_lshl_add_u64 v[178:179], s[48:49], 0, v[140:141]
	global_load_lds_dwordx4 v[178:179], off
	v_lshl_add_u64 v[178:179], s[48:49], 0, v[138:139]
	s_add_i32 m0, s7, 0xe000
	s_nop 0
	global_load_lds_dwordx4 v[178:179], off
	s_waitcnt vmcnt(8)
	s_waitcnt lgkmcnt(0)
	s_barrier
; #define PG8_STAGE(bufoff, gbase, voff) do { _Pragma("unroll") for (int _i = 0; _i < 2; ++_i) \
;         __builtin_amdgcn_global_load_lds((const unsigned*)((const char*)(gbase) + (voff)[_i]), (PG8_LAS unsigned*)(lds + (bufoff) + ldsw + _i * 8192), 16, 0, 0); } while (0)
; #define PG8_LDA(dst, b, h) do { _Pragma("unroll") for (int m = 0; m < 4; ++m) _Pragma("unroll") for (int k = 0; k < 2; ++k) dst[m][k] = *(const PG8_LAS bf16x8*)(lds + PG8_SA(b, h) + aoff + m * 2048 + k * 1024); } while (0)
; #define PG8_LDB(dst, b, h) do { _Pragma("unroll") for (int n = 0; n < 2; ++n) _Pragma("unroll") for (int k = 0; k < 2; ++k) dst[n][k] = *(const PG8_LAS bf16x8*)(lds + PG8_SB(b, h) + boff + n * 2048 + k * 1024); } while (0)
; #define PG8_MMA(ai, bj, At, Bt) do { __builtin_amdgcn_s_setprio(1); _Pragma("unroll") for (int m = 0; m < 4; ++m) _Pragma("unroll") for (int n = 0; n < 2; ++n) _Pragma("unroll") for (int k = 0; k < 2; ++k) \
;         acc[ai][bj][m][n] = __builtin_amdgcn_mfma_f32_16x16x32_bf16(Bt[n][k], At[m][k], acc[ai][bj][m][n], 0, 0, 0); __builtin_amdgcn_s_setprio(0); } while (0)
; #define PG8_WAIT_V(n) asm volatile("s_waitcnt vmcnt(" #n ")" ::: "memory")
; template <class Epi, class Sched, bool ALIGN_EPI = false, bool SP2 = false>
; __device__ __forceinline__ void gemm_phase(PG8_LAS unsigned char* lds, const Gemm g, const Sched& S, const Epi& E) {
;     ...
;             PG8_LDB(B0, 0, 0); PG8_LDB(B1, 0, 1); PG8_SCHED; PG8_LDA(At, 0, 0); PG8_STAGE(PG8_SA(1, 1), a1 + hstepA, voffA);
;             PG8_WAIT_V(8); PG8_WAIT_L(0); PG8_BAR; PG8_MMA(0, 0, At, B0); PG8_MMA(0, 1, At, B1); PG8_BAR; PG8_SCHED;
;             PG8_LDA(At, 0, 1); PG8_STAGE(PG8_SB(0, 0), b2, voffB); PG8_STAGE(PG8_SB(0, 1), b2 + hstep, voffB); PG8_STAGE(PG8_SA(0, 0), a2, voffA);
;             PG8_WAIT_V(8); PG8_WAIT_L(0); PG8_BAR; PG8_MMA(1, 0, At, B0); PG8_MMA(1, 1, At, B1); PG8_BAR; PG8_SCHED;
;             PG8_LDB(B0, 1, 0); PG8_LDB(B1, 1, 1); PG8_SCHED; PG8_LDA(At, 1, 0); PG8_STAGE(PG8_SA(0, 1), a2 + hstepA, voffA);
;             PG8_WAIT_V(8); PG8_WAIT_L(0); PG8_BAR; PG8_MMA(0, 0, At, B0); PG8_MMA(0, 1, At, B1); PG8_BAR; PG8_SCHED;
;             PG8_LDA(At, 1, 1); PG8_STAGE(PG8_SB(1, 0), b3, voffB); PG8_STAGE(PG8_SB(1, 1), b3 + hstep, voffB); PG8_STAGE(PG8_SA(1, 0), a3, voffA);
;             PG8_WAIT_V(8); PG8_WAIT_L(0); PG8_BAR; PG8_MMA(1, 0, At, B0); PG8_MMA(1, 1, At, B1); PG8_BAR; PG8_SCHED;
	s_setprio 1
	v_mfma_f32_16x16x32_bf16 v[124:127], v[144:147], v[192:195], v[124:127]
	v_mfma_f32_16x16x32_bf16 v[116:119], v[152:155], v[192:195], v[116:119]
	v_mfma_f32_16x16x32_bf16 v[108:111], v[144:147], v[200:203], v[108:111]
	v_mfma_f32_16x16x32_bf16 v[100:103], v[152:155], v[200:203], v[100:103]
	v_mfma_f32_16x16x32_bf16 v[92:95], v[144:147], v[208:211], v[92:95]
	v_mfma_f32_16x16x32_bf16 v[84:87], v[152:155], v[208:211], v[84:87]
	v_mfma_f32_16x16x32_bf16 v[76:79], v[144:147], v[216:219], v[76:79]
	v_mfma_f32_16x16x32_bf16 v[68:71], v[152:155], v[216:219], v[68:71]
	v_mfma_f32_16x16x32_bf16 v[124:127], v[148:151], v[196:199], v[124:127]
	v_mfma_f32_16x16x32_bf16 v[116:119], v[156:159], v[196:199], v[116:119]
	v_mfma_f32_16x16x32_bf16 v[108:111], v[148:151], v[204:207], v[108:111]
	v_mfma_f32_16x16x32_bf16 v[100:103], v[156:159], v[204:207], v[100:103]
	v_mfma_f32_16x16x32_bf16 v[92:95], v[148:151], v[212:215], v[92:95]
	v_mfma_f32_16x16x32_bf16 v[84:87], v[156:159], v[212:215], v[84:87]
	v_mfma_f32_16x16x32_bf16 v[76:79], v[148:151], v[220:223], v[76:79]
	v_mfma_f32_16x16x32_bf16 v[68:71], v[156:159], v[220:223], v[68:71]
	s_setprio 0
	s_setprio 1
	v_mfma_f32_16x16x32_bf16 v[120:123], v[160:163], v[192:195], v[120:123]
	v_mfma_f32_16x16x32_bf16 v[112:115], v[170:173], v[192:195], v[112:115]
	v_mfma_f32_16x16x32_bf16 v[104:107], v[160:163], v[200:203], v[104:107]
	v_mfma_f32_16x16x32_bf16 v[96:99], v[170:173], v[200:203], v[96:99]
	v_mfma_f32_16x16x32_bf16 v[88:91], v[160:163], v[208:211], v[88:91]
	v_mfma_f32_16x16x32_bf16 v[80:83], v[170:173], v[208:211], v[80:83]
	v_mfma_f32_16x16x32_bf16 v[72:75], v[160:163], v[216:219], v[72:75]
	v_mfma_f32_16x16x32_bf16 v[64:67], v[170:173], v[216:219], v[64:67]
	v_mfma_f32_16x16x32_bf16 v[120:123], v[164:167], v[196:199], v[120:123]
	v_mfma_f32_16x16x32_bf16 v[112:115], v[188:191], v[196:199], v[112:115]
	v_mfma_f32_16x16x32_bf16 v[104:107], v[164:167], v[204:207], v[104:107]
	v_mfma_f32_16x16x32_bf16 v[96:99], v[188:191], v[204:207], v[96:99]
	v_mfma_f32_16x16x32_bf16 v[88:91], v[164:167], v[212:215], v[88:91]
	s_add_i32 s74, s74, s6
	v_mfma_f32_16x16x32_bf16 v[80:83], v[188:191], v[212:215], v[80:83]
	v_lshl_add_u64 v[178:179], s[50:51], 0, v[132:133]
	v_mfma_f32_16x16x32_bf16 v[72:75], v[164:167], v[220:223], v[72:75]
	s_mov_b32 m0, s74
	v_mfma_f32_16x16x32_bf16 v[64:67], v[188:191], v[220:223], v[64:67]
	s_setprio 0
	s_barrier
	ds_read_b128 v[192:195], v143 offset:16384
	ds_read_b128 v[196:199], v143 offset:17408
	ds_read_b128 v[200:203], v143 offset:18432
	ds_read_b128 v[204:207], v143 offset:19456
	ds_read_b128 v[208:211], v143 offset:20480
	ds_read_b128 v[212:215], v143 offset:21504
	ds_read_b128 v[216:219], v143 offset:22528
	ds_read_b128 v[220:223], v143 offset:23552
	global_load_lds_dwordx4 v[178:179], off
	s_add_i32 m0, s74, 0x2000
	s_add_u32 s74, s50, 0x40000
	v_lshl_add_u64 v[224:225], s[50:51], 0, v[128:129]
	s_addc_u32 s75, s51, 0
	s_add_i32 s80, s80, s6
	global_load_lds_dwordx4 v[224:225], off
	v_lshl_add_u64 v[234:235], s[74:75], 0, v[132:133]
	s_mov_b32 m0, s80
	v_lshl_add_u64 v[236:237], s[52:53], 0, v[130:131]
	global_load_lds_dwordx4 v[234:235], off
	v_lshl_add_u64 v[234:235], s[74:75], 0, v[128:129]
	s_add_i32 m0, s80, 0x2000
	s_nop 0
	global_load_lds_dwordx4 v[234:235], off
	v_lshl_add_u64 v[234:235], s[52:53], 0, v[134:135]
	s_mov_b32 m0, s7
	s_nop 0
	global_load_lds_dwordx4 v[234:235], off
	s_mov_b32 m0, s34
	s_nop 0
	global_load_lds_dwordx4 v[236:237], off
	s_waitcnt vmcnt(8)
	s_waitcnt lgkmcnt(0)
	s_barrier
	s_setprio 1
	v_mfma_f32_16x16x32_bf16 v[60:63], v[144:147], v[192:195], v[60:63]
	v_mfma_f32_16x16x32_bf16 v[52:55], v[152:155], v[192:195], v[52:55]
	v_mfma_f32_16x16x32_bf16 v[44:47], v[144:147], v[200:203], v[44:47]
	v_mfma_f32_16x16x32_bf16 v[36:39], v[152:155], v[200:203], v[36:39]
	v_mfma_f32_16x16x32_bf16 v[28:31], v[144:147], v[208:211], v[28:31]
	v_mfma_f32_16x16x32_bf16 v[20:23], v[152:155], v[208:211], v[20:23]
	v_mfma_f32_16x16x32_bf16 v[12:15], v[144:147], v[216:219], v[12:15]
	v_mfma_f32_16x16x32_bf16 v[4:7], v[152:155], v[216:219], v[4:7]
	v_mfma_f32_16x16x32_bf16 v[60:63], v[148:151], v[196:199], v[60:63]
	v_mfma_f32_16x16x32_bf16 v[52:55], v[156:159], v[196:199], v[52:55]
	v_mfma_f32_16x16x32_bf16 v[44:47], v[148:151], v[204:207], v[44:47]
	v_mfma_f32_16x16x32_bf16 v[36:39], v[156:159], v[204:207], v[36:39]
	v_mfma_f32_16x16x32_bf16 v[28:31], v[148:151], v[212:215], v[28:31]
	v_mfma_f32_16x16x32_bf16 v[20:23], v[156:159], v[212:215], v[20:23]
	v_mfma_f32_16x16x32_bf16 v[12:15], v[148:151], v[220:223], v[12:15]
	v_mfma_f32_16x16x32_bf16 v[4:7], v[156:159], v[220:223], v[4:7]
	s_setprio 0
	s_setprio 1
	v_mfma_f32_16x16x32_bf16 v[56:59], v[160:163], v[192:195], v[56:59]
	v_mfma_f32_16x16x32_bf16 v[48:51], v[170:173], v[192:195], v[48:51]
	v_mfma_f32_16x16x32_bf16 v[40:43], v[160:163], v[200:203], v[40:43]
	v_mfma_f32_16x16x32_bf16 v[32:35], v[170:173], v[200:203], v[32:35]
	v_mfma_f32_16x16x32_bf16 v[24:27], v[160:163], v[208:211], v[24:27]
	v_mfma_f32_16x16x32_bf16 v[16:19], v[170:173], v[208:211], v[16:19]
	v_mfma_f32_16x16x32_bf16 v[8:11], v[160:163], v[216:219], v[8:11]
	v_mfma_f32_16x16x32_bf16 v[0:3], v[170:173], v[216:219], v[0:3]
	v_mfma_f32_16x16x32_bf16 v[56:59], v[164:167], v[196:199], v[56:59]
	v_mfma_f32_16x16x32_bf16 v[48:51], v[188:191], v[196:199], v[48:51]
	v_mfma_f32_16x16x32_bf16 v[40:43], v[164:167], v[204:207], v[40:43]
	v_mfma_f32_16x16x32_bf16 v[32:35], v[188:191], v[204:207], v[32:35]
	s_add_i32 s74, 0, 0x18000
	v_mfma_f32_16x16x32_bf16 v[24:27], v[164:167], v[212:215], v[24:27]
	s_add_i32 s75, 0, 0x1c000
	v_mfma_f32_16x16x32_bf16 v[16:19], v[188:191], v[212:215], v[16:19]
	v_add_u32_e32 v240, s74, v142
	v_mfma_f32_16x16x32_bf16 v[8:11], v[164:167], v[220:223], v[8:11]
	v_add_u32_e32 v241, s75, v142
	v_mfma_f32_16x16x32_bf16 v[0:3], v[188:191], v[220:223], v[0:3]
	s_setprio 0
	s_barrier
; #define PG8_STAGE(bufoff, gbase, voff) do { _Pragma("unroll") for (int _i = 0; _i < 2; ++_i) \
;         __builtin_amdgcn_global_load_lds((const unsigned*)((const char*)(gbase) + (voff)[_i]), (PG8_LAS unsigned*)(lds + (bufoff) + ldsw + _i * 8192), 16, 0, 0); } while (0)
; #define PG8_LDA(dst, b, h) do { _Pragma("unroll") for (int m = 0; m < 4; ++m) _Pragma("unroll") for (int k = 0; k < 2; ++k) dst[m][k] = *(const PG8_LAS bf16x8*)(lds + PG8_SA(b, h) + aoff + m * 2048 + k * 1024); } while (0)
; #define PG8_LDB(dst, b, h) do { _Pragma("unroll") for (int n = 0; n < 2; ++n) _Pragma("unroll") for (int k = 0; k < 2; ++k) dst[n][k] = *(const PG8_LAS bf16x8*)(lds + PG8_SB(b, h) + boff + n * 2048 + k * 1024); } while (0)
; #define PG8_MMA(ai, bj, At, Bt) do { __builtin_amdgcn_s_setprio(1); _Pragma("unroll") for (int m = 0; m < 4; ++m) _Pragma("unroll") for (int n = 0; n < 2; ++n) _Pragma("unroll") for (int k = 0; k < 2; ++k) \
;         acc[ai][bj][m][n] = __builtin_amdgcn_mfma_f32_16x16x32_bf16(Bt[n][k], At[m][k], acc[ai][bj][m][n], 0, 0, 0); __builtin_amdgcn_s_setprio(0); } while (0)
; #define PG8_WAIT_V(n) asm volatile("s_waitcnt vmcnt(" #n ")" ::: "memory")
; #define PG8_WAIT_L(n) asm volatile("s_waitcnt lgkmcnt(" #n ")" ::: "memory")
; #define PG8_BAR __builtin_amdgcn_s_barrier()
; #define PG8_SCHED __builtin_amdgcn_sched_barrier(0)
; template <class Epi, class Sched, bool ALIGN_EPI = false, bool SP2 = false>
; __device__ __forceinline__ void gemm_phase(PG8_LAS unsigned char* lds, const Gemm g, const Sched& S, const Epi& E) {
;     ...
;             PG8_LDB(B0, 1, 0); PG8_LDB(B1, 1, 1); PG8_SCHED; PG8_LDA(At, 1, 0); PG8_STAGE(PG8_SA(0, 1), a2 + hstepA, voffA);
;             PG8_WAIT_V(8); PG8_WAIT_L(0); PG8_BAR; PG8_MMA(0, 0, At, B0); PG8_MMA(0, 1, At, B1); PG8_BAR; PG8_SCHED;
	ds_read_b128 v[144:147], v240
	ds_read_b128 v[148:151], v240 offset:1024
	ds_read_b128 v[152:155], v240 offset:2048
	ds_read_b128 v[156:159], v240 offset:3072
	ds_read_b128 v[160:163], v241
	ds_read_b128 v[164:167], v241 offset:1024
	ds_read_b128 v[170:173], v241 offset:2048
	ds_read_b128 v[188:191], v241 offset:3072
	ds_read_b128 v[192:195], v143 offset:32768
	ds_read_b128 v[196:199], v143 offset:33792
	ds_read_b128 v[200:203], v143 offset:34816
	ds_read_b128 v[204:207], v143 offset:35840
	ds_read_b128 v[208:211], v143 offset:36864
	ds_read_b128 v[212:215], v143 offset:37888
	ds_read_b128 v[216:219], v143 offset:38912
	ds_read_b128 v[220:223], v143 offset:39936
	s_add_u32 s52, s52, 0x40000
	s_addc_u32 s53, s53, 0
	s_mov_b32 m0, s35
	v_lshl_add_u64 v[238:239], s[52:53], 0, v[134:135]
	global_load_lds_dwordx4 v[238:239], off
	v_lshl_add_u64 v[238:239], s[52:53], 0, v[130:131]
	s_mov_b32 m0, s54
	s_nop 0
	global_load_lds_dwordx4 v[238:239], off
	s_waitcnt vmcnt(8)
	s_waitcnt lgkmcnt(0)
	s_barrier
	s_setprio 1
	v_mfma_f32_16x16x32_bf16 v[124:127], v[144:147], v[192:195], v[124:127]
	v_mfma_f32_16x16x32_bf16 v[116:119], v[152:155], v[192:195], v[116:119]
	v_mfma_f32_16x16x32_bf16 v[108:111], v[144:147], v[200:203], v[108:111]
	v_mfma_f32_16x16x32_bf16 v[100:103], v[152:155], v[200:203], v[100:103]
	v_mfma_f32_16x16x32_bf16 v[92:95], v[144:147], v[208:211], v[92:95]
	v_mfma_f32_16x16x32_bf16 v[84:87], v[152:155], v[208:211], v[84:87]
	v_mfma_f32_16x16x32_bf16 v[76:79], v[144:147], v[216:219], v[76:79]
	v_mfma_f32_16x16x32_bf16 v[68:71], v[152:155], v[216:219], v[68:71]
	v_mfma_f32_16x16x32_bf16 v[124:127], v[148:151], v[196:199], v[124:127]
	v_mfma_f32_16x16x32_bf16 v[116:119], v[156:159], v[196:199], v[116:119]
	v_mfma_f32_16x16x32_bf16 v[108:111], v[148:151], v[204:207], v[108:111]
	v_mfma_f32_16x16x32_bf16 v[100:103], v[156:159], v[204:207], v[100:103]
	v_mfma_f32_16x16x32_bf16 v[92:95], v[148:151], v[212:215], v[92:95]
	v_mfma_f32_16x16x32_bf16 v[84:87], v[156:159], v[212:215], v[84:87]
	v_mfma_f32_16x16x32_bf16 v[76:79], v[148:151], v[220:223], v[76:79]
	v_mfma_f32_16x16x32_bf16 v[68:71], v[156:159], v[220:223], v[68:71]
	s_setprio 0
	s_setprio 1
	v_mfma_f32_16x16x32_bf16 v[120:123], v[160:163], v[192:195], v[120:123]
	v_mfma_f32_16x16x32_bf16 v[112:115], v[170:173], v[192:195], v[112:115]
	v_mfma_f32_16x16x32_bf16 v[104:107], v[160:163], v[200:203], v[104:107]
	v_mfma_f32_16x16x32_bf16 v[96:99], v[170:173], v[200:203], v[96:99]
	v_mfma_f32_16x16x32_bf16 v[88:91], v[160:163], v[208:211], v[88:91]
	v_mfma_f32_16x16x32_bf16 v[80:83], v[170:173], v[208:211], v[80:83]
	v_mfma_f32_16x16x32_bf16 v[72:75], v[160:163], v[216:219], v[72:75]
	v_mfma_f32_16x16x32_bf16 v[64:67], v[170:173], v[216:219], v[64:67]
	v_mfma_f32_16x16x32_bf16 v[120:123], v[164:167], v[196:199], v[120:123]
	v_mfma_f32_16x16x32_bf16 v[112:115], v[188:191], v[196:199], v[112:115]
	v_mfma_f32_16x16x32_bf16 v[104:107], v[164:167], v[204:207], v[104:107]
	v_mfma_f32_16x16x32_bf16 v[96:99], v[188:191], v[204:207], v[96:99]
	v_mfma_f32_16x16x32_bf16 v[88:91], v[164:167], v[212:215], v[88:91]
	s_add_i32 s52, s74, s6
	v_mfma_f32_16x16x32_bf16 v[80:83], v[188:191], v[212:215], v[80:83]
	v_lshl_add_u64 v[178:179], v[178:179], 0, s[30:31]
	v_mfma_f32_16x16x32_bf16 v[72:75], v[164:167], v[220:223], v[72:75]
	s_mov_b32 m0, s52
	v_mfma_f32_16x16x32_bf16 v[64:67], v[188:191], v[220:223], v[64:67]
	s_setprio 0
	s_barrier
; #define PG8_STAGE(bufoff, gbase, voff) do { _Pragma("unroll") for (int _i = 0; _i < 2; ++_i) \
;         __builtin_amdgcn_global_load_lds((const unsigned*)((const char*)(gbase) + (voff)[_i]), (PG8_LAS unsigned*)(lds + (bufoff) + ldsw + _i * 8192), 16, 0, 0); } while (0)
; #define PG8_LDA(dst, b, h) do { _Pragma("unroll") for (int m = 0; m < 4; ++m) _Pragma("unroll") for (int k = 0; k < 2; ++k) dst[m][k] = *(const PG8_LAS bf16x8*)(lds + PG8_SA(b, h) + aoff + m * 2048 + k * 1024); } while (0)
; #define PG8_LDB(dst, b, h) do { _Pragma("unroll") for (int n = 0; n < 2; ++n) _Pragma("unroll") for (int k = 0; k < 2; ++k) dst[n][k] = *(const PG8_LAS bf16x8*)(lds + PG8_SB(b, h) + boff + n * 2048 + k * 1024); } while (0)
; template <class Epi, class Sched, bool ALIGN_EPI = false, bool SP2 = false>
; __device__ __forceinline__ void gemm_phase(PG8_LAS unsigned char* lds, const Gemm g, const Sched& S, const Epi& E) {
;     ...
;         for (int t = 0; t < nt; t += 2) {
;             const bool last = (t == nt - 2);
;             const char* a1 = cA + (size_t)(t + 1) * kstepA;
;             const char* a2 = last ? nA : cA + (size_t)(t + 2) * kstepA; const char* b2 = last ? nB : cB + (size_t)(t + 2) * kstep;
;             const char* a3 = a2 + kstepA; const char* b3 = b2 + kstep;
;             if (last && has_next) S.a_ready(nxt);
;             if constexpr (SP2) {
;             PG8_LDB(B0, 0, 0); PG8_LDB(B1, 0, 1); PG8_SCHED; PG8_LDA(At, 0, 0); PG8_STAGE(PG8_SA(1, 1), a1 + hstepA, voffA);
;             PG8_WAIT_V(8); PG8_WAIT_L(0); PG8_BAR; PG8_MMA(0, 0, At, B0); PG8_MMA(0, 1, At, B1); PG8_BAR; PG8_SCHED;
;             PG8_LDA(At, 0, 1); PG8_STAGE(PG8_SB(0, 0), b2, voffB); PG8_STAGE(PG8_SB(0, 1), b2 + hstep, voffB); PG8_STAGE(PG8_SA(0, 0), a2, voffA);
;             PG8_WAIT_V(8); PG8_WAIT_L(0); PG8_BAR; PG8_MMA(1, 0, At, B0); PG8_MMA(1, 1, At, B1); PG8_BAR; PG8_SCHED;
;             PG8_LDB(B0, 1, 0); PG8_LDB(B1, 1, 1); PG8_SCHED; PG8_LDA(At, 1, 0); PG8_STAGE(PG8_SA(0, 1), a2 + hstepA, voffA);
;             PG8_WAIT_V(8); PG8_WAIT_L(0); PG8_BAR; PG8_MMA(0, 0, At, B0); PG8_MMA(0, 1, At, B1); PG8_BAR; PG8_SCHED;
;             PG8_LDA(At, 1, 1); PG8_STAGE(PG8_SB(1, 0), b3, voffB); PG8_STAGE(PG8_SB(1, 1), b3 + hstep, voffB); PG8_STAGE(PG8_SA(1, 0), a3, voffA);
;             PG8_WAIT_V(8); PG8_WAIT_L(0); PG8_BAR; PG8_MMA(1, 0, At, B0); PG8_MMA(1, 1, At, B1); PG8_BAR; PG8_SCHED;
	ds_read_b128 v[192:195], v143 offset:49152
	ds_read_b128 v[196:199], v143 offset:50176
	ds_read_b128 v[200:203], v143 offset:51200
	ds_read_b128 v[204:207], v143 offset:52224
	ds_read_b128 v[208:211], v143 offset:53248
	ds_read_b128 v[212:215], v143 offset:54272
	ds_read_b128 v[216:219], v143 offset:55296
	ds_read_b128 v[220:223], v143 offset:56320
	global_load_lds_dwordx4 v[178:179], off
	s_add_i32 m0, s52, 0x2000
	s_add_u32 s50, s50, 0x40080
	v_lshl_add_u64 v[178:179], v[224:225], 0, s[30:31]
	s_addc_u32 s51, s51, 0
	s_add_i32 s52, s75, s6
	global_load_lds_dwordx4 v[178:179], off
	v_lshl_add_u64 v[178:179], s[50:51], 0, v[132:133]
	s_mov_b32 m0, s52
	s_nop 0
	global_load_lds_dwordx4 v[178:179], off
	v_lshl_add_u64 v[178:179], s[50:51], 0, v[128:129]
	s_add_i32 m0, s52, 0x2000
	s_nop 0
	global_load_lds_dwordx4 v[178:179], off
	v_lshl_add_u64 v[178:179], v[234:235], 0, s[30:31]
	s_mov_b32 m0, s55
	s_nop 0
	global_load_lds_dwordx4 v[178:179], off
	v_lshl_add_u64 v[178:179], v[236:237], 0, s[30:31]
	s_mov_b32 m0, s56
	s_nop 0
	global_load_lds_dwordx4 v[178:179], off
	s_waitcnt vmcnt(8)
	s_waitcnt lgkmcnt(0)
	s_barrier
	s_setprio 1
	v_mfma_f32_16x16x32_bf16 v[60:63], v[144:147], v[192:195], v[60:63]
	v_mfma_f32_16x16x32_bf16 v[52:55], v[152:155], v[192:195], v[52:55]
	v_mfma_f32_16x16x32_bf16 v[44:47], v[144:147], v[200:203], v[44:47]
	v_mfma_f32_16x16x32_bf16 v[36:39], v[152:155], v[200:203], v[36:39]
	v_mfma_f32_16x16x32_bf16 v[28:31], v[144:147], v[208:211], v[28:31]
	v_mfma_f32_16x16x32_bf16 v[20:23], v[152:155], v[208:211], v[20:23]
	v_mfma_f32_16x16x32_bf16 v[12:15], v[144:147], v[216:219], v[12:15]
	v_mfma_f32_16x16x32_bf16 v[4:7], v[152:155], v[216:219], v[4:7]
	v_mfma_f32_16x16x32_bf16 v[60:63], v[148:151], v[196:199], v[60:63]
	v_mfma_f32_16x16x32_bf16 v[52:55], v[156:159], v[196:199], v[52:55]
	v_mfma_f32_16x16x32_bf16 v[44:47], v[148:151], v[204:207], v[44:47]
	v_mfma_f32_16x16x32_bf16 v[36:39], v[156:159], v[204:207], v[36:39]
	v_mfma_f32_16x16x32_bf16 v[28:31], v[148:151], v[212:215], v[28:31]
	v_mfma_f32_16x16x32_bf16 v[20:23], v[156:159], v[212:215], v[20:23]
	v_mfma_f32_16x16x32_bf16 v[12:15], v[148:151], v[220:223], v[12:15]
	s_add_i32 s73, s73, 2
	v_mfma_f32_16x16x32_bf16 v[4:7], v[156:159], v[220:223], v[4:7]
	s_add_u32 s65, s65, 0x100
	s_setprio 0
	s_setprio 1
	v_mfma_f32_16x16x32_bf16 v[56:59], v[160:163], v[192:195], v[56:59]
	s_addc_u32 s69, s69, 0
	v_mfma_f32_16x16x32_bf16 v[48:51], v[170:173], v[192:195], v[48:51]
	s_add_u32 s48, s48, 0x100
	v_mfma_f32_16x16x32_bf16 v[40:43], v[160:163], v[200:203], v[40:43]
	s_addc_u32 s49, s49, 0
	v_mfma_f32_16x16x32_bf16 v[32:35], v[170:173], v[200:203], v[32:35]
	s_add_u32 s50, s48, 0xfffc0080
	v_mfma_f32_16x16x32_bf16 v[24:27], v[160:163], v[208:211], v[24:27]
	s_addc_u32 s51, s49, -1
	v_mfma_f32_16x16x32_bf16 v[16:19], v[170:173], v[208:211], v[16:19]
	s_add_i32 s74, 0, 0x10000
	v_mfma_f32_16x16x32_bf16 v[8:11], v[160:163], v[216:219], v[8:11]
	s_cmp_eq_u32 s73, 12
	v_mfma_f32_16x16x32_bf16 v[0:3], v[170:173], v[216:219], v[0:3]
	s_cselect_b32 s53, s43, s51
	v_mfma_f32_16x16x32_bf16 v[56:59], v[164:167], v[196:199], v[56:59]
	s_cselect_b32 s52, s61, s50
	v_mfma_f32_16x16x32_bf16 v[48:51], v[188:191], v[196:199], v[48:51]
	s_cselect_b32 s51, s41, s69
	v_mfma_f32_16x16x32_bf16 v[40:43], v[164:167], v[204:207], v[40:43]
	s_cselect_b32 s50, s64, s65
	v_mfma_f32_16x16x32_bf16 v[32:35], v[188:191], v[204:207], v[32:35]
	s_add_i32 s80, 0, 0x14000
	v_mfma_f32_16x16x32_bf16 v[24:27], v[164:167], v[212:215], v[24:27]
	v_add_u32_e32 v242, s74, v142
	v_mfma_f32_16x16x32_bf16 v[16:19], v[188:191], v[212:215], v[16:19]
	v_add_u32_e32 v178, s80, v142
	v_mfma_f32_16x16x32_bf16 v[8:11], v[164:167], v[220:223], v[8:11]
	s_cmp_gt_u32 s73, 13
	v_mfma_f32_16x16x32_bf16 v[0:3], v[188:191], v[220:223], v[0:3]
	s_setprio 0
	s_barrier
	s_cbranch_scc0 .LBB0_836
	s_and_b64 vcc, exec, s[26:27]
	s_cbranch_vccz .LBB0_839
	s_barrier

; #define PG8_STAGE(bufoff, gbase, voff) do { _Pragma("unroll") for (int _i = 0; _i < 2; ++_i) \
;         __builtin_amdgcn_global_load_lds((const unsigned*)((const char*)(gbase) + (voff)[_i]), (PG8_LAS unsigned*)(lds + (bufoff) + ldsw + _i * 8192), 16, 0, 0); } while (0)
; #define PG8_LDA(dst, b, h) do { _Pragma("unroll") for (int m = 0; m < 4; ++m) _Pragma("unroll") for (int k = 0; k < 2; ++k) dst[m][k] = *(const PG8_LAS bf16x8*)(lds + PG8_SA(b, h) + aoff + m * 2048 + k * 1024); } while (0)
; template <class Epi, class Sched, bool ALIGN_EPI = false, bool SP2 = false>
; __device__ __forceinline__ void gemm_phase(PG8_LAS unsigned char* lds, const Gemm g, const Sched& S, const Epi& E) {
;     ...
;         const bool has_next = S.next(ui + 1, nxt);
;         const char* nA = has_next ? (const char*)g.A + (size_t)nxt.pm * tstepA : cA; const char* nB = has_next ? (const char*)g.Bt + (size_t)nxt.pn * tstep : cB;
;         for (int t = 0; t < nt; t += 2) {
;             const bool last = (t == nt - 2);
;             const char* a1 = cA + (size_t)(t + 1) * kstepA;
;             const char* a2 = last ? nA : cA + (size_t)(t + 2) * kstepA; const char* b2 = last ? nB : cB + (size_t)(t + 2) * kstep;
;             const char* a3 = a2 + kstepA; const char* b3 = b2 + kstep;
;             if (last && has_next) S.a_ready(nxt);
;             if constexpr (SP2) {
;             PG8_LDB(B0, 0, 0); PG8_LDB(B1, 0, 1); PG8_SCHED; PG8_LDA(At, 0, 0); PG8_STAGE(PG8_SA(1, 1), a1 + hstepA, voffA);
;             PG8_WAIT_V(8); PG8_WAIT_L(0); PG8_BAR; PG8_MMA(0, 0, At, B0); PG8_MMA(0, 1, At, B1); PG8_BAR; PG8_SCHED;
;             PG8_LDA(At, 0, 1); PG8_STAGE(PG8_SB(0, 0), b2, voffB); PG8_STAGE(PG8_SB(0, 1), b2 + hstep, voffB); PG8_STAGE(PG8_SA(0, 0), a2, voffA);
;             PG8_WAIT_V(8); PG8_WAIT_L(0); PG8_BAR; PG8_MMA(1, 0, At, B0); PG8_MMA(1, 1, At, B1); PG8_BAR; PG8_SCHED;
;             PG8_LDB(B0, 1, 0); PG8_LDB(B1, 1, 1); PG8_SCHED; PG8_LDA(At, 1, 0); PG8_STAGE(PG8_SA(0, 1), a2 + hstepA, voffA);
;             PG8_WAIT_V(8); PG8_WAIT_L(0); PG8_BAR; PG8_MMA(0, 0, At, B0); PG8_MMA(0, 1, At, B1); PG8_BAR; PG8_SCHED;
;             PG8_LDA(At, 1, 1); PG8_STAGE(PG8_SB(1, 0), b3, voffB); PG8_STAGE(PG8_SB(1, 1), b3 + hstep, voffB); PG8_STAGE(PG8_SA(1, 0), a3, voffA);
;             PG8_WAIT_V(8); PG8_WAIT_L(0); PG8_BAR; PG8_MMA(1, 0, At, B0); PG8_MMA(1, 1, At, B1); PG8_BAR; PG8_SCHED;
.LBB0_912:
	s_add_u32 s5, s52, 0x100
	s_addc_u32 s6, s53, 0
	s_add_u32 s40, s54, 0xb4000
	s_addc_u32 s41, s55, 0
	s_mov_b32 s7, -2
	s_add_u32 s52, s40, 0xfff54000
	s_addc_u32 s53, s41, -1
	s_cmp_eq_u32 s7, 40
	s_cselect_b32 s56, s48, s52
	s_cselect_b32 s57, s49, s53
	s_cselect_b32 s54, s50, s5
	s_cselect_b32 s55, s51, s6
	s_add_u32 s52, s56, 0x4000
	s_addc_u32 s53, s57, 0
	s_add_i32 s64, 0, 0x10000
	s_add_i32 s74, 0, 0x14000
	s_add_i32 m0, s3, 0xc000
	v_lshl_add_u64 v[178:179], s[40:41], 0, v[196:197]
	global_load_lds_dwordx4 v[178:179], off
	v_lshl_add_u64 v[178:179], s[40:41], 0, v[194:195]
	s_add_i32 m0, s3, 0xe000
	s_nop 0
	global_load_lds_dwordx4 v[178:179], off
	s_waitcnt vmcnt(8)
	s_waitcnt lgkmcnt(0)
	s_barrier
	s_setprio 1
	v_mfma_f32_16x16x32_bf16 v[124:127], v[128:131], v[160:163], 0
	v_mfma_f32_16x16x32_bf16 v[120:123], v[136:139], v[160:163], 0
	v_mfma_f32_16x16x32_bf16 v[108:111], v[128:131], v[170:173], 0
	v_mfma_f32_16x16x32_bf16 v[104:107], v[136:139], v[170:173], 0
	v_mfma_f32_16x16x32_bf16 v[92:95], v[128:131], v[202:205], 0
	v_mfma_f32_16x16x32_bf16 v[88:91], v[136:139], v[202:205], 0
	v_mfma_f32_16x16x32_bf16 v[76:79], v[128:131], v[210:213], 0
	v_mfma_f32_16x16x32_bf16 v[72:75], v[136:139], v[210:213], 0
	v_mfma_f32_16x16x32_bf16 v[124:127], v[132:135], v[164:167], v[124:127]
	v_mfma_f32_16x16x32_bf16 v[120:123], v[140:143], v[164:167], v[120:123]
	v_mfma_f32_16x16x32_bf16 v[108:111], v[132:135], v[198:201], v[108:111]
	v_mfma_f32_16x16x32_bf16 v[104:107], v[140:143], v[198:201], v[104:107]
	v_mfma_f32_16x16x32_bf16 v[92:95], v[132:135], v[206:209], v[92:95]
	v_mfma_f32_16x16x32_bf16 v[88:91], v[140:143], v[206:209], v[88:91]
	v_mfma_f32_16x16x32_bf16 v[76:79], v[132:135], v[214:217], v[76:79]
	v_mfma_f32_16x16x32_bf16 v[72:75], v[140:143], v[214:217], v[72:75]
	s_setprio 0
	s_setprio 1
	v_mfma_f32_16x16x32_bf16 v[116:119], v[144:147], v[160:163], 0
	v_mfma_f32_16x16x32_bf16 v[112:115], v[152:155], v[160:163], 0
	v_mfma_f32_16x16x32_bf16 v[100:103], v[144:147], v[170:173], 0
	v_mfma_f32_16x16x32_bf16 v[96:99], v[152:155], v[170:173], 0
	v_mfma_f32_16x16x32_bf16 v[84:87], v[144:147], v[202:205], 0
	v_mfma_f32_16x16x32_bf16 v[80:83], v[152:155], v[202:205], 0
	v_mfma_f32_16x16x32_bf16 v[68:71], v[144:147], v[210:213], 0
	v_mfma_f32_16x16x32_bf16 v[64:67], v[152:155], v[210:213], 0
	v_mfma_f32_16x16x32_bf16 v[116:119], v[148:151], v[164:167], v[116:119]
	v_mfma_f32_16x16x32_bf16 v[112:115], v[156:159], v[164:167], v[112:115]
	v_mfma_f32_16x16x32_bf16 v[100:103], v[148:151], v[198:201], v[100:103]
	v_mfma_f32_16x16x32_bf16 v[96:99], v[156:159], v[198:201], v[96:99]
	v_mfma_f32_16x16x32_bf16 v[84:87], v[148:151], v[206:209], v[84:87]
	s_add_i32 s64, s64, s2
	v_mfma_f32_16x16x32_bf16 v[80:83], v[156:159], v[206:209], v[80:83]
	v_lshl_add_u64 v[178:179], s[54:55], 0, v[168:169]
	v_mfma_f32_16x16x32_bf16 v[68:71], v[148:151], v[214:217], v[68:71]
	s_mov_b32 m0, s64
	v_mfma_f32_16x16x32_bf16 v[64:67], v[156:159], v[214:217], v[64:67]
	s_setprio 0
	s_barrier
	ds_read_b128 v[160:163], v225 offset:16384
	ds_read_b128 v[164:167], v225 offset:17408
	ds_read_b128 v[170:173], v225 offset:18432
	ds_read_b128 v[198:201], v225 offset:19456
	ds_read_b128 v[202:205], v225 offset:20480
	ds_read_b128 v[206:209], v225 offset:21504
	ds_read_b128 v[210:213], v225 offset:22528
	ds_read_b128 v[214:217], v225 offset:23552
	global_load_lds_dwordx4 v[178:179], off
	s_add_i32 m0, s64, 0x2000
	s_add_u32 s64, s54, 0xb0000
	v_lshl_add_u64 v[218:219], s[54:55], 0, v[188:189]
	s_addc_u32 s65, s55, 0
	s_add_i32 s74, s74, s2
	global_load_lds_dwordx4 v[218:219], off
	v_lshl_add_u64 v[220:221], s[64:65], 0, v[168:169]
	s_mov_b32 m0, s74
	s_nop 0
	global_load_lds_dwordx4 v[220:221], off
	v_lshl_add_u64 v[220:221], s[64:65], 0, v[188:189]
	s_add_i32 m0, s74, 0x2000
	s_nop 0
	global_load_lds_dwordx4 v[220:221], off
	v_lshl_add_u64 v[220:221], s[56:57], 0, v[192:193]
	s_mov_b32 m0, s3
	s_nop 0
	global_load_lds_dwordx4 v[220:221], off
	v_lshl_add_u64 v[220:221], s[56:57], 0, v[190:191]
	s_mov_b32 m0, s34
	s_nop 0
	global_load_lds_dwordx4 v[220:221], off
	s_waitcnt vmcnt(8)
	s_waitcnt lgkmcnt(0)
	s_barrier
	s_setprio 1
	v_mfma_f32_16x16x32_bf16 v[60:63], v[128:131], v[160:163], 0
	v_mfma_f32_16x16x32_bf16 v[56:59], v[136:139], v[160:163], 0
	v_mfma_f32_16x16x32_bf16 v[44:47], v[128:131], v[170:173], 0
	v_mfma_f32_16x16x32_bf16 v[40:43], v[136:139], v[170:173], 0
	v_mfma_f32_16x16x32_bf16 v[28:31], v[128:131], v[202:205], 0
	v_mfma_f32_16x16x32_bf16 v[24:27], v[136:139], v[202:205], 0
	v_mfma_f32_16x16x32_bf16 v[12:15], v[128:131], v[210:213], 0
	v_mfma_f32_16x16x32_bf16 v[8:11], v[136:139], v[210:213], 0
	v_mfma_f32_16x16x32_bf16 v[60:63], v[132:135], v[164:167], v[60:63]
	v_mfma_f32_16x16x32_bf16 v[56:59], v[140:143], v[164:167], v[56:59]
	v_mfma_f32_16x16x32_bf16 v[44:47], v[132:135], v[198:201], v[44:47]
	v_mfma_f32_16x16x32_bf16 v[40:43], v[140:143], v[198:201], v[40:43]
	v_mfma_f32_16x16x32_bf16 v[28:31], v[132:135], v[206:209], v[28:31]
	v_mfma_f32_16x16x32_bf16 v[24:27], v[140:143], v[206:209], v[24:27]
	v_mfma_f32_16x16x32_bf16 v[12:15], v[132:135], v[214:217], v[12:15]
	v_mfma_f32_16x16x32_bf16 v[8:11], v[140:143], v[214:217], v[8:11]
	s_setprio 0
	s_setprio 1
	v_mfma_f32_16x16x32_bf16 v[52:55], v[144:147], v[160:163], 0
	v_mfma_f32_16x16x32_bf16 v[48:51], v[152:155], v[160:163], 0
	v_mfma_f32_16x16x32_bf16 v[36:39], v[144:147], v[170:173], 0
	v_mfma_f32_16x16x32_bf16 v[32:35], v[152:155], v[170:173], 0
	v_mfma_f32_16x16x32_bf16 v[20:23], v[144:147], v[202:205], 0
	v_mfma_f32_16x16x32_bf16 v[16:19], v[152:155], v[202:205], 0
	v_mfma_f32_16x16x32_bf16 v[4:7], v[144:147], v[210:213], 0
	v_mfma_f32_16x16x32_bf16 v[0:3], v[152:155], v[210:213], 0
	v_mfma_f32_16x16x32_bf16 v[52:55], v[148:151], v[164:167], v[52:55]
	v_mfma_f32_16x16x32_bf16 v[48:51], v[156:159], v[164:167], v[48:51]
	v_mfma_f32_16x16x32_bf16 v[36:39], v[148:151], v[198:201], v[36:39]
	v_mfma_f32_16x16x32_bf16 v[32:35], v[156:159], v[198:201], v[32:35]
	s_add_i32 s64, 0, 0x18000
	v_mfma_f32_16x16x32_bf16 v[20:23], v[148:151], v[206:209], v[20:23]
	s_add_i32 s65, 0, 0x1c000
	v_mfma_f32_16x16x32_bf16 v[16:19], v[156:159], v[206:209], v[16:19]
	v_add_u32_e32 v240, s64, v224
	v_mfma_f32_16x16x32_bf16 v[4:7], v[148:151], v[214:217], v[4:7]
	v_add_u32_e32 v241, s65, v224
	v_mfma_f32_16x16x32_bf16 v[0:3], v[156:159], v[214:217], v[0:3]
	s_setprio 0
	s_barrier
; #define PG8_STAGE(bufoff, gbase, voff) do { _Pragma("unroll") for (int _i = 0; _i < 2; ++_i) \
;         __builtin_amdgcn_global_load_lds((const unsigned*)((const char*)(gbase) + (voff)[_i]), (PG8_LAS unsigned*)(lds + (bufoff) + ldsw + _i * 8192), 16, 0, 0); } while (0)
; #define PG8_LDA(dst, b, h) do { _Pragma("unroll") for (int m = 0; m < 4; ++m) _Pragma("unroll") for (int k = 0; k < 2; ++k) dst[m][k] = *(const PG8_LAS bf16x8*)(lds + PG8_SA(b, h) + aoff + m * 2048 + k * 1024); } while (0)
; #define PG8_LDB(dst, b, h) do { _Pragma("unroll") for (int n = 0; n < 2; ++n) _Pragma("unroll") for (int k = 0; k < 2; ++k) dst[n][k] = *(const PG8_LAS bf16x8*)(lds + PG8_SB(b, h) + boff + n * 2048 + k * 1024); } while (0)
; #define PG8_MMA(ai, bj, At, Bt) do { __builtin_amdgcn_s_setprio(1); _Pragma("unroll") for (int m = 0; m < 4; ++m) _Pragma("unroll") for (int n = 0; n < 2; ++n) _Pragma("unroll") for (int k = 0; k < 2; ++k) \
;         acc[ai][bj][m][n] = __builtin_amdgcn_mfma_f32_16x16x32_bf16(Bt[n][k], At[m][k], acc[ai][bj][m][n], 0, 0, 0); __builtin_amdgcn_s_setprio(0); } while (0)
; #define PG8_WAIT_V(n) asm volatile("s_waitcnt vmcnt(" #n ")" ::: "memory")
; template <class Epi, class Sched, bool ALIGN_EPI = false, bool SP2 = false>
; __device__ __forceinline__ void gemm_phase(PG8_LAS unsigned char* lds, const Gemm g, const Sched& S, const Epi& E) {
;     ...
;             PG8_LDB(B0, 0, 0); PG8_LDB(B1, 0, 1); PG8_SCHED; PG8_LDA(At, 0, 0); PG8_STAGE(PG8_SA(1, 1), a1 + hstepA, voffA);
;             PG8_WAIT_V(8); PG8_WAIT_L(0); PG8_BAR; PG8_MMA(0, 0, At, B0); PG8_MMA(0, 1, At, B1); PG8_BAR; PG8_SCHED;
;             PG8_LDA(At, 0, 1); PG8_STAGE(PG8_SB(0, 0), b2, voffB); PG8_STAGE(PG8_SB(0, 1), b2 + hstep, voffB); PG8_STAGE(PG8_SA(0, 0), a2, voffA);
;             PG8_WAIT_V(8); PG8_WAIT_L(0); PG8_BAR; PG8_MMA(1, 0, At, B0); PG8_MMA(1, 1, At, B1); PG8_BAR; PG8_SCHED;
;             PG8_LDB(B0, 1, 0); PG8_LDB(B1, 1, 1); PG8_SCHED; PG8_LDA(At, 1, 0); PG8_STAGE(PG8_SA(0, 1), a2 + hstepA, voffA);
;             PG8_WAIT_V(8); PG8_WAIT_L(0); PG8_BAR; PG8_MMA(0, 0, At, B0); PG8_MMA(0, 1, At, B1); PG8_BAR; PG8_SCHED;
;             PG8_LDA(At, 1, 1); PG8_STAGE(PG8_SB(1, 0), b3, voffB); PG8_STAGE(PG8_SB(1, 1), b3 + hstep, voffB); PG8_STAGE(PG8_SA(1, 0), a3, voffA);
;             PG8_WAIT_V(8); PG8_WAIT_L(0); PG8_BAR; PG8_MMA(1, 0, At, B0); PG8_MMA(1, 1, At, B1); PG8_BAR; PG8_SCHED;
	ds_read_b128 v[128:131], v240
	ds_read_b128 v[132:135], v240 offset:1024
	ds_read_b128 v[136:139], v240 offset:2048
	ds_read_b128 v[140:143], v240 offset:3072
	ds_read_b128 v[144:147], v241
	ds_read_b128 v[148:151], v241 offset:1024
	ds_read_b128 v[152:155], v241 offset:2048
	ds_read_b128 v[156:159], v241 offset:3072
	ds_read_b128 v[160:163], v225 offset:32768
	ds_read_b128 v[164:167], v225 offset:33792
	ds_read_b128 v[170:173], v225 offset:34816
	ds_read_b128 v[198:201], v225 offset:35840
	ds_read_b128 v[202:205], v225 offset:36864
	ds_read_b128 v[206:209], v225 offset:37888
	ds_read_b128 v[210:213], v225 offset:38912
	ds_read_b128 v[214:217], v225 offset:39936
	s_add_u32 s56, s56, 0xb0000
	s_addc_u32 s57, s57, 0
	s_mov_b32 m0, s35
	v_lshl_add_u64 v[220:221], s[56:57], 0, v[192:193]
	global_load_lds_dwordx4 v[220:221], off
	v_lshl_add_u64 v[220:221], s[56:57], 0, v[190:191]
	s_mov_b32 m0, s60
	s_nop 0
	global_load_lds_dwordx4 v[220:221], off
	s_waitcnt vmcnt(8)
	s_waitcnt lgkmcnt(0)
	s_barrier
	s_setprio 1
	v_mfma_f32_16x16x32_bf16 v[124:127], v[128:131], v[160:163], v[124:127]
	v_mfma_f32_16x16x32_bf16 v[120:123], v[136:139], v[160:163], v[120:123]
	v_mfma_f32_16x16x32_bf16 v[108:111], v[128:131], v[170:173], v[108:111]
	v_mfma_f32_16x16x32_bf16 v[104:107], v[136:139], v[170:173], v[104:107]
	v_mfma_f32_16x16x32_bf16 v[92:95], v[128:131], v[202:205], v[92:95]
	v_mfma_f32_16x16x32_bf16 v[88:91], v[136:139], v[202:205], v[88:91]
	v_mfma_f32_16x16x32_bf16 v[76:79], v[128:131], v[210:213], v[76:79]
	v_mfma_f32_16x16x32_bf16 v[72:75], v[136:139], v[210:213], v[72:75]
	v_mfma_f32_16x16x32_bf16 v[124:127], v[132:135], v[164:167], v[124:127]
	v_mfma_f32_16x16x32_bf16 v[120:123], v[140:143], v[164:167], v[120:123]
	v_mfma_f32_16x16x32_bf16 v[108:111], v[132:135], v[198:201], v[108:111]
	v_mfma_f32_16x16x32_bf16 v[104:107], v[140:143], v[198:201], v[104:107]
	v_mfma_f32_16x16x32_bf16 v[92:95], v[132:135], v[206:209], v[92:95]
	v_mfma_f32_16x16x32_bf16 v[88:91], v[140:143], v[206:209], v[88:91]
	v_mfma_f32_16x16x32_bf16 v[76:79], v[132:135], v[214:217], v[76:79]
	v_mfma_f32_16x16x32_bf16 v[72:75], v[140:143], v[214:217], v[72:75]
	s_setprio 0
	s_setprio 1
	v_mfma_f32_16x16x32_bf16 v[116:119], v[144:147], v[160:163], v[116:119]
	v_mfma_f32_16x16x32_bf16 v[112:115], v[152:155], v[160:163], v[112:115]
	v_mfma_f32_16x16x32_bf16 v[100:103], v[144:147], v[170:173], v[100:103]
	v_mfma_f32_16x16x32_bf16 v[96:99], v[152:155], v[170:173], v[96:99]
	v_mfma_f32_16x16x32_bf16 v[84:87], v[144:147], v[202:205], v[84:87]
	v_mfma_f32_16x16x32_bf16 v[80:83], v[152:155], v[202:205], v[80:83]
	v_mfma_f32_16x16x32_bf16 v[68:71], v[144:147], v[210:213], v[68:71]
	v_mfma_f32_16x16x32_bf16 v[64:67], v[152:155], v[210:213], v[64:67]
	v_mfma_f32_16x16x32_bf16 v[116:119], v[148:151], v[164:167], v[116:119]
	v_mfma_f32_16x16x32_bf16 v[112:115], v[156:159], v[164:167], v[112:115]
	v_mfma_f32_16x16x32_bf16 v[100:103], v[148:151], v[198:201], v[100:103]
	v_mfma_f32_16x16x32_bf16 v[96:99], v[156:159], v[198:201], v[96:99]
	v_mfma_f32_16x16x32_bf16 v[84:87], v[148:151], v[206:209], v[84:87]
	s_add_i32 s56, s64, s2
	v_mfma_f32_16x16x32_bf16 v[80:83], v[156:159], v[206:209], v[80:83]
	v_lshl_add_u64 v[178:179], v[178:179], 0, s[30:31]
	v_mfma_f32_16x16x32_bf16 v[68:71], v[148:151], v[214:217], v[68:71]
	s_mov_b32 m0, s56
	v_mfma_f32_16x16x32_bf16 v[64:67], v[156:159], v[214:217], v[64:67]
	s_setprio 0
	s_barrier
	ds_read_b128 v[160:163], v225 offset:49152
	ds_read_b128 v[164:167], v225 offset:50176
	ds_read_b128 v[170:173], v225 offset:51200
	ds_read_b128 v[198:201], v225 offset:52224
	ds_read_b128 v[202:205], v225 offset:53248
	ds_read_b128 v[206:209], v225 offset:54272
	ds_read_b128 v[210:213], v225 offset:55296
	ds_read_b128 v[214:217], v225 offset:56320
	global_load_lds_dwordx4 v[178:179], off
	s_add_i32 m0, s56, 0x2000
	s_add_u32 s54, s54, 0xb0080
	v_lshl_add_u64 v[178:179], v[218:219], 0, s[30:31]
	s_addc_u32 s55, s55, 0
	s_add_i32 s56, s65, s2
	global_load_lds_dwordx4 v[178:179], off
	v_lshl_add_u64 v[178:179], s[54:55], 0, v[168:169]
	s_mov_b32 m0, s56
	s_nop 0
	global_load_lds_dwordx4 v[178:179], off
	v_lshl_add_u64 v[178:179], s[54:55], 0, v[188:189]
	s_add_i32 m0, s56, 0x2000
	s_nop 0
	global_load_lds_dwordx4 v[178:179], off
	v_lshl_add_u64 v[178:179], s[52:53], 0, v[192:193]
	s_mov_b32 m0, s69
	s_nop 0
	global_load_lds_dwordx4 v[178:179], off
	v_lshl_add_u64 v[178:179], s[52:53], 0, v[190:191]
	s_mov_b32 m0, s73
	s_nop 0
	global_load_lds_dwordx4 v[178:179], off
	s_waitcnt vmcnt(8)
	s_waitcnt lgkmcnt(0)
	s_barrier
; #define PG8_STAGE(bufoff, gbase, voff) do { _Pragma("unroll") for (int _i = 0; _i < 2; ++_i) \
;         __builtin_amdgcn_global_load_lds((const unsigned*)((const char*)(gbase) + (voff)[_i]), (PG8_LAS unsigned*)(lds + (bufoff) + ldsw + _i * 8192), 16, 0, 0); } while (0)
; #define PG8_LDA(dst, b, h) do { _Pragma("unroll") for (int m = 0; m < 4; ++m) _Pragma("unroll") for (int k = 0; k < 2; ++k) dst[m][k] = *(const PG8_LAS bf16x8*)(lds + PG8_SA(b, h) + aoff + m * 2048 + k * 1024); } while (0)
; #define PG8_LDB(dst, b, h) do { _Pragma("unroll") for (int n = 0; n < 2; ++n) _Pragma("unroll") for (int k = 0; k < 2; ++k) dst[n][k] = *(const PG8_LAS bf16x8*)(lds + PG8_SB(b, h) + boff + n * 2048 + k * 1024); } while (0)
; template <class Epi, class Sched, bool ALIGN_EPI = false, bool SP2 = false>
; __device__ __forceinline__ void gemm_phase(PG8_LAS unsigned char* lds, const Gemm g, const Sched& S, const Epi& E) {
;     ...
;         for (int t = 0; t < nt; t += 2) {
;             const bool last = (t == nt - 2);
;             const char* a1 = cA + (size_t)(t + 1) * kstepA;
;             const char* a2 = last ? nA : cA + (size_t)(t + 2) * kstepA; const char* b2 = last ? nB : cB + (size_t)(t + 2) * kstep;
;             const char* a3 = a2 + kstepA; const char* b3 = b2 + kstep;
;             if (last && has_next) S.a_ready(nxt);
;             if constexpr (SP2) {
;             PG8_LDB(B0, 0, 0); PG8_LDB(B1, 0, 1); PG8_SCHED; PG8_LDA(At, 0, 0); PG8_STAGE(PG8_SA(1, 1), a1 + hstepA, voffA);
;             PG8_WAIT_V(8); PG8_WAIT_L(0); PG8_BAR; PG8_MMA(0, 0, At, B0); PG8_MMA(0, 1, At, B1); PG8_BAR; PG8_SCHED;
;             PG8_LDA(At, 0, 1); PG8_STAGE(PG8_SB(0, 0), b2, voffB); PG8_STAGE(PG8_SB(0, 1), b2 + hstep, voffB); PG8_STAGE(PG8_SA(0, 0), a2, voffA);
;             PG8_WAIT_V(8); PG8_WAIT_L(0); PG8_BAR; PG8_MMA(1, 0, At, B0); PG8_MMA(1, 1, At, B1); PG8_BAR; PG8_SCHED;
;             PG8_LDB(B0, 1, 0); PG8_LDB(B1, 1, 1); PG8_SCHED; PG8_LDA(At, 1, 0); PG8_STAGE(PG8_SA(0, 1), a2 + hstepA, voffA);
;             PG8_WAIT_V(8); PG8_WAIT_L(0); PG8_BAR; PG8_MMA(0, 0, At, B0); PG8_MMA(0, 1, At, B1); PG8_BAR; PG8_SCHED;
;             PG8_LDA(At, 1, 1); PG8_STAGE(PG8_SB(1, 0), b3, voffB); PG8_STAGE(PG8_SB(1, 1), b3 + hstep, voffB); PG8_STAGE(PG8_SA(1, 0), a3, voffA);
;             PG8_WAIT_V(8); PG8_WAIT_L(0); PG8_BAR; PG8_MMA(1, 0, At, B0); PG8_MMA(1, 1, At, B1); PG8_BAR; PG8_SCHED;
	s_setprio 1
	v_mfma_f32_16x16x32_bf16 v[60:63], v[128:131], v[160:163], v[60:63]
	v_mfma_f32_16x16x32_bf16 v[56:59], v[136:139], v[160:163], v[56:59]
	v_mfma_f32_16x16x32_bf16 v[44:47], v[128:131], v[170:173], v[44:47]
	v_mfma_f32_16x16x32_bf16 v[40:43], v[136:139], v[170:173], v[40:43]
	v_mfma_f32_16x16x32_bf16 v[28:31], v[128:131], v[202:205], v[28:31]
	v_mfma_f32_16x16x32_bf16 v[24:27], v[136:139], v[202:205], v[24:27]
	v_mfma_f32_16x16x32_bf16 v[12:15], v[128:131], v[210:213], v[12:15]
	v_mfma_f32_16x16x32_bf16 v[8:11], v[136:139], v[210:213], v[8:11]
	v_mfma_f32_16x16x32_bf16 v[60:63], v[132:135], v[164:167], v[60:63]
	v_mfma_f32_16x16x32_bf16 v[56:59], v[140:143], v[164:167], v[56:59]
	v_mfma_f32_16x16x32_bf16 v[44:47], v[132:135], v[198:201], v[44:47]
	v_mfma_f32_16x16x32_bf16 v[40:43], v[140:143], v[198:201], v[40:43]
	v_mfma_f32_16x16x32_bf16 v[28:31], v[132:135], v[206:209], v[28:31]
	v_mfma_f32_16x16x32_bf16 v[24:27], v[140:143], v[206:209], v[24:27]
	s_add_i32 s7, s7, 2
	v_mfma_f32_16x16x32_bf16 v[12:15], v[132:135], v[214:217], v[12:15]
	s_add_u32 s5, s5, 0x100
	v_mfma_f32_16x16x32_bf16 v[8:11], v[140:143], v[214:217], v[8:11]
	s_addc_u32 s6, s6, 0
	s_setprio 0
	s_setprio 1
	v_mfma_f32_16x16x32_bf16 v[52:55], v[144:147], v[160:163], v[52:55]
	s_add_u32 s40, s40, 0x8000
	v_mfma_f32_16x16x32_bf16 v[48:51], v[152:155], v[160:163], v[48:51]
	s_addc_u32 s41, s41, 0
	v_mfma_f32_16x16x32_bf16 v[36:39], v[144:147], v[170:173], v[36:39]
	s_add_u32 s52, s40, 0xfff54000
	v_mfma_f32_16x16x32_bf16 v[32:35], v[152:155], v[170:173], v[32:35]
	s_addc_u32 s53, s41, -1
	v_mfma_f32_16x16x32_bf16 v[20:23], v[144:147], v[202:205], v[20:23]
	s_cmp_eq_u32 s7, 40
	v_mfma_f32_16x16x32_bf16 v[16:19], v[152:155], v[202:205], v[16:19]
	s_cselect_b32 s56, s48, s52
	v_mfma_f32_16x16x32_bf16 v[4:7], v[144:147], v[210:213], v[4:7]
	s_cselect_b32 s57, s49, s53
	v_mfma_f32_16x16x32_bf16 v[0:3], v[152:155], v[210:213], v[0:3]
	s_cselect_b32 s54, s50, s5
	v_mfma_f32_16x16x32_bf16 v[52:55], v[148:151], v[164:167], v[52:55]
	s_cselect_b32 s55, s51, s6
	v_mfma_f32_16x16x32_bf16 v[48:51], v[156:159], v[164:167], v[48:51]
	s_add_u32 s52, s56, 0x4000
	v_mfma_f32_16x16x32_bf16 v[36:39], v[148:151], v[198:201], v[36:39]
	s_addc_u32 s53, s57, 0
	v_mfma_f32_16x16x32_bf16 v[32:35], v[156:159], v[198:201], v[32:35]
	s_add_i32 s64, 0, 0x10000
	v_mfma_f32_16x16x32_bf16 v[20:23], v[148:151], v[206:209], v[20:23]
	s_add_i32 s74, 0, 0x14000
	v_mfma_f32_16x16x32_bf16 v[16:19], v[156:159], v[206:209], v[16:19]
	v_add_u32_e32 v242, s64, v224
	v_mfma_f32_16x16x32_bf16 v[4:7], v[148:151], v[214:217], v[4:7]
	v_add_u32_e32 v243, s74, v224
	v_mfma_f32_16x16x32_bf16 v[0:3], v[156:159], v[214:217], v[0:3]
	s_setprio 0
	s_barrier
.LBB0_913:
	ds_read_b128 v[128:131], v242
	ds_read_b128 v[132:135], v242 offset:1024
	ds_read_b128 v[136:139], v242 offset:2048
	ds_read_b128 v[140:143], v242 offset:3072
	ds_read_b128 v[144:147], v243
	ds_read_b128 v[148:151], v243 offset:1024
	ds_read_b128 v[152:155], v243 offset:2048
	ds_read_b128 v[156:159], v243 offset:3072
	ds_read_b128 v[160:163], v225
	ds_read_b128 v[164:167], v225 offset:1024
	ds_read_b128 v[170:173], v225 offset:2048
	ds_read_b128 v[198:201], v225 offset:3072
	ds_read_b128 v[202:205], v225 offset:4096
	ds_read_b128 v[206:209], v225 offset:5120
	ds_read_b128 v[210:213], v225 offset:6144
	ds_read_b128 v[214:217], v225 offset:7168
	s_add_i32 m0, s3, 0xc000
	v_lshl_add_u64 v[178:179], s[40:41], 0, v[196:197]
	global_load_lds_dwordx4 v[178:179], off
	v_lshl_add_u64 v[178:179], s[40:41], 0, v[194:195]
	s_add_i32 m0, s3, 0xe000
	s_nop 0
	global_load_lds_dwordx4 v[178:179], off
	s_waitcnt vmcnt(8)
	s_waitcnt lgkmcnt(0)
	s_barrier
	s_setprio 1
	v_mfma_f32_16x16x32_bf16 v[124:127], v[128:131], v[160:163], v[124:127]
	v_mfma_f32_16x16x32_bf16 v[120:123], v[136:139], v[160:163], v[120:123]
	v_mfma_f32_16x16x32_bf16 v[108:111], v[128:131], v[170:173], v[108:111]
	v_mfma_f32_16x16x32_bf16 v[104:107], v[136:139], v[170:173], v[104:107]
	v_mfma_f32_16x16x32_bf16 v[92:95], v[128:131], v[202:205], v[92:95]
	v_mfma_f32_16x16x32_bf16 v[88:91], v[136:139], v[202:205], v[88:91]
	v_mfma_f32_16x16x32_bf16 v[76:79], v[128:131], v[210:213], v[76:79]
	v_mfma_f32_16x16x32_bf16 v[72:75], v[136:139], v[210:213], v[72:75]
	v_mfma_f32_16x16x32_bf16 v[124:127], v[132:135], v[164:167], v[124:127]
	v_mfma_f32_16x16x32_bf16 v[120:123], v[140:143], v[164:167], v[120:123]
	v_mfma_f32_16x16x32_bf16 v[108:111], v[132:135], v[198:201], v[108:111]
	v_mfma_f32_16x16x32_bf16 v[104:107], v[140:143], v[198:201], v[104:107]
	v_mfma_f32_16x16x32_bf16 v[92:95], v[132:135], v[206:209], v[92:95]
	v_mfma_f32_16x16x32_bf16 v[88:91], v[140:143], v[206:209], v[88:91]
	v_mfma_f32_16x16x32_bf16 v[76:79], v[132:135], v[214:217], v[76:79]
	v_mfma_f32_16x16x32_bf16 v[72:75], v[140:143], v[214:217], v[72:75]
	s_setprio 0
	s_setprio 1
	v_mfma_f32_16x16x32_bf16 v[116:119], v[144:147], v[160:163], v[116:119]
	v_mfma_f32_16x16x32_bf16 v[112:115], v[152:155], v[160:163], v[112:115]
	v_mfma_f32_16x16x32_bf16 v[100:103], v[144:147], v[170:173], v[100:103]
	v_mfma_f32_16x16x32_bf16 v[96:99], v[152:155], v[170:173], v[96:99]
	v_mfma_f32_16x16x32_bf16 v[84:87], v[144:147], v[202:205], v[84:87]
	v_mfma_f32_16x16x32_bf16 v[80:83], v[152:155], v[202:205], v[80:83]
	v_mfma_f32_16x16x32_bf16 v[68:71], v[144:147], v[210:213], v[68:71]
	v_mfma_f32_16x16x32_bf16 v[64:67], v[152:155], v[210:213], v[64:67]
	v_mfma_f32_16x16x32_bf16 v[116:119], v[148:151], v[164:167], v[116:119]
	v_mfma_f32_16x16x32_bf16 v[112:115], v[156:159], v[164:167], v[112:115]
	v_mfma_f32_16x16x32_bf16 v[100:103], v[148:151], v[198:201], v[100:103]
	v_mfma_f32_16x16x32_bf16 v[96:99], v[156:159], v[198:201], v[96:99]
	v_mfma_f32_16x16x32_bf16 v[84:87], v[148:151], v[206:209], v[84:87]
	s_add_i32 s64, s64, s2
	v_mfma_f32_16x16x32_bf16 v[80:83], v[156:159], v[206:209], v[80:83]
	v_lshl_add_u64 v[178:179], s[54:55], 0, v[168:169]
	v_mfma_f32_16x16x32_bf16 v[68:71], v[148:151], v[214:217], v[68:71]
	s_mov_b32 m0, s64
	v_mfma_f32_16x16x32_bf16 v[64:67], v[156:159], v[214:217], v[64:67]
	s_setprio 0
	s_barrier
; #define PG8_STAGE(bufoff, gbase, voff) do { _Pragma("unroll") for (int _i = 0; _i < 2; ++_i) \
;         __builtin_amdgcn_global_load_lds((const unsigned*)((const char*)(gbase) + (voff)[_i]), (PG8_LAS unsigned*)(lds + (bufoff) + ldsw + _i * 8192), 16, 0, 0); } while (0)
; #define PG8_LDA(dst, b, h) do { _Pragma("unroll") for (int m = 0; m < 4; ++m) _Pragma("unroll") for (int k = 0; k < 2; ++k) dst[m][k] = *(const PG8_LAS bf16x8*)(lds + PG8_SA(b, h) + aoff + m * 2048 + k * 1024); } while (0)
; #define PG8_LDB(dst, b, h) do { _Pragma("unroll") for (int n = 0; n < 2; ++n) _Pragma("unroll") for (int k = 0; k < 2; ++k) dst[n][k] = *(const PG8_LAS bf16x8*)(lds + PG8_SB(b, h) + boff + n * 2048 + k * 1024); } while (0)
; #define PG8_MMA(ai, bj, At, Bt) do { __builtin_amdgcn_s_setprio(1); _Pragma("unroll") for (int m = 0; m < 4; ++m) _Pragma("unroll") for (int n = 0; n < 2; ++n) _Pragma("unroll") for (int k = 0; k < 2; ++k) \
;         acc[ai][bj][m][n] = __builtin_amdgcn_mfma_f32_16x16x32_bf16(Bt[n][k], At[m][k], acc[ai][bj][m][n], 0, 0, 0); __builtin_amdgcn_s_setprio(0); } while (0)
; #define PG8_WAIT_V(n) asm volatile("s_waitcnt vmcnt(" #n ")" ::: "memory")
; template <class Epi, class Sched, bool ALIGN_EPI = false, bool SP2 = false>
; __device__ __forceinline__ void gemm_phase(PG8_LAS unsigned char* lds, const Gemm g, const Sched& S, const Epi& E) {
;     ...
;             PG8_LDB(B0, 0, 0); PG8_LDB(B1, 0, 1); PG8_SCHED; PG8_LDA(At, 0, 0); PG8_STAGE(PG8_SA(1, 1), a1 + hstepA, voffA);
;             PG8_WAIT_V(8); PG8_WAIT_L(0); PG8_BAR; PG8_MMA(0, 0, At, B0); PG8_MMA(0, 1, At, B1); PG8_BAR; PG8_SCHED;
;             PG8_LDA(At, 0, 1); PG8_STAGE(PG8_SB(0, 0), b2, voffB); PG8_STAGE(PG8_SB(0, 1), b2 + hstep, voffB); PG8_STAGE(PG8_SA(0, 0), a2, voffA);
;             PG8_WAIT_V(8); PG8_WAIT_L(0); PG8_BAR; PG8_MMA(1, 0, At, B0); PG8_MMA(1, 1, At, B1); PG8_BAR; PG8_SCHED;
;             PG8_LDB(B0, 1, 0); PG8_LDB(B1, 1, 1); PG8_SCHED; PG8_LDA(At, 1, 0); PG8_STAGE(PG8_SA(0, 1), a2 + hstepA, voffA);
;             PG8_WAIT_V(8); PG8_WAIT_L(0); PG8_BAR; PG8_MMA(0, 0, At, B0); PG8_MMA(0, 1, At, B1); PG8_BAR; PG8_SCHED;
;             PG8_LDA(At, 1, 1); PG8_STAGE(PG8_SB(1, 0), b3, voffB); PG8_STAGE(PG8_SB(1, 1), b3 + hstep, voffB); PG8_STAGE(PG8_SA(1, 0), a3, voffA);
;             PG8_WAIT_V(8); PG8_WAIT_L(0); PG8_BAR; PG8_MMA(1, 0, At, B0); PG8_MMA(1, 1, At, B1); PG8_BAR; PG8_SCHED;
	ds_read_b128 v[160:163], v225 offset:16384
	ds_read_b128 v[164:167], v225 offset:17408
	ds_read_b128 v[170:173], v225 offset:18432
	ds_read_b128 v[198:201], v225 offset:19456
	ds_read_b128 v[202:205], v225 offset:20480
	ds_read_b128 v[206:209], v225 offset:21504
	ds_read_b128 v[210:213], v225 offset:22528
	ds_read_b128 v[214:217], v225 offset:23552
	global_load_lds_dwordx4 v[178:179], off
	s_add_i32 m0, s64, 0x2000
	s_add_u32 s64, s54, 0xb0000
	v_lshl_add_u64 v[218:219], s[54:55], 0, v[188:189]
	s_addc_u32 s65, s55, 0
	s_add_i32 s74, s74, s2
	global_load_lds_dwordx4 v[218:219], off
	v_lshl_add_u64 v[220:221], s[64:65], 0, v[168:169]
	s_mov_b32 m0, s74
	s_nop 0
	global_load_lds_dwordx4 v[220:221], off
	v_lshl_add_u64 v[220:221], s[64:65], 0, v[188:189]
	s_add_i32 m0, s74, 0x2000
	s_nop 0
	global_load_lds_dwordx4 v[220:221], off
	v_lshl_add_u64 v[220:221], s[56:57], 0, v[192:193]
	s_mov_b32 m0, s3
	s_nop 0
	global_load_lds_dwordx4 v[220:221], off
	v_lshl_add_u64 v[220:221], s[56:57], 0, v[190:191]
	s_mov_b32 m0, s34
	s_nop 0
	global_load_lds_dwordx4 v[220:221], off
	s_waitcnt vmcnt(8)
	s_waitcnt lgkmcnt(0)
	s_barrier
	s_setprio 1
	v_mfma_f32_16x16x32_bf16 v[60:63], v[128:131], v[160:163], v[60:63]
	v_mfma_f32_16x16x32_bf16 v[56:59], v[136:139], v[160:163], v[56:59]
	v_mfma_f32_16x16x32_bf16 v[44:47], v[128:131], v[170:173], v[44:47]
	v_mfma_f32_16x16x32_bf16 v[40:43], v[136:139], v[170:173], v[40:43]
	v_mfma_f32_16x16x32_bf16 v[28:31], v[128:131], v[202:205], v[28:31]
	v_mfma_f32_16x16x32_bf16 v[24:27], v[136:139], v[202:205], v[24:27]
	v_mfma_f32_16x16x32_bf16 v[12:15], v[128:131], v[210:213], v[12:15]
	v_mfma_f32_16x16x32_bf16 v[8:11], v[136:139], v[210:213], v[8:11]
	v_mfma_f32_16x16x32_bf16 v[60:63], v[132:135], v[164:167], v[60:63]
	v_mfma_f32_16x16x32_bf16 v[56:59], v[140:143], v[164:167], v[56:59]
	v_mfma_f32_16x16x32_bf16 v[44:47], v[132:135], v[198:201], v[44:47]
	v_mfma_f32_16x16x32_bf16 v[40:43], v[140:143], v[198:201], v[40:43]
	v_mfma_f32_16x16x32_bf16 v[28:31], v[132:135], v[206:209], v[28:31]
	v_mfma_f32_16x16x32_bf16 v[24:27], v[140:143], v[206:209], v[24:27]
	v_mfma_f32_16x16x32_bf16 v[12:15], v[132:135], v[214:217], v[12:15]
	v_mfma_f32_16x16x32_bf16 v[8:11], v[140:143], v[214:217], v[8:11]
	s_setprio 0
	s_setprio 1
	v_mfma_f32_16x16x32_bf16 v[52:55], v[144:147], v[160:163], v[52:55]
	v_mfma_f32_16x16x32_bf16 v[48:51], v[152:155], v[160:163], v[48:51]
	v_mfma_f32_16x16x32_bf16 v[36:39], v[144:147], v[170:173], v[36:39]
	v_mfma_f32_16x16x32_bf16 v[32:35], v[152:155], v[170:173], v[32:35]
	v_mfma_f32_16x16x32_bf16 v[20:23], v[144:147], v[202:205], v[20:23]
	v_mfma_f32_16x16x32_bf16 v[16:19], v[152:155], v[202:205], v[16:19]
	v_mfma_f32_16x16x32_bf16 v[4:7], v[144:147], v[210:213], v[4:7]
	v_mfma_f32_16x16x32_bf16 v[0:3], v[152:155], v[210:213], v[0:3]
	v_mfma_f32_16x16x32_bf16 v[52:55], v[148:151], v[164:167], v[52:55]
	v_mfma_f32_16x16x32_bf16 v[48:51], v[156:159], v[164:167], v[48:51]
	v_mfma_f32_16x16x32_bf16 v[36:39], v[148:151], v[198:201], v[36:39]
	v_mfma_f32_16x16x32_bf16 v[32:35], v[156:159], v[198:201], v[32:35]
	s_add_i32 s64, 0, 0x18000
	v_mfma_f32_16x16x32_bf16 v[20:23], v[148:151], v[206:209], v[20:23]
	s_add_i32 s65, 0, 0x1c000
	v_mfma_f32_16x16x32_bf16 v[16:19], v[156:159], v[206:209], v[16:19]
	v_add_u32_e32 v240, s64, v224
	v_mfma_f32_16x16x32_bf16 v[4:7], v[148:151], v[214:217], v[4:7]
	v_add_u32_e32 v241, s65, v224
	v_mfma_f32_16x16x32_bf16 v[0:3], v[156:159], v[214:217], v[0:3]
	s_setprio 0
	s_barrier
	ds_read_b128 v[128:131], v240
	ds_read_b128 v[132:135], v240 offset:1024
	ds_read_b128 v[136:139], v240 offset:2048
	ds_read_b128 v[140:143], v240 offset:3072
	ds_read_b128 v[144:147], v241
	ds_read_b128 v[148:151], v241 offset:1024
	ds_read_b128 v[152:155], v241 offset:2048
	ds_read_b128 v[156:159], v241 offset:3072
	ds_read_b128 v[160:163], v225 offset:32768
	ds_read_b128 v[164:167], v225 offset:33792
	ds_read_b128 v[170:173], v225 offset:34816
	ds_read_b128 v[198:201], v225 offset:35840
	ds_read_b128 v[202:205], v225 offset:36864
	ds_read_b128 v[206:209], v225 offset:37888
	ds_read_b128 v[210:213], v225 offset:38912
	ds_read_b128 v[214:217], v225 offset:39936
	s_add_u32 s56, s56, 0xb0000
	s_addc_u32 s57, s57, 0
	s_mov_b32 m0, s35
	v_lshl_add_u64 v[220:221], s[56:57], 0, v[192:193]
	global_load_lds_dwordx4 v[220:221], off
	v_lshl_add_u64 v[220:221], s[56:57], 0, v[190:191]
	s_mov_b32 m0, s60
	s_nop 0
	global_load_lds_dwordx4 v[220:221], off
	s_waitcnt vmcnt(8)
	s_waitcnt lgkmcnt(0)
	s_barrier
; #define PG8_STAGE(bufoff, gbase, voff) do { _Pragma("unroll") for (int _i = 0; _i < 2; ++_i) \
;         __builtin_amdgcn_global_load_lds((const unsigned*)((const char*)(gbase) + (voff)[_i]), (PG8_LAS unsigned*)(lds + (bufoff) + ldsw + _i * 8192), 16, 0, 0); } while (0)
; #define PG8_LDA(dst, b, h) do { _Pragma("unroll") for (int m = 0; m < 4; ++m) _Pragma("unroll") for (int k = 0; k < 2; ++k) dst[m][k] = *(const PG8_LAS bf16x8*)(lds + PG8_SA(b, h) + aoff + m * 2048 + k * 1024); } while (0)
; #define PG8_LDB(dst, b, h) do { _Pragma("unroll") for (int n = 0; n < 2; ++n) _Pragma("unroll") for (int k = 0; k < 2; ++k) dst[n][k] = *(const PG8_LAS bf16x8*)(lds + PG8_SB(b, h) + boff + n * 2048 + k * 1024); } while (0)
; template <class Epi, class Sched, bool ALIGN_EPI = false, bool SP2 = false>
; __device__ __forceinline__ void gemm_phase(PG8_LAS unsigned char* lds, const Gemm g, const Sched& S, const Epi& E) {
;     ...
;         for (int t = 0; t < nt; t += 2) {
;             const bool last = (t == nt - 2);
;             const char* a1 = cA + (size_t)(t + 1) * kstepA;
;             const char* a2 = last ? nA : cA + (size_t)(t + 2) * kstepA; const char* b2 = last ? nB : cB + (size_t)(t + 2) * kstep;
;             const char* a3 = a2 + kstepA; const char* b3 = b2 + kstep;
;             if (last && has_next) S.a_ready(nxt);
;             if constexpr (SP2) {
;             PG8_LDB(B0, 0, 0); PG8_LDB(B1, 0, 1); PG8_SCHED; PG8_LDA(At, 0, 0); PG8_STAGE(PG8_SA(1, 1), a1 + hstepA, voffA);
;             PG8_WAIT_V(8); PG8_WAIT_L(0); PG8_BAR; PG8_MMA(0, 0, At, B0); PG8_MMA(0, 1, At, B1); PG8_BAR; PG8_SCHED;
;             PG8_LDA(At, 0, 1); PG8_STAGE(PG8_SB(0, 0), b2, voffB); PG8_STAGE(PG8_SB(0, 1), b2 + hstep, voffB); PG8_STAGE(PG8_SA(0, 0), a2, voffA);
;             PG8_WAIT_V(8); PG8_WAIT_L(0); PG8_BAR; PG8_MMA(1, 0, At, B0); PG8_MMA(1, 1, At, B1); PG8_BAR; PG8_SCHED;
;             PG8_LDB(B0, 1, 0); PG8_LDB(B1, 1, 1); PG8_SCHED; PG8_LDA(At, 1, 0); PG8_STAGE(PG8_SA(0, 1), a2 + hstepA, voffA);
;             PG8_WAIT_V(8); PG8_WAIT_L(0); PG8_BAR; PG8_MMA(0, 0, At, B0); PG8_MMA(0, 1, At, B1); PG8_BAR; PG8_SCHED;
;             PG8_LDA(At, 1, 1); PG8_STAGE(PG8_SB(1, 0), b3, voffB); PG8_STAGE(PG8_SB(1, 1), b3 + hstep, voffB); PG8_STAGE(PG8_SA(1, 0), a3, voffA);
;             PG8_WAIT_V(8); PG8_WAIT_L(0); PG8_BAR; PG8_MMA(1, 0, At, B0); PG8_MMA(1, 1, At, B1); PG8_BAR; PG8_SCHED;
	s_setprio 1
	v_mfma_f32_16x16x32_bf16 v[124:127], v[128:131], v[160:163], v[124:127]
	v_mfma_f32_16x16x32_bf16 v[120:123], v[136:139], v[160:163], v[120:123]
	v_mfma_f32_16x16x32_bf16 v[108:111], v[128:131], v[170:173], v[108:111]
	v_mfma_f32_16x16x32_bf16 v[104:107], v[136:139], v[170:173], v[104:107]
	v_mfma_f32_16x16x32_bf16 v[92:95], v[128:131], v[202:205], v[92:95]
	v_mfma_f32_16x16x32_bf16 v[88:91], v[136:139], v[202:205], v[88:91]
	v_mfma_f32_16x16x32_bf16 v[76:79], v[128:131], v[210:213], v[76:79]
	v_mfma_f32_16x16x32_bf16 v[72:75], v[136:139], v[210:213], v[72:75]
	v_mfma_f32_16x16x32_bf16 v[124:127], v[132:135], v[164:167], v[124:127]
	v_mfma_f32_16x16x32_bf16 v[120:123], v[140:143], v[164:167], v[120:123]
	v_mfma_f32_16x16x32_bf16 v[108:111], v[132:135], v[198:201], v[108:111]
	v_mfma_f32_16x16x32_bf16 v[104:107], v[140:143], v[198:201], v[104:107]
	v_mfma_f32_16x16x32_bf16 v[92:95], v[132:135], v[206:209], v[92:95]
	v_mfma_f32_16x16x32_bf16 v[88:91], v[140:143], v[206:209], v[88:91]
	v_mfma_f32_16x16x32_bf16 v[76:79], v[132:135], v[214:217], v[76:79]
	v_mfma_f32_16x16x32_bf16 v[72:75], v[140:143], v[214:217], v[72:75]
	s_setprio 0
	s_setprio 1
	v_mfma_f32_16x16x32_bf16 v[116:119], v[144:147], v[160:163], v[116:119]
	v_mfma_f32_16x16x32_bf16 v[112:115], v[152:155], v[160:163], v[112:115]
	v_mfma_f32_16x16x32_bf16 v[100:103], v[144:147], v[170:173], v[100:103]
	v_mfma_f32_16x16x32_bf16 v[96:99], v[152:155], v[170:173], v[96:99]
	v_mfma_f32_16x16x32_bf16 v[84:87], v[144:147], v[202:205], v[84:87]
	v_mfma_f32_16x16x32_bf16 v[80:83], v[152:155], v[202:205], v[80:83]
	v_mfma_f32_16x16x32_bf16 v[68:71], v[144:147], v[210:213], v[68:71]
	v_mfma_f32_16x16x32_bf16 v[64:67], v[152:155], v[210:213], v[64:67]
	v_mfma_f32_16x16x32_bf16 v[116:119], v[148:151], v[164:167], v[116:119]
	v_mfma_f32_16x16x32_bf16 v[112:115], v[156:159], v[164:167], v[112:115]
	v_mfma_f32_16x16x32_bf16 v[100:103], v[148:151], v[198:201], v[100:103]
	v_mfma_f32_16x16x32_bf16 v[96:99], v[156:159], v[198:201], v[96:99]
	v_mfma_f32_16x16x32_bf16 v[84:87], v[148:151], v[206:209], v[84:87]
	s_add_i32 s56, s64, s2
	v_mfma_f32_16x16x32_bf16 v[80:83], v[156:159], v[206:209], v[80:83]
	v_lshl_add_u64 v[178:179], v[178:179], 0, s[30:31]
	v_mfma_f32_16x16x32_bf16 v[68:71], v[148:151], v[214:217], v[68:71]
	s_mov_b32 m0, s56
	v_mfma_f32_16x16x32_bf16 v[64:67], v[156:159], v[214:217], v[64:67]
	s_setprio 0
	s_barrier
	ds_read_b128 v[160:163], v225 offset:49152
	ds_read_b128 v[164:167], v225 offset:50176
	ds_read_b128 v[170:173], v225 offset:51200
	ds_read_b128 v[198:201], v225 offset:52224
	ds_read_b128 v[202:205], v225 offset:53248
	ds_read_b128 v[206:209], v225 offset:54272
	ds_read_b128 v[210:213], v225 offset:55296
	ds_read_b128 v[214:217], v225 offset:56320
	global_load_lds_dwordx4 v[178:179], off
	s_add_i32 m0, s56, 0x2000
	s_add_u32 s54, s54, 0xb0080
	v_lshl_add_u64 v[178:179], v[218:219], 0, s[30:31]
	s_addc_u32 s55, s55, 0
	s_add_i32 s56, s65, s2
	global_load_lds_dwordx4 v[178:179], off
	v_lshl_add_u64 v[178:179], s[54:55], 0, v[168:169]
	s_mov_b32 m0, s56
	s_nop 0
	global_load_lds_dwordx4 v[178:179], off
	v_lshl_add_u64 v[178:179], s[54:55], 0, v[188:189]
	s_add_i32 m0, s56, 0x2000
	s_nop 0
	global_load_lds_dwordx4 v[178:179], off
	v_lshl_add_u64 v[178:179], s[52:53], 0, v[192:193]
	s_mov_b32 m0, s69
	s_nop 0
	global_load_lds_dwordx4 v[178:179], off
	v_lshl_add_u64 v[178:179], s[52:53], 0, v[190:191]
	s_mov_b32 m0, s73
	s_nop 0
	global_load_lds_dwordx4 v[178:179], off
	s_waitcnt vmcnt(8)
	s_waitcnt lgkmcnt(0)
	s_barrier
	s_setprio 1
	v_mfma_f32_16x16x32_bf16 v[60:63], v[128:131], v[160:163], v[60:63]
	v_mfma_f32_16x16x32_bf16 v[56:59], v[136:139], v[160:163], v[56:59]
	v_mfma_f32_16x16x32_bf16 v[44:47], v[128:131], v[170:173], v[44:47]
	v_mfma_f32_16x16x32_bf16 v[40:43], v[136:139], v[170:173], v[40:43]
	v_mfma_f32_16x16x32_bf16 v[28:31], v[128:131], v[202:205], v[28:31]
	v_mfma_f32_16x16x32_bf16 v[24:27], v[136:139], v[202:205], v[24:27]
	v_mfma_f32_16x16x32_bf16 v[12:15], v[128:131], v[210:213], v[12:15]
	v_mfma_f32_16x16x32_bf16 v[8:11], v[136:139], v[210:213], v[8:11]
	v_mfma_f32_16x16x32_bf16 v[60:63], v[132:135], v[164:167], v[60:63]
	v_mfma_f32_16x16x32_bf16 v[56:59], v[140:143], v[164:167], v[56:59]
	v_mfma_f32_16x16x32_bf16 v[44:47], v[132:135], v[198:201], v[44:47]
	v_mfma_f32_16x16x32_bf16 v[40:43], v[140:143], v[198:201], v[40:43]
	v_mfma_f32_16x16x32_bf16 v[28:31], v[132:135], v[206:209], v[28:31]
	s_add_i32 s7, s7, 2
	v_mfma_f32_16x16x32_bf16 v[24:27], v[140:143], v[206:209], v[24:27]
	s_add_u32 s5, s5, 0x100
	v_mfma_f32_16x16x32_bf16 v[12:15], v[132:135], v[214:217], v[12:15]
	s_addc_u32 s6, s6, 0
	v_mfma_f32_16x16x32_bf16 v[8:11], v[140:143], v[214:217], v[8:11]
	s_add_u32 s40, s40, 0x8000
	s_setprio 0
	s_setprio 1
	v_mfma_f32_16x16x32_bf16 v[52:55], v[144:147], v[160:163], v[52:55]
	s_addc_u32 s41, s41, 0
	v_mfma_f32_16x16x32_bf16 v[48:51], v[152:155], v[160:163], v[48:51]
	s_add_u32 s52, s40, 0xfff54000
	v_mfma_f32_16x16x32_bf16 v[36:39], v[144:147], v[170:173], v[36:39]
	s_addc_u32 s53, s41, -1
	v_mfma_f32_16x16x32_bf16 v[32:35], v[152:155], v[170:173], v[32:35]
	s_cmp_eq_u32 s7, 40
	v_mfma_f32_16x16x32_bf16 v[20:23], v[144:147], v[202:205], v[20:23]
	s_cselect_b32 s56, s48, s52
	v_mfma_f32_16x16x32_bf16 v[16:19], v[152:155], v[202:205], v[16:19]
	s_cselect_b32 s57, s49, s53
	v_mfma_f32_16x16x32_bf16 v[4:7], v[144:147], v[210:213], v[4:7]
	s_cselect_b32 s54, s50, s5
	v_mfma_f32_16x16x32_bf16 v[0:3], v[152:155], v[210:213], v[0:3]
	s_cselect_b32 s55, s51, s6
	v_mfma_f32_16x16x32_bf16 v[52:55], v[148:151], v[164:167], v[52:55]
	s_add_u32 s52, s56, 0x4000
	v_mfma_f32_16x16x32_bf16 v[48:51], v[156:159], v[164:167], v[48:51]
	s_addc_u32 s53, s57, 0
	v_mfma_f32_16x16x32_bf16 v[36:39], v[148:151], v[198:201], v[36:39]
	s_add_i32 s64, 0, 0x10000
	v_mfma_f32_16x16x32_bf16 v[32:35], v[156:159], v[198:201], v[32:35]
	s_add_i32 s74, 0, 0x14000
	v_mfma_f32_16x16x32_bf16 v[20:23], v[148:151], v[206:209], v[20:23]
	v_add_u32_e32 v242, s64, v224
	v_mfma_f32_16x16x32_bf16 v[16:19], v[156:159], v[206:209], v[16:19]
	v_add_u32_e32 v243, s74, v224
	v_mfma_f32_16x16x32_bf16 v[4:7], v[148:151], v[214:217], v[4:7]
	s_cmp_gt_u32 s7, 41
	v_mfma_f32_16x16x32_bf16 v[0:3], v[156:159], v[214:217], v[0:3]
	s_setprio 0
	s_barrier
	s_cbranch_scc0 .LBB0_913
	s_and_b64 vcc, exec, s[42:43]
	s_cbranch_vccz .LBB0_916
	s_barrier

; #define PG8_STAGE(bufoff, gbase, voff) do { _Pragma("unroll") for (int _i = 0; _i < 2; ++_i) \
;         __builtin_amdgcn_global_load_lds((const unsigned*)((const char*)(gbase) + (voff)[_i]), (PG8_LAS unsigned*)(lds + (bufoff) + ldsw + _i * 8192), 16, 0, 0); } while (0)
; #define PG8_LDA(dst, b, h) do { _Pragma("unroll") for (int m = 0; m < 4; ++m) _Pragma("unroll") for (int k = 0; k < 2; ++k) dst[m][k] = *(const PG8_LAS bf16x8*)(lds + PG8_SA(b, h) + aoff + m * 2048 + k * 1024); } while (0)
; template <class Epi, class Sched, bool ALIGN_EPI = false, bool SP2 = false>
; __device__ __forceinline__ void gemm_phase(PG8_LAS unsigned char* lds, const Gemm g, const Sched& S, const Epi& E) {
;     ...
;         const bool has_next = S.next(ui + 1, nxt);
;         const char* nA = has_next ? (const char*)g.A + (size_t)nxt.pm * tstepA : cA; const char* nB = has_next ? (const char*)g.Bt + (size_t)nxt.pn * tstep : cB;
;         for (int t = 0; t < nt; t += 2) {
;             const bool last = (t == nt - 2);
;             const char* a1 = cA + (size_t)(t + 1) * kstepA;
;             const char* a2 = last ? nA : cA + (size_t)(t + 2) * kstepA; const char* b2 = last ? nB : cB + (size_t)(t + 2) * kstep;
;             const char* a3 = a2 + kstepA; const char* b3 = b2 + kstep;
;             if (last && has_next) S.a_ready(nxt);
;             if constexpr (SP2) {
;             PG8_LDB(B0, 0, 0); PG8_LDB(B1, 0, 1); PG8_SCHED; PG8_LDA(At, 0, 0); PG8_STAGE(PG8_SA(1, 1), a1 + hstepA, voffA);
;             PG8_WAIT_V(8); PG8_WAIT_L(0); PG8_BAR; PG8_MMA(0, 0, At, B0); PG8_MMA(0, 1, At, B1); PG8_BAR; PG8_SCHED;
;             PG8_LDA(At, 0, 1); PG8_STAGE(PG8_SB(0, 0), b2, voffB); PG8_STAGE(PG8_SB(0, 1), b2 + hstep, voffB); PG8_STAGE(PG8_SA(0, 0), a2, voffA);
;             PG8_WAIT_V(8); PG8_WAIT_L(0); PG8_BAR; PG8_MMA(1, 0, At, B0); PG8_MMA(1, 1, At, B1); PG8_BAR; PG8_SCHED;
;             PG8_LDB(B0, 1, 0); PG8_LDB(B1, 1, 1); PG8_SCHED; PG8_LDA(At, 1, 0); PG8_STAGE(PG8_SA(0, 1), a2 + hstepA, voffA);
;             PG8_WAIT_V(8); PG8_WAIT_L(0); PG8_BAR; PG8_MMA(0, 0, At, B0); PG8_MMA(0, 1, At, B1); PG8_BAR; PG8_SCHED;
;             PG8_LDA(At, 1, 1); PG8_STAGE(PG8_SB(1, 0), b3, voffB); PG8_STAGE(PG8_SB(1, 1), b3 + hstep, voffB); PG8_STAGE(PG8_SA(1, 0), a3, voffA);
;             PG8_WAIT_V(8); PG8_WAIT_L(0); PG8_BAR; PG8_MMA(1, 0, At, B0); PG8_MMA(1, 1, At, B1); PG8_BAR; PG8_SCHED;
.LBB0_973:
	s_add_u32 s5, s48, 0x100
	s_addc_u32 s6, s49, 0
	s_add_u32 s38, s50, 0xb4000
	s_addc_u32 s39, s51, 0
	s_mov_b32 s7, -2
	s_add_u32 s48, s38, 0xfff54000
	s_addc_u32 s49, s39, -1
	s_cmp_eq_u32 s7, 40
	s_cselect_b32 s52, s44, s48
	s_cselect_b32 s53, s45, s49
	s_cselect_b32 s50, s46, s5
	s_cselect_b32 s51, s47, s6
	s_add_u32 s48, s52, 0x4000
	s_addc_u32 s49, s53, 0
	s_add_i32 s64, 0, 0x10000
	s_add_i32 s74, 0, 0x14000
	s_add_i32 m0, s3, 0xc000
	v_lshl_add_u64 v[178:179], s[38:39], 0, v[196:197]
	global_load_lds_dwordx4 v[178:179], off
	v_lshl_add_u64 v[178:179], s[38:39], 0, v[194:195]
	s_add_i32 m0, s3, 0xe000
	s_nop 0
	global_load_lds_dwordx4 v[178:179], off
	s_waitcnt vmcnt(8)
	s_waitcnt lgkmcnt(0)
	s_barrier
	s_setprio 1
	v_mfma_f32_16x16x32_bf16 v[124:127], v[128:131], v[160:163], 0
	v_mfma_f32_16x16x32_bf16 v[120:123], v[136:139], v[160:163], 0
	v_mfma_f32_16x16x32_bf16 v[108:111], v[128:131], v[170:173], 0
	v_mfma_f32_16x16x32_bf16 v[104:107], v[136:139], v[170:173], 0
	v_mfma_f32_16x16x32_bf16 v[92:95], v[128:131], v[202:205], 0
	v_mfma_f32_16x16x32_bf16 v[88:91], v[136:139], v[202:205], 0
	v_mfma_f32_16x16x32_bf16 v[76:79], v[128:131], v[210:213], 0
	v_mfma_f32_16x16x32_bf16 v[72:75], v[136:139], v[210:213], 0
	v_mfma_f32_16x16x32_bf16 v[124:127], v[132:135], v[164:167], v[124:127]
	v_mfma_f32_16x16x32_bf16 v[120:123], v[140:143], v[164:167], v[120:123]
	v_mfma_f32_16x16x32_bf16 v[108:111], v[132:135], v[198:201], v[108:111]
	v_mfma_f32_16x16x32_bf16 v[104:107], v[140:143], v[198:201], v[104:107]
	v_mfma_f32_16x16x32_bf16 v[92:95], v[132:135], v[206:209], v[92:95]
	v_mfma_f32_16x16x32_bf16 v[88:91], v[140:143], v[206:209], v[88:91]
	v_mfma_f32_16x16x32_bf16 v[76:79], v[132:135], v[214:217], v[76:79]
	v_mfma_f32_16x16x32_bf16 v[72:75], v[140:143], v[214:217], v[72:75]
	s_setprio 0
	s_setprio 1
	v_mfma_f32_16x16x32_bf16 v[116:119], v[144:147], v[160:163], 0
	v_mfma_f32_16x16x32_bf16 v[112:115], v[152:155], v[160:163], 0
	v_mfma_f32_16x16x32_bf16 v[100:103], v[144:147], v[170:173], 0
	v_mfma_f32_16x16x32_bf16 v[96:99], v[152:155], v[170:173], 0
	v_mfma_f32_16x16x32_bf16 v[84:87], v[144:147], v[202:205], 0
	v_mfma_f32_16x16x32_bf16 v[80:83], v[152:155], v[202:205], 0
	v_mfma_f32_16x16x32_bf16 v[68:71], v[144:147], v[210:213], 0
	v_mfma_f32_16x16x32_bf16 v[64:67], v[152:155], v[210:213], 0
	v_mfma_f32_16x16x32_bf16 v[116:119], v[148:151], v[164:167], v[116:119]
	v_mfma_f32_16x16x32_bf16 v[112:115], v[156:159], v[164:167], v[112:115]
	v_mfma_f32_16x16x32_bf16 v[100:103], v[148:151], v[198:201], v[100:103]
	v_mfma_f32_16x16x32_bf16 v[96:99], v[156:159], v[198:201], v[96:99]
	v_mfma_f32_16x16x32_bf16 v[84:87], v[148:151], v[206:209], v[84:87]
	s_add_i32 s64, s64, s2
	v_mfma_f32_16x16x32_bf16 v[80:83], v[156:159], v[206:209], v[80:83]
	v_lshl_add_u64 v[178:179], s[50:51], 0, v[168:169]
	v_mfma_f32_16x16x32_bf16 v[68:71], v[148:151], v[214:217], v[68:71]
	s_mov_b32 m0, s64
	v_mfma_f32_16x16x32_bf16 v[64:67], v[156:159], v[214:217], v[64:67]
	s_setprio 0
	s_barrier
	ds_read_b128 v[160:163], v237 offset:16384
	ds_read_b128 v[164:167], v237 offset:17408
	ds_read_b128 v[170:173], v237 offset:18432
	ds_read_b128 v[198:201], v237 offset:19456
	ds_read_b128 v[202:205], v237 offset:20480
	ds_read_b128 v[206:209], v237 offset:21504
	ds_read_b128 v[210:213], v237 offset:22528
	ds_read_b128 v[214:217], v237 offset:23552
	global_load_lds_dwordx4 v[178:179], off
	s_add_i32 m0, s64, 0x2000
	s_add_u32 s64, s50, 0xb0000
	v_lshl_add_u64 v[218:219], s[50:51], 0, v[188:189]
	s_addc_u32 s65, s51, 0
	s_add_i32 s74, s74, s2
	global_load_lds_dwordx4 v[218:219], off
	v_lshl_add_u64 v[220:221], s[64:65], 0, v[168:169]
	s_mov_b32 m0, s74
	s_nop 0
	global_load_lds_dwordx4 v[220:221], off
	v_lshl_add_u64 v[220:221], s[64:65], 0, v[188:189]
	s_add_i32 m0, s74, 0x2000
	s_nop 0
	global_load_lds_dwordx4 v[220:221], off
	v_lshl_add_u64 v[220:221], s[52:53], 0, v[192:193]
	s_mov_b32 m0, s3
	s_nop 0
	global_load_lds_dwordx4 v[220:221], off
	v_lshl_add_u64 v[220:221], s[52:53], 0, v[190:191]
	s_mov_b32 m0, s34
	s_nop 0
	global_load_lds_dwordx4 v[220:221], off
	s_waitcnt vmcnt(8)
	s_waitcnt lgkmcnt(0)
	s_barrier
	s_setprio 1
	v_mfma_f32_16x16x32_bf16 v[60:63], v[128:131], v[160:163], 0
	v_mfma_f32_16x16x32_bf16 v[56:59], v[136:139], v[160:163], 0
	v_mfma_f32_16x16x32_bf16 v[44:47], v[128:131], v[170:173], 0
	v_mfma_f32_16x16x32_bf16 v[40:43], v[136:139], v[170:173], 0
	v_mfma_f32_16x16x32_bf16 v[28:31], v[128:131], v[202:205], 0
	v_mfma_f32_16x16x32_bf16 v[24:27], v[136:139], v[202:205], 0
	v_mfma_f32_16x16x32_bf16 v[12:15], v[128:131], v[210:213], 0
	v_mfma_f32_16x16x32_bf16 v[8:11], v[136:139], v[210:213], 0
	v_mfma_f32_16x16x32_bf16 v[60:63], v[132:135], v[164:167], v[60:63]
	v_mfma_f32_16x16x32_bf16 v[56:59], v[140:143], v[164:167], v[56:59]
	v_mfma_f32_16x16x32_bf16 v[44:47], v[132:135], v[198:201], v[44:47]
	v_mfma_f32_16x16x32_bf16 v[40:43], v[140:143], v[198:201], v[40:43]
	v_mfma_f32_16x16x32_bf16 v[28:31], v[132:135], v[206:209], v[28:31]
	v_mfma_f32_16x16x32_bf16 v[24:27], v[140:143], v[206:209], v[24:27]
	v_mfma_f32_16x16x32_bf16 v[12:15], v[132:135], v[214:217], v[12:15]
	v_mfma_f32_16x16x32_bf16 v[8:11], v[140:143], v[214:217], v[8:11]
	s_setprio 0
	s_setprio 1
	v_mfma_f32_16x16x32_bf16 v[52:55], v[144:147], v[160:163], 0
	v_mfma_f32_16x16x32_bf16 v[48:51], v[152:155], v[160:163], 0
	v_mfma_f32_16x16x32_bf16 v[36:39], v[144:147], v[170:173], 0
	v_mfma_f32_16x16x32_bf16 v[32:35], v[152:155], v[170:173], 0
	v_mfma_f32_16x16x32_bf16 v[20:23], v[144:147], v[202:205], 0
	v_mfma_f32_16x16x32_bf16 v[16:19], v[152:155], v[202:205], 0
	v_mfma_f32_16x16x32_bf16 v[4:7], v[144:147], v[210:213], 0
	v_mfma_f32_16x16x32_bf16 v[0:3], v[152:155], v[210:213], 0
	v_mfma_f32_16x16x32_bf16 v[52:55], v[148:151], v[164:167], v[52:55]
	v_mfma_f32_16x16x32_bf16 v[48:51], v[156:159], v[164:167], v[48:51]
	v_mfma_f32_16x16x32_bf16 v[36:39], v[148:151], v[198:201], v[36:39]
	v_mfma_f32_16x16x32_bf16 v[32:35], v[156:159], v[198:201], v[32:35]
	s_add_i32 s64, 0, 0x18000
	v_mfma_f32_16x16x32_bf16 v[20:23], v[148:151], v[206:209], v[20:23]
	s_add_i32 s65, 0, 0x1c000
	v_mfma_f32_16x16x32_bf16 v[16:19], v[156:159], v[206:209], v[16:19]
	v_add_u32_e32 v240, s64, v236
	v_mfma_f32_16x16x32_bf16 v[4:7], v[148:151], v[214:217], v[4:7]
	v_add_u32_e32 v241, s65, v236
	v_mfma_f32_16x16x32_bf16 v[0:3], v[156:159], v[214:217], v[0:3]
	s_setprio 0
	s_barrier
; #define PG8_STAGE(bufoff, gbase, voff) do { _Pragma("unroll") for (int _i = 0; _i < 2; ++_i) \
;         __builtin_amdgcn_global_load_lds((const unsigned*)((const char*)(gbase) + (voff)[_i]), (PG8_LAS unsigned*)(lds + (bufoff) + ldsw + _i * 8192), 16, 0, 0); } while (0)
; #define PG8_LDA(dst, b, h) do { _Pragma("unroll") for (int m = 0; m < 4; ++m) _Pragma("unroll") for (int k = 0; k < 2; ++k) dst[m][k] = *(const PG8_LAS bf16x8*)(lds + PG8_SA(b, h) + aoff + m * 2048 + k * 1024); } while (0)
; #define PG8_LDB(dst, b, h) do { _Pragma("unroll") for (int n = 0; n < 2; ++n) _Pragma("unroll") for (int k = 0; k < 2; ++k) dst[n][k] = *(const PG8_LAS bf16x8*)(lds + PG8_SB(b, h) + boff + n * 2048 + k * 1024); } while (0)
; #define PG8_MMA(ai, bj, At, Bt) do { __builtin_amdgcn_s_setprio(1); _Pragma("unroll") for (int m = 0; m < 4; ++m) _Pragma("unroll") for (int n = 0; n < 2; ++n) _Pragma("unroll") for (int k = 0; k < 2; ++k) \
;         acc[ai][bj][m][n] = __builtin_amdgcn_mfma_f32_16x16x32_bf16(Bt[n][k], At[m][k], acc[ai][bj][m][n], 0, 0, 0); __builtin_amdgcn_s_setprio(0); } while (0)
; #define PG8_WAIT_V(n) asm volatile("s_waitcnt vmcnt(" #n ")" ::: "memory")
; template <class Epi, class Sched, bool ALIGN_EPI = false, bool SP2 = false>
; __device__ __forceinline__ void gemm_phase(PG8_LAS unsigned char* lds, const Gemm g, const Sched& S, const Epi& E) {
;     ...
;             PG8_LDB(B0, 0, 0); PG8_LDB(B1, 0, 1); PG8_SCHED; PG8_LDA(At, 0, 0); PG8_STAGE(PG8_SA(1, 1), a1 + hstepA, voffA);
;             PG8_WAIT_V(8); PG8_WAIT_L(0); PG8_BAR; PG8_MMA(0, 0, At, B0); PG8_MMA(0, 1, At, B1); PG8_BAR; PG8_SCHED;
;             PG8_LDA(At, 0, 1); PG8_STAGE(PG8_SB(0, 0), b2, voffB); PG8_STAGE(PG8_SB(0, 1), b2 + hstep, voffB); PG8_STAGE(PG8_SA(0, 0), a2, voffA);
;             PG8_WAIT_V(8); PG8_WAIT_L(0); PG8_BAR; PG8_MMA(1, 0, At, B0); PG8_MMA(1, 1, At, B1); PG8_BAR; PG8_SCHED;
;             PG8_LDB(B0, 1, 0); PG8_LDB(B1, 1, 1); PG8_SCHED; PG8_LDA(At, 1, 0); PG8_STAGE(PG8_SA(0, 1), a2 + hstepA, voffA);
;             PG8_WAIT_V(8); PG8_WAIT_L(0); PG8_BAR; PG8_MMA(0, 0, At, B0); PG8_MMA(0, 1, At, B1); PG8_BAR; PG8_SCHED;
;             PG8_LDA(At, 1, 1); PG8_STAGE(PG8_SB(1, 0), b3, voffB); PG8_STAGE(PG8_SB(1, 1), b3 + hstep, voffB); PG8_STAGE(PG8_SA(1, 0), a3, voffA);
;             PG8_WAIT_V(8); PG8_WAIT_L(0); PG8_BAR; PG8_MMA(1, 0, At, B0); PG8_MMA(1, 1, At, B1); PG8_BAR; PG8_SCHED;
	ds_read_b128 v[128:131], v240
	ds_read_b128 v[132:135], v240 offset:1024
	ds_read_b128 v[136:139], v240 offset:2048
	ds_read_b128 v[140:143], v240 offset:3072
	ds_read_b128 v[144:147], v241
	ds_read_b128 v[148:151], v241 offset:1024
	ds_read_b128 v[152:155], v241 offset:2048
	ds_read_b128 v[156:159], v241 offset:3072
	ds_read_b128 v[160:163], v237 offset:32768
	ds_read_b128 v[164:167], v237 offset:33792
	ds_read_b128 v[170:173], v237 offset:34816
	ds_read_b128 v[198:201], v237 offset:35840
	ds_read_b128 v[202:205], v237 offset:36864
	ds_read_b128 v[206:209], v237 offset:37888
	ds_read_b128 v[210:213], v237 offset:38912
	ds_read_b128 v[214:217], v237 offset:39936
	s_add_u32 s52, s52, 0xb0000
	s_addc_u32 s53, s53, 0
	s_mov_b32 m0, s35
	v_lshl_add_u64 v[220:221], s[52:53], 0, v[192:193]
	global_load_lds_dwordx4 v[220:221], off
	v_lshl_add_u64 v[220:221], s[52:53], 0, v[190:191]
	s_mov_b32 m0, s54
	s_nop 0
	global_load_lds_dwordx4 v[220:221], off
	s_waitcnt vmcnt(8)
	s_waitcnt lgkmcnt(0)
	s_barrier
	s_setprio 1
	v_mfma_f32_16x16x32_bf16 v[124:127], v[128:131], v[160:163], v[124:127]
	v_mfma_f32_16x16x32_bf16 v[120:123], v[136:139], v[160:163], v[120:123]
	v_mfma_f32_16x16x32_bf16 v[108:111], v[128:131], v[170:173], v[108:111]
	v_mfma_f32_16x16x32_bf16 v[104:107], v[136:139], v[170:173], v[104:107]
	v_mfma_f32_16x16x32_bf16 v[92:95], v[128:131], v[202:205], v[92:95]
	v_mfma_f32_16x16x32_bf16 v[88:91], v[136:139], v[202:205], v[88:91]
	v_mfma_f32_16x16x32_bf16 v[76:79], v[128:131], v[210:213], v[76:79]
	v_mfma_f32_16x16x32_bf16 v[72:75], v[136:139], v[210:213], v[72:75]
	v_mfma_f32_16x16x32_bf16 v[124:127], v[132:135], v[164:167], v[124:127]
	v_mfma_f32_16x16x32_bf16 v[120:123], v[140:143], v[164:167], v[120:123]
	v_mfma_f32_16x16x32_bf16 v[108:111], v[132:135], v[198:201], v[108:111]
	v_mfma_f32_16x16x32_bf16 v[104:107], v[140:143], v[198:201], v[104:107]
	v_mfma_f32_16x16x32_bf16 v[92:95], v[132:135], v[206:209], v[92:95]
	v_mfma_f32_16x16x32_bf16 v[88:91], v[140:143], v[206:209], v[88:91]
	v_mfma_f32_16x16x32_bf16 v[76:79], v[132:135], v[214:217], v[76:79]
	v_mfma_f32_16x16x32_bf16 v[72:75], v[140:143], v[214:217], v[72:75]
	s_setprio 0
	s_setprio 1
	v_mfma_f32_16x16x32_bf16 v[116:119], v[144:147], v[160:163], v[116:119]
	v_mfma_f32_16x16x32_bf16 v[112:115], v[152:155], v[160:163], v[112:115]
	v_mfma_f32_16x16x32_bf16 v[100:103], v[144:147], v[170:173], v[100:103]
	v_mfma_f32_16x16x32_bf16 v[96:99], v[152:155], v[170:173], v[96:99]
	v_mfma_f32_16x16x32_bf16 v[84:87], v[144:147], v[202:205], v[84:87]
	v_mfma_f32_16x16x32_bf16 v[80:83], v[152:155], v[202:205], v[80:83]
	v_mfma_f32_16x16x32_bf16 v[68:71], v[144:147], v[210:213], v[68:71]
	v_mfma_f32_16x16x32_bf16 v[64:67], v[152:155], v[210:213], v[64:67]
	v_mfma_f32_16x16x32_bf16 v[116:119], v[148:151], v[164:167], v[116:119]
	v_mfma_f32_16x16x32_bf16 v[112:115], v[156:159], v[164:167], v[112:115]
	v_mfma_f32_16x16x32_bf16 v[100:103], v[148:151], v[198:201], v[100:103]
	v_mfma_f32_16x16x32_bf16 v[96:99], v[156:159], v[198:201], v[96:99]
	v_mfma_f32_16x16x32_bf16 v[84:87], v[148:151], v[206:209], v[84:87]
	s_add_i32 s52, s64, s2
	v_mfma_f32_16x16x32_bf16 v[80:83], v[156:159], v[206:209], v[80:83]
	v_lshl_add_u64 v[178:179], v[178:179], 0, s[30:31]
	v_mfma_f32_16x16x32_bf16 v[68:71], v[148:151], v[214:217], v[68:71]
	s_mov_b32 m0, s52
	v_mfma_f32_16x16x32_bf16 v[64:67], v[156:159], v[214:217], v[64:67]
	s_setprio 0
	s_barrier
	ds_read_b128 v[160:163], v237 offset:49152
	ds_read_b128 v[164:167], v237 offset:50176
	ds_read_b128 v[170:173], v237 offset:51200
	ds_read_b128 v[198:201], v237 offset:52224
	ds_read_b128 v[202:205], v237 offset:53248
	ds_read_b128 v[206:209], v237 offset:54272
	ds_read_b128 v[210:213], v237 offset:55296
	ds_read_b128 v[214:217], v237 offset:56320
	global_load_lds_dwordx4 v[178:179], off
	s_add_i32 m0, s52, 0x2000
	s_add_u32 s50, s50, 0xb0080
	v_lshl_add_u64 v[178:179], v[218:219], 0, s[30:31]
	s_addc_u32 s51, s51, 0
	s_add_i32 s52, s65, s2
	global_load_lds_dwordx4 v[178:179], off
	v_lshl_add_u64 v[178:179], s[50:51], 0, v[168:169]
	s_mov_b32 m0, s52
	s_nop 0
	global_load_lds_dwordx4 v[178:179], off
	v_lshl_add_u64 v[178:179], s[50:51], 0, v[188:189]
	s_add_i32 m0, s52, 0x2000
	s_nop 0
	global_load_lds_dwordx4 v[178:179], off
	v_lshl_add_u64 v[178:179], s[48:49], 0, v[192:193]
	s_mov_b32 m0, s57
	s_nop 0
	global_load_lds_dwordx4 v[178:179], off
	v_lshl_add_u64 v[178:179], s[48:49], 0, v[190:191]
	s_mov_b32 m0, s60
	s_nop 0
	global_load_lds_dwordx4 v[178:179], off
	s_waitcnt vmcnt(8)
	s_waitcnt lgkmcnt(0)
	s_barrier
; #define PG8_STAGE(bufoff, gbase, voff) do { _Pragma("unroll") for (int _i = 0; _i < 2; ++_i) \
;         __builtin_amdgcn_global_load_lds((const unsigned*)((const char*)(gbase) + (voff)[_i]), (PG8_LAS unsigned*)(lds + (bufoff) + ldsw + _i * 8192), 16, 0, 0); } while (0)
; #define PG8_LDA(dst, b, h) do { _Pragma("unroll") for (int m = 0; m < 4; ++m) _Pragma("unroll") for (int k = 0; k < 2; ++k) dst[m][k] = *(const PG8_LAS bf16x8*)(lds + PG8_SA(b, h) + aoff + m * 2048 + k * 1024); } while (0)
; #define PG8_LDB(dst, b, h) do { _Pragma("unroll") for (int n = 0; n < 2; ++n) _Pragma("unroll") for (int k = 0; k < 2; ++k) dst[n][k] = *(const PG8_LAS bf16x8*)(lds + PG8_SB(b, h) + boff + n * 2048 + k * 1024); } while (0)
; template <class Epi, class Sched, bool ALIGN_EPI = false, bool SP2 = false>
; __device__ __forceinline__ void gemm_phase(PG8_LAS unsigned char* lds, const Gemm g, const Sched& S, const Epi& E) {
;     ...
;         for (int t = 0; t < nt; t += 2) {
;             const bool last = (t == nt - 2);
;             const char* a1 = cA + (size_t)(t + 1) * kstepA;
;             const char* a2 = last ? nA : cA + (size_t)(t + 2) * kstepA; const char* b2 = last ? nB : cB + (size_t)(t + 2) * kstep;
;             const char* a3 = a2 + kstepA; const char* b3 = b2 + kstep;
;             if (last && has_next) S.a_ready(nxt);
;             if constexpr (SP2) {
;             PG8_LDB(B0, 0, 0); PG8_LDB(B1, 0, 1); PG8_SCHED; PG8_LDA(At, 0, 0); PG8_STAGE(PG8_SA(1, 1), a1 + hstepA, voffA);
;             PG8_WAIT_V(8); PG8_WAIT_L(0); PG8_BAR; PG8_MMA(0, 0, At, B0); PG8_MMA(0, 1, At, B1); PG8_BAR; PG8_SCHED;
;             PG8_LDA(At, 0, 1); PG8_STAGE(PG8_SB(0, 0), b2, voffB); PG8_STAGE(PG8_SB(0, 1), b2 + hstep, voffB); PG8_STAGE(PG8_SA(0, 0), a2, voffA);
;             PG8_WAIT_V(8); PG8_WAIT_L(0); PG8_BAR; PG8_MMA(1, 0, At, B0); PG8_MMA(1, 1, At, B1); PG8_BAR; PG8_SCHED;
;             PG8_LDB(B0, 1, 0); PG8_LDB(B1, 1, 1); PG8_SCHED; PG8_LDA(At, 1, 0); PG8_STAGE(PG8_SA(0, 1), a2 + hstepA, voffA);
;             PG8_WAIT_V(8); PG8_WAIT_L(0); PG8_BAR; PG8_MMA(0, 0, At, B0); PG8_MMA(0, 1, At, B1); PG8_BAR; PG8_SCHED;
;             PG8_LDA(At, 1, 1); PG8_STAGE(PG8_SB(1, 0), b3, voffB); PG8_STAGE(PG8_SB(1, 1), b3 + hstep, voffB); PG8_STAGE(PG8_SA(1, 0), a3, voffA);
;             PG8_WAIT_V(8); PG8_WAIT_L(0); PG8_BAR; PG8_MMA(1, 0, At, B0); PG8_MMA(1, 1, At, B1); PG8_BAR; PG8_SCHED;
	s_setprio 1
	v_mfma_f32_16x16x32_bf16 v[60:63], v[128:131], v[160:163], v[60:63]
	v_mfma_f32_16x16x32_bf16 v[56:59], v[136:139], v[160:163], v[56:59]
	v_mfma_f32_16x16x32_bf16 v[44:47], v[128:131], v[170:173], v[44:47]
	v_mfma_f32_16x16x32_bf16 v[40:43], v[136:139], v[170:173], v[40:43]
	v_mfma_f32_16x16x32_bf16 v[28:31], v[128:131], v[202:205], v[28:31]
	v_mfma_f32_16x16x32_bf16 v[24:27], v[136:139], v[202:205], v[24:27]
	v_mfma_f32_16x16x32_bf16 v[12:15], v[128:131], v[210:213], v[12:15]
	v_mfma_f32_16x16x32_bf16 v[8:11], v[136:139], v[210:213], v[8:11]
	v_mfma_f32_16x16x32_bf16 v[60:63], v[132:135], v[164:167], v[60:63]
	v_mfma_f32_16x16x32_bf16 v[56:59], v[140:143], v[164:167], v[56:59]
	v_mfma_f32_16x16x32_bf16 v[44:47], v[132:135], v[198:201], v[44:47]
	v_mfma_f32_16x16x32_bf16 v[40:43], v[140:143], v[198:201], v[40:43]
	v_mfma_f32_16x16x32_bf16 v[28:31], v[132:135], v[206:209], v[28:31]
	v_mfma_f32_16x16x32_bf16 v[24:27], v[140:143], v[206:209], v[24:27]
	s_add_i32 s7, s7, 2
	v_mfma_f32_16x16x32_bf16 v[12:15], v[132:135], v[214:217], v[12:15]
	s_add_u32 s5, s5, 0x100
	v_mfma_f32_16x16x32_bf16 v[8:11], v[140:143], v[214:217], v[8:11]
	s_addc_u32 s6, s6, 0
	s_setprio 0
	s_setprio 1
	v_mfma_f32_16x16x32_bf16 v[52:55], v[144:147], v[160:163], v[52:55]
	s_add_u32 s38, s38, 0x8000
	v_mfma_f32_16x16x32_bf16 v[48:51], v[152:155], v[160:163], v[48:51]
	s_addc_u32 s39, s39, 0
	v_mfma_f32_16x16x32_bf16 v[36:39], v[144:147], v[170:173], v[36:39]
	s_add_u32 s48, s38, 0xfff54000
	v_mfma_f32_16x16x32_bf16 v[32:35], v[152:155], v[170:173], v[32:35]
	s_addc_u32 s49, s39, -1
	v_mfma_f32_16x16x32_bf16 v[20:23], v[144:147], v[202:205], v[20:23]
	s_cmp_eq_u32 s7, 40
	v_mfma_f32_16x16x32_bf16 v[16:19], v[152:155], v[202:205], v[16:19]
	s_cselect_b32 s52, s44, s48
	v_mfma_f32_16x16x32_bf16 v[4:7], v[144:147], v[210:213], v[4:7]
	s_cselect_b32 s53, s45, s49
	v_mfma_f32_16x16x32_bf16 v[0:3], v[152:155], v[210:213], v[0:3]
	s_cselect_b32 s50, s46, s5
	v_mfma_f32_16x16x32_bf16 v[52:55], v[148:151], v[164:167], v[52:55]
	s_cselect_b32 s51, s47, s6
	v_mfma_f32_16x16x32_bf16 v[48:51], v[156:159], v[164:167], v[48:51]
	s_add_u32 s48, s52, 0x4000
	v_mfma_f32_16x16x32_bf16 v[36:39], v[148:151], v[198:201], v[36:39]
	s_addc_u32 s49, s53, 0
	v_mfma_f32_16x16x32_bf16 v[32:35], v[156:159], v[198:201], v[32:35]
	s_add_i32 s64, 0, 0x10000
	v_mfma_f32_16x16x32_bf16 v[20:23], v[148:151], v[206:209], v[20:23]
	s_add_i32 s74, 0, 0x14000
	v_mfma_f32_16x16x32_bf16 v[16:19], v[156:159], v[206:209], v[16:19]
	v_add_u32_e32 v242, s64, v236
	v_mfma_f32_16x16x32_bf16 v[4:7], v[148:151], v[214:217], v[4:7]
	v_add_u32_e32 v243, s74, v236
	v_mfma_f32_16x16x32_bf16 v[0:3], v[156:159], v[214:217], v[0:3]
	s_setprio 0
	s_barrier
.LBB0_974:
	ds_read_b128 v[128:131], v242
	ds_read_b128 v[132:135], v242 offset:1024
	ds_read_b128 v[136:139], v242 offset:2048
	ds_read_b128 v[140:143], v242 offset:3072
	ds_read_b128 v[144:147], v243
	ds_read_b128 v[148:151], v243 offset:1024
	ds_read_b128 v[152:155], v243 offset:2048
	ds_read_b128 v[156:159], v243 offset:3072
	ds_read_b128 v[160:163], v237
	ds_read_b128 v[164:167], v237 offset:1024
	ds_read_b128 v[170:173], v237 offset:2048
	ds_read_b128 v[198:201], v237 offset:3072
	ds_read_b128 v[202:205], v237 offset:4096
	ds_read_b128 v[206:209], v237 offset:5120
	ds_read_b128 v[210:213], v237 offset:6144
	ds_read_b128 v[214:217], v237 offset:7168
	s_add_i32 m0, s3, 0xc000
	v_lshl_add_u64 v[178:179], s[38:39], 0, v[196:197]
	global_load_lds_dwordx4 v[178:179], off
	v_lshl_add_u64 v[178:179], s[38:39], 0, v[194:195]
	s_add_i32 m0, s3, 0xe000
	s_nop 0
	global_load_lds_dwordx4 v[178:179], off
	s_waitcnt vmcnt(8)
	s_waitcnt lgkmcnt(0)
	s_barrier
	s_setprio 1
	v_mfma_f32_16x16x32_bf16 v[124:127], v[128:131], v[160:163], v[124:127]
	v_mfma_f32_16x16x32_bf16 v[120:123], v[136:139], v[160:163], v[120:123]
	v_mfma_f32_16x16x32_bf16 v[108:111], v[128:131], v[170:173], v[108:111]
	v_mfma_f32_16x16x32_bf16 v[104:107], v[136:139], v[170:173], v[104:107]
	v_mfma_f32_16x16x32_bf16 v[92:95], v[128:131], v[202:205], v[92:95]
	v_mfma_f32_16x16x32_bf16 v[88:91], v[136:139], v[202:205], v[88:91]
	v_mfma_f32_16x16x32_bf16 v[76:79], v[128:131], v[210:213], v[76:79]
	v_mfma_f32_16x16x32_bf16 v[72:75], v[136:139], v[210:213], v[72:75]
	v_mfma_f32_16x16x32_bf16 v[124:127], v[132:135], v[164:167], v[124:127]
	v_mfma_f32_16x16x32_bf16 v[120:123], v[140:143], v[164:167], v[120:123]
	v_mfma_f32_16x16x32_bf16 v[108:111], v[132:135], v[198:201], v[108:111]
	v_mfma_f32_16x16x32_bf16 v[104:107], v[140:143], v[198:201], v[104:107]
	v_mfma_f32_16x16x32_bf16 v[92:95], v[132:135], v[206:209], v[92:95]
	v_mfma_f32_16x16x32_bf16 v[88:91], v[140:143], v[206:209], v[88:91]
	v_mfma_f32_16x16x32_bf16 v[76:79], v[132:135], v[214:217], v[76:79]
	v_mfma_f32_16x16x32_bf16 v[72:75], v[140:143], v[214:217], v[72:75]
	s_setprio 0
	s_setprio 1
	v_mfma_f32_16x16x32_bf16 v[116:119], v[144:147], v[160:163], v[116:119]
	v_mfma_f32_16x16x32_bf16 v[112:115], v[152:155], v[160:163], v[112:115]
	v_mfma_f32_16x16x32_bf16 v[100:103], v[144:147], v[170:173], v[100:103]
	v_mfma_f32_16x16x32_bf16 v[96:99], v[152:155], v[170:173], v[96:99]
	v_mfma_f32_16x16x32_bf16 v[84:87], v[144:147], v[202:205], v[84:87]
	v_mfma_f32_16x16x32_bf16 v[80:83], v[152:155], v[202:205], v[80:83]
	v_mfma_f32_16x16x32_bf16 v[68:71], v[144:147], v[210:213], v[68:71]
	v_mfma_f32_16x16x32_bf16 v[64:67], v[152:155], v[210:213], v[64:67]
	v_mfma_f32_16x16x32_bf16 v[116:119], v[148:151], v[164:167], v[116:119]
	v_mfma_f32_16x16x32_bf16 v[112:115], v[156:159], v[164:167], v[112:115]
	v_mfma_f32_16x16x32_bf16 v[100:103], v[148:151], v[198:201], v[100:103]
	v_mfma_f32_16x16x32_bf16 v[96:99], v[156:159], v[198:201], v[96:99]
	v_mfma_f32_16x16x32_bf16 v[84:87], v[148:151], v[206:209], v[84:87]
	s_add_i32 s64, s64, s2
	v_mfma_f32_16x16x32_bf16 v[80:83], v[156:159], v[206:209], v[80:83]
	v_lshl_add_u64 v[178:179], s[50:51], 0, v[168:169]
	v_mfma_f32_16x16x32_bf16 v[68:71], v[148:151], v[214:217], v[68:71]
	s_mov_b32 m0, s64
	v_mfma_f32_16x16x32_bf16 v[64:67], v[156:159], v[214:217], v[64:67]
	s_setprio 0
	s_barrier
; #define PG8_STAGE(bufoff, gbase, voff) do { _Pragma("unroll") for (int _i = 0; _i < 2; ++_i) \
;         __builtin_amdgcn_global_load_lds((const unsigned*)((const char*)(gbase) + (voff)[_i]), (PG8_LAS unsigned*)(lds + (bufoff) + ldsw + _i * 8192), 16, 0, 0); } while (0)
; #define PG8_LDA(dst, b, h) do { _Pragma("unroll") for (int m = 0; m < 4; ++m) _Pragma("unroll") for (int k = 0; k < 2; ++k) dst[m][k] = *(const PG8_LAS bf16x8*)(lds + PG8_SA(b, h) + aoff + m * 2048 + k * 1024); } while (0)
; #define PG8_LDB(dst, b, h) do { _Pragma("unroll") for (int n = 0; n < 2; ++n) _Pragma("unroll") for (int k = 0; k < 2; ++k) dst[n][k] = *(const PG8_LAS bf16x8*)(lds + PG8_SB(b, h) + boff + n * 2048 + k * 1024); } while (0)
; #define PG8_MMA(ai, bj, At, Bt) do { __builtin_amdgcn_s_setprio(1); _Pragma("unroll") for (int m = 0; m < 4; ++m) _Pragma("unroll") for (int n = 0; n < 2; ++n) _Pragma("unroll") for (int k = 0; k < 2; ++k) \
;         acc[ai][bj][m][n] = __builtin_amdgcn_mfma_f32_16x16x32_bf16(Bt[n][k], At[m][k], acc[ai][bj][m][n], 0, 0, 0); __builtin_amdgcn_s_setprio(0); } while (0)
; #define PG8_WAIT_V(n) asm volatile("s_waitcnt vmcnt(" #n ")" ::: "memory")
; template <class Epi, class Sched, bool ALIGN_EPI = false, bool SP2 = false>
; __device__ __forceinline__ void gemm_phase(PG8_LAS unsigned char* lds, const Gemm g, const Sched& S, const Epi& E) {
;     ...
;             PG8_LDB(B0, 0, 0); PG8_LDB(B1, 0, 1); PG8_SCHED; PG8_LDA(At, 0, 0); PG8_STAGE(PG8_SA(1, 1), a1 + hstepA, voffA);
;             PG8_WAIT_V(8); PG8_WAIT_L(0); PG8_BAR; PG8_MMA(0, 0, At, B0); PG8_MMA(0, 1, At, B1); PG8_BAR; PG8_SCHED;
;             PG8_LDA(At, 0, 1); PG8_STAGE(PG8_SB(0, 0), b2, voffB); PG8_STAGE(PG8_SB(0, 1), b2 + hstep, voffB); PG8_STAGE(PG8_SA(0, 0), a2, voffA);
;             PG8_WAIT_V(8); PG8_WAIT_L(0); PG8_BAR; PG8_MMA(1, 0, At, B0); PG8_MMA(1, 1, At, B1); PG8_BAR; PG8_SCHED;
;             PG8_LDB(B0, 1, 0); PG8_LDB(B1, 1, 1); PG8_SCHED; PG8_LDA(At, 1, 0); PG8_STAGE(PG8_SA(0, 1), a2 + hstepA, voffA);
;             PG8_WAIT_V(8); PG8_WAIT_L(0); PG8_BAR; PG8_MMA(0, 0, At, B0); PG8_MMA(0, 1, At, B1); PG8_BAR; PG8_SCHED;
;             PG8_LDA(At, 1, 1); PG8_STAGE(PG8_SB(1, 0), b3, voffB); PG8_STAGE(PG8_SB(1, 1), b3 + hstep, voffB); PG8_STAGE(PG8_SA(1, 0), a3, voffA);
;             PG8_WAIT_V(8); PG8_WAIT_L(0); PG8_BAR; PG8_MMA(1, 0, At, B0); PG8_MMA(1, 1, At, B1); PG8_BAR; PG8_SCHED;
	ds_read_b128 v[160:163], v237 offset:16384
	ds_read_b128 v[164:167], v237 offset:17408
	ds_read_b128 v[170:173], v237 offset:18432
	ds_read_b128 v[198:201], v237 offset:19456
	ds_read_b128 v[202:205], v237 offset:20480
	ds_read_b128 v[206:209], v237 offset:21504
	ds_read_b128 v[210:213], v237 offset:22528
	ds_read_b128 v[214:217], v237 offset:23552
	global_load_lds_dwordx4 v[178:179], off
	s_add_i32 m0, s64, 0x2000
	s_add_u32 s64, s50, 0xb0000
	v_lshl_add_u64 v[218:219], s[50:51], 0, v[188:189]
	s_addc_u32 s65, s51, 0
	s_add_i32 s74, s74, s2
	global_load_lds_dwordx4 v[218:219], off
	v_lshl_add_u64 v[220:221], s[64:65], 0, v[168:169]
	s_mov_b32 m0, s74
	s_nop 0
	global_load_lds_dwordx4 v[220:221], off
	v_lshl_add_u64 v[220:221], s[64:65], 0, v[188:189]
	s_add_i32 m0, s74, 0x2000
	s_nop 0
	global_load_lds_dwordx4 v[220:221], off
	v_lshl_add_u64 v[220:221], s[52:53], 0, v[192:193]
	s_mov_b32 m0, s3
	s_nop 0
	global_load_lds_dwordx4 v[220:221], off
	v_lshl_add_u64 v[220:221], s[52:53], 0, v[190:191]
	s_mov_b32 m0, s34
	s_nop 0
	global_load_lds_dwordx4 v[220:221], off
	s_waitcnt vmcnt(8)
	s_waitcnt lgkmcnt(0)
	s_barrier
	s_setprio 1
	v_mfma_f32_16x16x32_bf16 v[60:63], v[128:131], v[160:163], v[60:63]
	v_mfma_f32_16x16x32_bf16 v[56:59], v[136:139], v[160:163], v[56:59]
	v_mfma_f32_16x16x32_bf16 v[44:47], v[128:131], v[170:173], v[44:47]
	v_mfma_f32_16x16x32_bf16 v[40:43], v[136:139], v[170:173], v[40:43]
	v_mfma_f32_16x16x32_bf16 v[28:31], v[128:131], v[202:205], v[28:31]
	v_mfma_f32_16x16x32_bf16 v[24:27], v[136:139], v[202:205], v[24:27]
	v_mfma_f32_16x16x32_bf16 v[12:15], v[128:131], v[210:213], v[12:15]
	v_mfma_f32_16x16x32_bf16 v[8:11], v[136:139], v[210:213], v[8:11]
	v_mfma_f32_16x16x32_bf16 v[60:63], v[132:135], v[164:167], v[60:63]
	v_mfma_f32_16x16x32_bf16 v[56:59], v[140:143], v[164:167], v[56:59]
	v_mfma_f32_16x16x32_bf16 v[44:47], v[132:135], v[198:201], v[44:47]
	v_mfma_f32_16x16x32_bf16 v[40:43], v[140:143], v[198:201], v[40:43]
	v_mfma_f32_16x16x32_bf16 v[28:31], v[132:135], v[206:209], v[28:31]
	v_mfma_f32_16x16x32_bf16 v[24:27], v[140:143], v[206:209], v[24:27]
	v_mfma_f32_16x16x32_bf16 v[12:15], v[132:135], v[214:217], v[12:15]
	v_mfma_f32_16x16x32_bf16 v[8:11], v[140:143], v[214:217], v[8:11]
	s_setprio 0
	s_setprio 1
	v_mfma_f32_16x16x32_bf16 v[52:55], v[144:147], v[160:163], v[52:55]
	v_mfma_f32_16x16x32_bf16 v[48:51], v[152:155], v[160:163], v[48:51]
	v_mfma_f32_16x16x32_bf16 v[36:39], v[144:147], v[170:173], v[36:39]
	v_mfma_f32_16x16x32_bf16 v[32:35], v[152:155], v[170:173], v[32:35]
	v_mfma_f32_16x16x32_bf16 v[20:23], v[144:147], v[202:205], v[20:23]
	v_mfma_f32_16x16x32_bf16 v[16:19], v[152:155], v[202:205], v[16:19]
	v_mfma_f32_16x16x32_bf16 v[4:7], v[144:147], v[210:213], v[4:7]
	v_mfma_f32_16x16x32_bf16 v[0:3], v[152:155], v[210:213], v[0:3]
	v_mfma_f32_16x16x32_bf16 v[52:55], v[148:151], v[164:167], v[52:55]
	v_mfma_f32_16x16x32_bf16 v[48:51], v[156:159], v[164:167], v[48:51]
	v_mfma_f32_16x16x32_bf16 v[36:39], v[148:151], v[198:201], v[36:39]
	v_mfma_f32_16x16x32_bf16 v[32:35], v[156:159], v[198:201], v[32:35]
	s_add_i32 s64, 0, 0x18000
	v_mfma_f32_16x16x32_bf16 v[20:23], v[148:151], v[206:209], v[20:23]
	s_add_i32 s65, 0, 0x1c000
	v_mfma_f32_16x16x32_bf16 v[16:19], v[156:159], v[206:209], v[16:19]
	v_add_u32_e32 v240, s64, v236
	v_mfma_f32_16x16x32_bf16 v[4:7], v[148:151], v[214:217], v[4:7]
	v_add_u32_e32 v241, s65, v236
	v_mfma_f32_16x16x32_bf16 v[0:3], v[156:159], v[214:217], v[0:3]
	s_setprio 0
	s_barrier
	ds_read_b128 v[128:131], v240
	ds_read_b128 v[132:135], v240 offset:1024
	ds_read_b128 v[136:139], v240 offset:2048
	ds_read_b128 v[140:143], v240 offset:3072
	ds_read_b128 v[144:147], v241
	ds_read_b128 v[148:151], v241 offset:1024
	ds_read_b128 v[152:155], v241 offset:2048
	ds_read_b128 v[156:159], v241 offset:3072
	ds_read_b128 v[160:163], v237 offset:32768
	ds_read_b128 v[164:167], v237 offset:33792
	ds_read_b128 v[170:173], v237 offset:34816
	ds_read_b128 v[198:201], v237 offset:35840
	ds_read_b128 v[202:205], v237 offset:36864
	ds_read_b128 v[206:209], v237 offset:37888
	ds_read_b128 v[210:213], v237 offset:38912
	ds_read_b128 v[214:217], v237 offset:39936
	s_add_u32 s52, s52, 0xb0000
	s_addc_u32 s53, s53, 0
	s_mov_b32 m0, s35
	v_lshl_add_u64 v[220:221], s[52:53], 0, v[192:193]
	global_load_lds_dwordx4 v[220:221], off
	v_lshl_add_u64 v[220:221], s[52:53], 0, v[190:191]
	s_mov_b32 m0, s54
	s_nop 0
	global_load_lds_dwordx4 v[220:221], off
	s_waitcnt vmcnt(8)
	s_waitcnt lgkmcnt(0)
	s_barrier
; #define PG8_STAGE(bufoff, gbase, voff) do { _Pragma("unroll") for (int _i = 0; _i < 2; ++_i) \
;         __builtin_amdgcn_global_load_lds((const unsigned*)((const char*)(gbase) + (voff)[_i]), (PG8_LAS unsigned*)(lds + (bufoff) + ldsw + _i * 8192), 16, 0, 0); } while (0)
; #define PG8_LDA(dst, b, h) do { _Pragma("unroll") for (int m = 0; m < 4; ++m) _Pragma("unroll") for (int k = 0; k < 2; ++k) dst[m][k] = *(const PG8_LAS bf16x8*)(lds + PG8_SA(b, h) + aoff + m * 2048 + k * 1024); } while (0)
; #define PG8_LDB(dst, b, h) do { _Pragma("unroll") for (int n = 0; n < 2; ++n) _Pragma("unroll") for (int k = 0; k < 2; ++k) dst[n][k] = *(const PG8_LAS bf16x8*)(lds + PG8_SB(b, h) + boff + n * 2048 + k * 1024); } while (0)
; template <class Epi, class Sched, bool ALIGN_EPI = false, bool SP2 = false>
; __device__ __forceinline__ void gemm_phase(PG8_LAS unsigned char* lds, const Gemm g, const Sched& S, const Epi& E) {
;     ...
;         for (int t = 0; t < nt; t += 2) {
;             const bool last = (t == nt - 2);
;             const char* a1 = cA + (size_t)(t + 1) * kstepA;
;             const char* a2 = last ? nA : cA + (size_t)(t + 2) * kstepA; const char* b2 = last ? nB : cB + (size_t)(t + 2) * kstep;
;             const char* a3 = a2 + kstepA; const char* b3 = b2 + kstep;
;             if (last && has_next) S.a_ready(nxt);
;             if constexpr (SP2) {
;             PG8_LDB(B0, 0, 0); PG8_LDB(B1, 0, 1); PG8_SCHED; PG8_LDA(At, 0, 0); PG8_STAGE(PG8_SA(1, 1), a1 + hstepA, voffA);
;             PG8_WAIT_V(8); PG8_WAIT_L(0); PG8_BAR; PG8_MMA(0, 0, At, B0); PG8_MMA(0, 1, At, B1); PG8_BAR; PG8_SCHED;
;             PG8_LDA(At, 0, 1); PG8_STAGE(PG8_SB(0, 0), b2, voffB); PG8_STAGE(PG8_SB(0, 1), b2 + hstep, voffB); PG8_STAGE(PG8_SA(0, 0), a2, voffA);
;             PG8_WAIT_V(8); PG8_WAIT_L(0); PG8_BAR; PG8_MMA(1, 0, At, B0); PG8_MMA(1, 1, At, B1); PG8_BAR; PG8_SCHED;
;             PG8_LDB(B0, 1, 0); PG8_LDB(B1, 1, 1); PG8_SCHED; PG8_LDA(At, 1, 0); PG8_STAGE(PG8_SA(0, 1), a2 + hstepA, voffA);
;             PG8_WAIT_V(8); PG8_WAIT_L(0); PG8_BAR; PG8_MMA(0, 0, At, B0); PG8_MMA(0, 1, At, B1); PG8_BAR; PG8_SCHED;
;             PG8_LDA(At, 1, 1); PG8_STAGE(PG8_SB(1, 0), b3, voffB); PG8_STAGE(PG8_SB(1, 1), b3 + hstep, voffB); PG8_STAGE(PG8_SA(1, 0), a3, voffA);
;             PG8_WAIT_V(8); PG8_WAIT_L(0); PG8_BAR; PG8_MMA(1, 0, At, B0); PG8_MMA(1, 1, At, B1); PG8_BAR; PG8_SCHED;
	s_setprio 1
	v_mfma_f32_16x16x32_bf16 v[124:127], v[128:131], v[160:163], v[124:127]
	v_mfma_f32_16x16x32_bf16 v[120:123], v[136:139], v[160:163], v[120:123]
	v_mfma_f32_16x16x32_bf16 v[108:111], v[128:131], v[170:173], v[108:111]
	v_mfma_f32_16x16x32_bf16 v[104:107], v[136:139], v[170:173], v[104:107]
	v_mfma_f32_16x16x32_bf16 v[92:95], v[128:131], v[202:205], v[92:95]
	v_mfma_f32_16x16x32_bf16 v[88:91], v[136:139], v[202:205], v[88:91]
	v_mfma_f32_16x16x32_bf16 v[76:79], v[128:131], v[210:213], v[76:79]
	v_mfma_f32_16x16x32_bf16 v[72:75], v[136:139], v[210:213], v[72:75]
	v_mfma_f32_16x16x32_bf16 v[124:127], v[132:135], v[164:167], v[124:127]
	v_mfma_f32_16x16x32_bf16 v[120:123], v[140:143], v[164:167], v[120:123]
	v_mfma_f32_16x16x32_bf16 v[108:111], v[132:135], v[198:201], v[108:111]
	v_mfma_f32_16x16x32_bf16 v[104:107], v[140:143], v[198:201], v[104:107]
	v_mfma_f32_16x16x32_bf16 v[92:95], v[132:135], v[206:209], v[92:95]
	v_mfma_f32_16x16x32_bf16 v[88:91], v[140:143], v[206:209], v[88:91]
	v_mfma_f32_16x16x32_bf16 v[76:79], v[132:135], v[214:217], v[76:79]
	v_mfma_f32_16x16x32_bf16 v[72:75], v[140:143], v[214:217], v[72:75]
	s_setprio 0
	s_setprio 1
	v_mfma_f32_16x16x32_bf16 v[116:119], v[144:147], v[160:163], v[116:119]
	v_mfma_f32_16x16x32_bf16 v[112:115], v[152:155], v[160:163], v[112:115]
	v_mfma_f32_16x16x32_bf16 v[100:103], v[144:147], v[170:173], v[100:103]
	v_mfma_f32_16x16x32_bf16 v[96:99], v[152:155], v[170:173], v[96:99]
	v_mfma_f32_16x16x32_bf16 v[84:87], v[144:147], v[202:205], v[84:87]
	v_mfma_f32_16x16x32_bf16 v[80:83], v[152:155], v[202:205], v[80:83]
	v_mfma_f32_16x16x32_bf16 v[68:71], v[144:147], v[210:213], v[68:71]
	v_mfma_f32_16x16x32_bf16 v[64:67], v[152:155], v[210:213], v[64:67]
	v_mfma_f32_16x16x32_bf16 v[116:119], v[148:151], v[164:167], v[116:119]
	v_mfma_f32_16x16x32_bf16 v[112:115], v[156:159], v[164:167], v[112:115]
	v_mfma_f32_16x16x32_bf16 v[100:103], v[148:151], v[198:201], v[100:103]
	v_mfma_f32_16x16x32_bf16 v[96:99], v[156:159], v[198:201], v[96:99]
	v_mfma_f32_16x16x32_bf16 v[84:87], v[148:151], v[206:209], v[84:87]
	s_add_i32 s52, s64, s2
	v_mfma_f32_16x16x32_bf16 v[80:83], v[156:159], v[206:209], v[80:83]
	v_lshl_add_u64 v[178:179], v[178:179], 0, s[30:31]
	v_mfma_f32_16x16x32_bf16 v[68:71], v[148:151], v[214:217], v[68:71]
	s_mov_b32 m0, s52
	v_mfma_f32_16x16x32_bf16 v[64:67], v[156:159], v[214:217], v[64:67]
	s_setprio 0
	s_barrier
	ds_read_b128 v[160:163], v237 offset:49152
	ds_read_b128 v[164:167], v237 offset:50176
	ds_read_b128 v[170:173], v237 offset:51200
	ds_read_b128 v[198:201], v237 offset:52224
	ds_read_b128 v[202:205], v237 offset:53248
	ds_read_b128 v[206:209], v237 offset:54272
	ds_read_b128 v[210:213], v237 offset:55296
	ds_read_b128 v[214:217], v237 offset:56320
	global_load_lds_dwordx4 v[178:179], off
	s_add_i32 m0, s52, 0x2000
	s_add_u32 s50, s50, 0xb0080
	v_lshl_add_u64 v[178:179], v[218:219], 0, s[30:31]
	s_addc_u32 s51, s51, 0
	s_add_i32 s52, s65, s2
	global_load_lds_dwordx4 v[178:179], off
	v_lshl_add_u64 v[178:179], s[50:51], 0, v[168:169]
	s_mov_b32 m0, s52
	s_nop 0
	global_load_lds_dwordx4 v[178:179], off
	v_lshl_add_u64 v[178:179], s[50:51], 0, v[188:189]
	s_add_i32 m0, s52, 0x2000
	s_nop 0
	global_load_lds_dwordx4 v[178:179], off
	v_lshl_add_u64 v[178:179], s[48:49], 0, v[192:193]
	s_mov_b32 m0, s57
	s_nop 0
	global_load_lds_dwordx4 v[178:179], off
	v_lshl_add_u64 v[178:179], s[48:49], 0, v[190:191]
	s_mov_b32 m0, s60
	s_nop 0
	global_load_lds_dwordx4 v[178:179], off
	s_waitcnt vmcnt(8)
	s_waitcnt lgkmcnt(0)
	s_barrier
	s_setprio 1
	v_mfma_f32_16x16x32_bf16 v[60:63], v[128:131], v[160:163], v[60:63]
	v_mfma_f32_16x16x32_bf16 v[56:59], v[136:139], v[160:163], v[56:59]
	v_mfma_f32_16x16x32_bf16 v[44:47], v[128:131], v[170:173], v[44:47]
	v_mfma_f32_16x16x32_bf16 v[40:43], v[136:139], v[170:173], v[40:43]
	v_mfma_f32_16x16x32_bf16 v[28:31], v[128:131], v[202:205], v[28:31]
	v_mfma_f32_16x16x32_bf16 v[24:27], v[136:139], v[202:205], v[24:27]
	v_mfma_f32_16x16x32_bf16 v[12:15], v[128:131], v[210:213], v[12:15]
	v_mfma_f32_16x16x32_bf16 v[8:11], v[136:139], v[210:213], v[8:11]
	v_mfma_f32_16x16x32_bf16 v[60:63], v[132:135], v[164:167], v[60:63]
	v_mfma_f32_16x16x32_bf16 v[56:59], v[140:143], v[164:167], v[56:59]
	v_mfma_f32_16x16x32_bf16 v[44:47], v[132:135], v[198:201], v[44:47]
	v_mfma_f32_16x16x32_bf16 v[40:43], v[140:143], v[198:201], v[40:43]
	v_mfma_f32_16x16x32_bf16 v[28:31], v[132:135], v[206:209], v[28:31]
	s_add_i32 s7, s7, 2
	v_mfma_f32_16x16x32_bf16 v[24:27], v[140:143], v[206:209], v[24:27]
	s_add_u32 s5, s5, 0x100
	v_mfma_f32_16x16x32_bf16 v[12:15], v[132:135], v[214:217], v[12:15]
	s_addc_u32 s6, s6, 0
	v_mfma_f32_16x16x32_bf16 v[8:11], v[140:143], v[214:217], v[8:11]
	s_add_u32 s38, s38, 0x8000
	s_setprio 0
	s_setprio 1
	v_mfma_f32_16x16x32_bf16 v[52:55], v[144:147], v[160:163], v[52:55]
	s_addc_u32 s39, s39, 0
	v_mfma_f32_16x16x32_bf16 v[48:51], v[152:155], v[160:163], v[48:51]
	s_add_u32 s48, s38, 0xfff54000
	v_mfma_f32_16x16x32_bf16 v[36:39], v[144:147], v[170:173], v[36:39]
	s_addc_u32 s49, s39, -1
	v_mfma_f32_16x16x32_bf16 v[32:35], v[152:155], v[170:173], v[32:35]
	s_cmp_eq_u32 s7, 40
	v_mfma_f32_16x16x32_bf16 v[20:23], v[144:147], v[202:205], v[20:23]
	s_cselect_b32 s52, s44, s48
	v_mfma_f32_16x16x32_bf16 v[16:19], v[152:155], v[202:205], v[16:19]
	s_cselect_b32 s53, s45, s49
	v_mfma_f32_16x16x32_bf16 v[4:7], v[144:147], v[210:213], v[4:7]
	s_cselect_b32 s50, s46, s5
	v_mfma_f32_16x16x32_bf16 v[0:3], v[152:155], v[210:213], v[0:3]
	s_cselect_b32 s51, s47, s6
	v_mfma_f32_16x16x32_bf16 v[52:55], v[148:151], v[164:167], v[52:55]
	s_add_u32 s48, s52, 0x4000
	v_mfma_f32_16x16x32_bf16 v[48:51], v[156:159], v[164:167], v[48:51]
	s_addc_u32 s49, s53, 0
	v_mfma_f32_16x16x32_bf16 v[36:39], v[148:151], v[198:201], v[36:39]
	s_add_i32 s64, 0, 0x10000
	v_mfma_f32_16x16x32_bf16 v[32:35], v[156:159], v[198:201], v[32:35]
	s_add_i32 s74, 0, 0x14000
	v_mfma_f32_16x16x32_bf16 v[20:23], v[148:151], v[206:209], v[20:23]
	v_add_u32_e32 v242, s64, v236
	v_mfma_f32_16x16x32_bf16 v[16:19], v[156:159], v[206:209], v[16:19]
	v_add_u32_e32 v243, s74, v236
	v_mfma_f32_16x16x32_bf16 v[4:7], v[148:151], v[214:217], v[4:7]
	s_cmp_gt_u32 s7, 41
	v_mfma_f32_16x16x32_bf16 v[0:3], v[156:159], v[214:217], v[0:3]
	s_setprio 0
	s_barrier
	s_cbranch_scc0 .LBB0_974
	s_and_b64 vcc, exec, s[26:27]
	s_cbranch_vccz .LBB0_977
	s_barrier
